# norm phases: context rows (split-K fold) also on the hand-written path, partial-sum loads pipelined
# speedup vs baseline: 1.0011x; 1.0011x over previous
.LBB0_221:
	s_andn2_b64 vcc, exec, s[4:5]
	s_cbranch_vccnz .LBB0_289
	v_readlane_b32 s8, v253, 2
	s_mov_b64 s[4:5], s[96:97]
	s_mov_b64 s[36:37], s[96:97]
	s_mov_b64 s[20:21], s[96:97]
	v_mov_b32_e32 v2, v0
	v_readlane_b32 s9, v253, 3
	s_load_dword s6, s[8:9], 0x0
	v_readfirstlane_b32 s7, v2
	s_ashr_i32 s10, s7, 6
	v_readlane_b32 s7, v254, 16
	s_add_i32 s7, s10, s7
	s_cmpk_gt_i32 s7, 0x43ff
	s_cbranch_scc1 .LBB0_235
	s_load_dwordx2 s[8:9], s[36:37], 0xb8
	s_waitcnt lgkmcnt(0)
	s_mul_i32 s52, s80, 0x5000
	s_load_dwordx2 s[20:21], s[20:21], 0xb8
	s_lshl_b64 s[36:37], s[52:53], 2
	s_mul_i32 s52, s80, 0xf000
	s_waitcnt lgkmcnt(0)
	s_add_u32 s8, s8, s36
	s_addc_u32 s9, s9, s37
	s_add_u32 s8, s8, 0x195d4000
	s_addc_u32 s9, s9, 0
	s_lshl_b64 s[36:37], s[52:53], 2
	s_load_dwordx2 s[38:39], s[4:5], 0xb8
	s_add_u32 s11, s20, s36
	s_addc_u32 s12, s21, s37
	s_add_u32 s54, s11, 0x194e0000
	v_and_b32_e32 v3, 63, v2
	s_addc_u32 s55, s12, 0
	v_lshlrev_b32_e32 v98, 5, v3
	s_cmp_lg_u32 s80, 0
	s_waitcnt lgkmcnt(0)
	v_lshl_add_u64 v[4:5], s[38:39], 0, v[98:99]
	s_mov_b64 s[12:13], 0x3bce8000
	s_cselect_b64 s[20:21], -1, 0
	s_lshl_b32 s36, s6, 3
	v_lshl_add_u64 v[34:35], v[4:5], 0, s[12:13]
	s_ashr_i32 s11, s10, 31
	v_readlane_b32 s12, v254, 16
	s_add_u32 s10, s12, s10
	v_readlane_b32 s12, v254, 58
	s_addc_u32 s11, s12, s11
	s_lshl_b64 s[40:41], s[10:11], 12
	s_add_u32 s38, s38, s40
	v_lshlrev_b32_e32 v4, 3, v3
	v_lshlrev_b32_e32 v98, 4, v3
	s_addc_u32 s39, s39, s41
	v_lshlrev_b32_e32 v2, 1, v3
	v_or_b32_e32 v6, 0x400, v4
	v_or_b32_e32 v8, 0x600, v4
	v_lshl_add_u64 v[10:11], s[38:39], 0, v[98:99]
	s_mov_b64 s[12:13], 0x1da24c00
	s_ashr_i32 s37, s36, 31
	v_lshl_add_u64 v[36:37], v[10:11], 0, s[12:13]
	s_lshl_b64 s[38:39], s[36:37], 12
	s_lshl_b64 s[42:43], s[10:11], 13
	s_lshl_b64 s[44:45], s[36:37], 13
	v_cndmask_b32_e64 v56, 0, 1, s[20:21]
	v_lshlrev_b32_e32 v98, 4, v2
	s_xor_b64 s[46:47], s[20:21], -1
	v_lshlrev_b32_e32 v57, 2, v4
	v_lshlrev_b32_e32 v58, 2, v6
	v_lshlrev_b32_e32 v59, 2, v8
	s_mov_b32 s101, 0
	s_cmp_lg_u32 s6, 0x100
	s_cbranch_scc1 .Lnf1_skip
	s_cmp_eq_u32 s80, 0
	s_cbranch_scc1 .Lnf1_skip
	s_mov_b32 s101, 1
	s_load_dwordx2 s[40:41], s[4:5], 0xb8
	v_and_b32_e32 v38, 63, v0
	v_lshlrev_b32_e32 v39, 4, v38
	v_lshlrev_b32_e32 v40, 5, v38
	s_lshr_b32 s20, s7, 3
	s_and_b32 s21, s20, 7
	s_lshl_b32 s21, s21, 5
	s_lshr_b32 s20, s20, 3
	s_or_b32 s20, s20, s21
	s_lshl_b32 s20, s20, 3
	s_and_b32 s21, s7, 7
	s_or_b32 s49, s20, s21
	s_lshl_b32 s10, s49, 15
	s_lshr_b32 s48, s49, 9
	s_lshl_b32 s20, s48, 13
	s_mul_i32 s49, s48, 0xc000
	s_waitcnt lgkmcnt(0)
	s_add_u32 s10, s40, s10
	s_addc_u32 s11, s41, 0
	s_add_u32 s10, s10, 0x19624000
	s_addc_u32 s11, s11, 0
	s_add_u32 s40, s8, s20
	s_addc_u32 s41, s9, 0
	s_add_u32 s48, s54, s49
	s_addc_u32 s49, s55, 0
	s_add_u32 s20, s10, 0x4400000
	s_addc_u32 s21, s11, 0
	global_load_dwordx4 v[100:103], v39, s[10:11]
	global_load_dwordx4 v[104:107], v39, s[10:11] offset:1024
	global_load_dwordx4 v[108:111], v39, s[10:11] offset:2048
	global_load_dwordx4 v[112:115], v39, s[10:11] offset:3072
	s_add_u32 s10, s10, 0x1000
	s_addc_u32 s11, s11, 0
	global_load_dwordx4 v[2:5], v40, s[40:41]
	global_load_dwordx4 v[6:9], v40, s[40:41] offset:16
	global_load_dwordx4 v[10:13], v40, s[40:41] offset:2048
	global_load_dwordx4 v[14:17], v40, s[40:41] offset:2064
	s_add_u32 s40, s40, 0x1000
	s_addc_u32 s41, s41, 0
	global_load_dwordx4 v[18:21], v40, s[40:41]
	global_load_dwordx4 v[22:25], v40, s[40:41] offset:16
	global_load_dwordx4 v[26:29], v40, s[40:41] offset:2048
	global_load_dwordx4 v[30:33], v40, s[40:41] offset:2064
	global_load_dwordx4 v[164:167], v40, s[48:49]
	global_load_dwordx4 v[168:171], v40, s[48:49] offset:16
	global_load_dwordx4 v[172:175], v40, s[48:49] offset:2048
	global_load_dwordx4 v[176:179], v40, s[48:49] offset:2064
	s_add_u32 s48, s48, 0x1000
	s_addc_u32 s49, s49, 0
	global_load_dwordx4 v[180:183], v40, s[48:49]
	global_load_dwordx4 v[184:187], v40, s[48:49] offset:16
	global_load_dwordx4 v[188:191], v40, s[48:49] offset:2048
	global_load_dwordx4 v[192:195], v40, s[48:49] offset:2064
	global_load_dwordx4 v[116:119], v39, s[10:11]
	global_load_dwordx4 v[120:123], v39, s[10:11] offset:1024
	global_load_dwordx4 v[124:127], v39, s[10:11] offset:2048
	global_load_dwordx4 v[128:131], v39, s[10:11] offset:3072
	s_add_u32 s10, s10, 0x1000
	s_addc_u32 s11, s11, 0
	global_load_dwordx4 v[132:135], v39, s[10:11]
	global_load_dwordx4 v[136:139], v39, s[10:11] offset:1024
	global_load_dwordx4 v[140:143], v39, s[10:11] offset:2048
	global_load_dwordx4 v[144:147], v39, s[10:11] offset:3072
	s_add_u32 s10, s10, 0x1000
	s_addc_u32 s11, s11, 0
	global_load_dwordx4 v[148:151], v39, s[10:11]
	global_load_dwordx4 v[152:155], v39, s[10:11] offset:1024
	global_load_dwordx4 v[156:159], v39, s[10:11] offset:2048
	global_load_dwordx4 v[160:163], v39, s[10:11] offset:3072
	s_add_u32 s10, s10, 0x1000
	s_addc_u32 s11, s11, 0
	v_mov_b32_e32 v47, 0x3a000000
	s_waitcnt vmcnt(28)
	v_lshlrev_b32_e32 v60, 16, v100
	v_and_b32_e32 v61, 0xffff0000, v100
	v_pk_mul_f32 v[42:43], v[60:61], v[60:61]
	v_lshlrev_b32_e32 v62, 16, v101
	v_and_b32_e32 v63, 0xffff0000, v101
	v_pk_fma_f32 v[42:43], v[62:63], v[62:63], v[42:43]
	v_lshlrev_b32_e32 v64, 16, v102
	v_and_b32_e32 v65, 0xffff0000, v102
	v_pk_fma_f32 v[42:43], v[64:65], v[64:65], v[42:43]
	v_lshlrev_b32_e32 v66, 16, v103
	v_and_b32_e32 v67, 0xffff0000, v103
	v_pk_fma_f32 v[42:43], v[66:67], v[66:67], v[42:43]
	v_lshlrev_b32_e32 v60, 16, v104
	v_and_b32_e32 v61, 0xffff0000, v104
	v_pk_fma_f32 v[42:43], v[60:61], v[60:61], v[42:43]
	v_lshlrev_b32_e32 v62, 16, v105
	v_and_b32_e32 v63, 0xffff0000, v105
	v_pk_fma_f32 v[42:43], v[62:63], v[62:63], v[42:43]
	v_lshlrev_b32_e32 v64, 16, v106
	v_and_b32_e32 v65, 0xffff0000, v106
	v_pk_fma_f32 v[42:43], v[64:65], v[64:65], v[42:43]
	v_lshlrev_b32_e32 v66, 16, v107
	v_and_b32_e32 v67, 0xffff0000, v107
	v_pk_fma_f32 v[42:43], v[66:67], v[66:67], v[42:43]
	v_lshlrev_b32_e32 v60, 16, v108
	v_and_b32_e32 v61, 0xffff0000, v108
	v_pk_fma_f32 v[42:43], v[60:61], v[60:61], v[42:43]
	v_lshlrev_b32_e32 v62, 16, v109
	v_and_b32_e32 v63, 0xffff0000, v109
	v_pk_fma_f32 v[42:43], v[62:63], v[62:63], v[42:43]
	v_lshlrev_b32_e32 v64, 16, v110
	v_and_b32_e32 v65, 0xffff0000, v110
	v_pk_fma_f32 v[42:43], v[64:65], v[64:65], v[42:43]
	v_lshlrev_b32_e32 v66, 16, v111
	v_and_b32_e32 v67, 0xffff0000, v111
	v_pk_fma_f32 v[42:43], v[66:67], v[66:67], v[42:43]
	v_lshlrev_b32_e32 v60, 16, v112
	v_and_b32_e32 v61, 0xffff0000, v112
	v_pk_fma_f32 v[42:43], v[60:61], v[60:61], v[42:43]
	v_lshlrev_b32_e32 v62, 16, v113
	v_and_b32_e32 v63, 0xffff0000, v113
	v_pk_fma_f32 v[42:43], v[62:63], v[62:63], v[42:43]
	v_lshlrev_b32_e32 v64, 16, v114
	v_and_b32_e32 v65, 0xffff0000, v114
	v_pk_fma_f32 v[42:43], v[64:65], v[64:65], v[42:43]
	v_lshlrev_b32_e32 v66, 16, v115
	v_and_b32_e32 v67, 0xffff0000, v115
	v_pk_fma_f32 v[42:43], v[66:67], v[66:67], v[42:43]
	v_add_f32_e32 v42, v42, v43
	s_nop 1
	v_add_f32_dpp v42, v42, v42 quad_perm:[1,0,3,2] row_mask:0xf bank_mask:0xf
	s_nop 1
	v_add_f32_dpp v42, v42, v42 quad_perm:[2,3,0,1] row_mask:0xf bank_mask:0xf
	s_nop 1
	v_add_f32_dpp v42, v42, v42 row_half_mirror row_mask:0xf bank_mask:0xf
	s_nop 1
	v_add_f32_dpp v42, v42, v42 row_mirror row_mask:0xf bank_mask:0xf
	s_nop 1
	v_add_f32_dpp v42, v42, v42 row_bcast:15 row_mask:0xa bank_mask:0xf
	s_nop 1
	v_add_f32_dpp v42, v42, v42 row_bcast:31 row_mask:0xc bank_mask:0xf
	s_nop 1
	v_readlane_b32 s100, v42, 63
	s_nop 3
	v_mov_b32_e32 v44, s100
	v_fma_f32 v44, v44, v47, v224
	v_rsq_f32_e32 v45, v44
	s_nop 0
	v_mul_f32_e32 v46, v44, v45
	v_mul_f32_e32 v46, v46, v45
	v_fmaak_f32 v46, -0.5, v46, 0x3fc00000
	v_mul_f32_e32 v44, v45, v46
	v_mov_b32_e32 v45, v44
	s_waitcnt vmcnt(12)
	v_lshlrev_b32_e32 v60, 16, v100
	v_and_b32_e32 v61, 0xffff0000, v100
	v_pk_mul_f32 v[60:61], v[60:61], v[44:45]
	v_pk_fma_f32 v[60:61], v[60:61], v[2:3], v[164:165]
	v_cvt_pk_bf16_f32 v100, v60, v61
	v_lshlrev_b32_e32 v62, 16, v101
	v_and_b32_e32 v63, 0xffff0000, v101
	v_pk_mul_f32 v[62:63], v[62:63], v[44:45]
	v_pk_fma_f32 v[62:63], v[62:63], v[4:5], v[166:167]
	v_cvt_pk_bf16_f32 v101, v62, v63
	v_lshlrev_b32_e32 v64, 16, v102
	v_and_b32_e32 v65, 0xffff0000, v102
	v_pk_mul_f32 v[64:65], v[64:65], v[44:45]
	v_pk_fma_f32 v[64:65], v[64:65], v[6:7], v[168:169]
	v_cvt_pk_bf16_f32 v102, v64, v65
	v_lshlrev_b32_e32 v66, 16, v103
	v_and_b32_e32 v67, 0xffff0000, v103
	v_pk_mul_f32 v[66:67], v[66:67], v[44:45]
	v_pk_fma_f32 v[66:67], v[66:67], v[8:9], v[170:171]
	v_cvt_pk_bf16_f32 v103, v66, v67
	v_lshlrev_b32_e32 v60, 16, v104
	v_and_b32_e32 v61, 0xffff0000, v104
	v_pk_mul_f32 v[60:61], v[60:61], v[44:45]
	v_pk_fma_f32 v[60:61], v[60:61], v[10:11], v[172:173]
	v_cvt_pk_bf16_f32 v104, v60, v61
	v_lshlrev_b32_e32 v62, 16, v105
	v_and_b32_e32 v63, 0xffff0000, v105
	v_pk_mul_f32 v[62:63], v[62:63], v[44:45]
	v_pk_fma_f32 v[62:63], v[62:63], v[12:13], v[174:175]
	v_cvt_pk_bf16_f32 v105, v62, v63
	v_lshlrev_b32_e32 v64, 16, v106
	v_and_b32_e32 v65, 0xffff0000, v106
	v_pk_mul_f32 v[64:65], v[64:65], v[44:45]
	v_pk_fma_f32 v[64:65], v[64:65], v[14:15], v[176:177]
	v_cvt_pk_bf16_f32 v106, v64, v65
	v_lshlrev_b32_e32 v66, 16, v107
	v_and_b32_e32 v67, 0xffff0000, v107
	v_pk_mul_f32 v[66:67], v[66:67], v[44:45]
	v_pk_fma_f32 v[66:67], v[66:67], v[16:17], v[178:179]
	v_cvt_pk_bf16_f32 v107, v66, v67
	v_lshlrev_b32_e32 v60, 16, v108
	v_and_b32_e32 v61, 0xffff0000, v108
	v_pk_mul_f32 v[60:61], v[60:61], v[44:45]
	v_pk_fma_f32 v[60:61], v[60:61], v[18:19], v[180:181]
	v_cvt_pk_bf16_f32 v108, v60, v61
	v_lshlrev_b32_e32 v62, 16, v109
	v_and_b32_e32 v63, 0xffff0000, v109
	v_pk_mul_f32 v[62:63], v[62:63], v[44:45]
	v_pk_fma_f32 v[62:63], v[62:63], v[20:21], v[182:183]
	v_cvt_pk_bf16_f32 v109, v62, v63
	v_lshlrev_b32_e32 v64, 16, v110
	v_and_b32_e32 v65, 0xffff0000, v110
	v_pk_mul_f32 v[64:65], v[64:65], v[44:45]
	v_pk_fma_f32 v[64:65], v[64:65], v[22:23], v[184:185]
	v_cvt_pk_bf16_f32 v110, v64, v65
	v_lshlrev_b32_e32 v66, 16, v111
	v_and_b32_e32 v67, 0xffff0000, v111
	v_pk_mul_f32 v[66:67], v[66:67], v[44:45]
	v_pk_fma_f32 v[66:67], v[66:67], v[24:25], v[186:187]
	v_cvt_pk_bf16_f32 v111, v66, v67
	v_lshlrev_b32_e32 v60, 16, v112
	v_and_b32_e32 v61, 0xffff0000, v112
	v_pk_mul_f32 v[60:61], v[60:61], v[44:45]
	v_pk_fma_f32 v[60:61], v[60:61], v[26:27], v[188:189]
	v_cvt_pk_bf16_f32 v112, v60, v61
	v_lshlrev_b32_e32 v62, 16, v113
	v_and_b32_e32 v63, 0xffff0000, v113
	v_pk_mul_f32 v[62:63], v[62:63], v[44:45]
	v_pk_fma_f32 v[62:63], v[62:63], v[28:29], v[190:191]
	v_cvt_pk_bf16_f32 v113, v62, v63
	v_lshlrev_b32_e32 v64, 16, v114
	v_and_b32_e32 v65, 0xffff0000, v114
	v_pk_mul_f32 v[64:65], v[64:65], v[44:45]
	v_pk_fma_f32 v[64:65], v[64:65], v[30:31], v[192:193]
	v_cvt_pk_bf16_f32 v114, v64, v65
	v_lshlrev_b32_e32 v66, 16, v115
	v_and_b32_e32 v67, 0xffff0000, v115
	v_pk_mul_f32 v[66:67], v[66:67], v[44:45]
	v_pk_fma_f32 v[66:67], v[66:67], v[32:33], v[194:195]
	v_cvt_pk_bf16_f32 v115, v66, v67
	global_store_dwordx4 v39, v[100:103], s[20:21]
	global_store_dwordx4 v39, v[104:107], s[20:21] offset:1024
	global_store_dwordx4 v39, v[108:111], s[20:21] offset:2048
	global_store_dwordx4 v39, v[112:115], s[20:21] offset:3072
	s_add_u32 s20, s20, 0x1000
	s_addc_u32 s21, s21, 0
	global_load_dwordx4 v[100:103], v39, s[10:11]
	global_load_dwordx4 v[104:107], v39, s[10:11] offset:1024
	global_load_dwordx4 v[108:111], v39, s[10:11] offset:2048
	global_load_dwordx4 v[112:115], v39, s[10:11] offset:3072
	s_add_u32 s10, s10, 0x1000
	s_addc_u32 s11, s11, 0
	s_waitcnt vmcnt(16)
	v_lshlrev_b32_e32 v60, 16, v116
	v_and_b32_e32 v61, 0xffff0000, v116
	v_pk_mul_f32 v[42:43], v[60:61], v[60:61]
	v_lshlrev_b32_e32 v62, 16, v117
	v_and_b32_e32 v63, 0xffff0000, v117
	v_pk_fma_f32 v[42:43], v[62:63], v[62:63], v[42:43]
	v_lshlrev_b32_e32 v64, 16, v118
	v_and_b32_e32 v65, 0xffff0000, v118
	v_pk_fma_f32 v[42:43], v[64:65], v[64:65], v[42:43]
	v_lshlrev_b32_e32 v66, 16, v119
	v_and_b32_e32 v67, 0xffff0000, v119
	v_pk_fma_f32 v[42:43], v[66:67], v[66:67], v[42:43]
	v_lshlrev_b32_e32 v60, 16, v120
	v_and_b32_e32 v61, 0xffff0000, v120
	v_pk_fma_f32 v[42:43], v[60:61], v[60:61], v[42:43]
	v_lshlrev_b32_e32 v62, 16, v121
	v_and_b32_e32 v63, 0xffff0000, v121
	v_pk_fma_f32 v[42:43], v[62:63], v[62:63], v[42:43]
	v_lshlrev_b32_e32 v64, 16, v122
	v_and_b32_e32 v65, 0xffff0000, v122
	v_pk_fma_f32 v[42:43], v[64:65], v[64:65], v[42:43]
	v_lshlrev_b32_e32 v66, 16, v123
	v_and_b32_e32 v67, 0xffff0000, v123
	v_pk_fma_f32 v[42:43], v[66:67], v[66:67], v[42:43]
	v_lshlrev_b32_e32 v60, 16, v124
	v_and_b32_e32 v61, 0xffff0000, v124
	v_pk_fma_f32 v[42:43], v[60:61], v[60:61], v[42:43]
	v_lshlrev_b32_e32 v62, 16, v125
	v_and_b32_e32 v63, 0xffff0000, v125
	v_pk_fma_f32 v[42:43], v[62:63], v[62:63], v[42:43]
	v_lshlrev_b32_e32 v64, 16, v126
	v_and_b32_e32 v65, 0xffff0000, v126
	v_pk_fma_f32 v[42:43], v[64:65], v[64:65], v[42:43]
	v_lshlrev_b32_e32 v66, 16, v127
	v_and_b32_e32 v67, 0xffff0000, v127
	v_pk_fma_f32 v[42:43], v[66:67], v[66:67], v[42:43]
	v_lshlrev_b32_e32 v60, 16, v128
	v_and_b32_e32 v61, 0xffff0000, v128
	v_pk_fma_f32 v[42:43], v[60:61], v[60:61], v[42:43]
	v_lshlrev_b32_e32 v62, 16, v129
	v_and_b32_e32 v63, 0xffff0000, v129
	v_pk_fma_f32 v[42:43], v[62:63], v[62:63], v[42:43]
	v_lshlrev_b32_e32 v64, 16, v130
	v_and_b32_e32 v65, 0xffff0000, v130
	v_pk_fma_f32 v[42:43], v[64:65], v[64:65], v[42:43]
	v_lshlrev_b32_e32 v66, 16, v131
	v_and_b32_e32 v67, 0xffff0000, v131
	v_pk_fma_f32 v[42:43], v[66:67], v[66:67], v[42:43]
	v_add_f32_e32 v42, v42, v43
	s_nop 1
	v_add_f32_dpp v42, v42, v42 quad_perm:[1,0,3,2] row_mask:0xf bank_mask:0xf
	s_nop 1
	v_add_f32_dpp v42, v42, v42 quad_perm:[2,3,0,1] row_mask:0xf bank_mask:0xf
	s_nop 1
	v_add_f32_dpp v42, v42, v42 row_half_mirror row_mask:0xf bank_mask:0xf
	s_nop 1
	v_add_f32_dpp v42, v42, v42 row_mirror row_mask:0xf bank_mask:0xf
	s_nop 1
	v_add_f32_dpp v42, v42, v42 row_bcast:15 row_mask:0xa bank_mask:0xf
	s_nop 1
	v_add_f32_dpp v42, v42, v42 row_bcast:31 row_mask:0xc bank_mask:0xf
	s_nop 1
	v_readlane_b32 s100, v42, 63
	s_nop 3
	v_mov_b32_e32 v44, s100
	v_fma_f32 v44, v44, v47, v224
	v_rsq_f32_e32 v45, v44
	s_nop 0
	v_mul_f32_e32 v46, v44, v45
	v_mul_f32_e32 v46, v46, v45
	v_fmaak_f32 v46, -0.5, v46, 0x3fc00000
	v_mul_f32_e32 v44, v45, v46
	v_mov_b32_e32 v45, v44
	v_lshlrev_b32_e32 v60, 16, v116
	v_and_b32_e32 v61, 0xffff0000, v116
	v_pk_mul_f32 v[60:61], v[60:61], v[44:45]
	v_pk_fma_f32 v[60:61], v[60:61], v[2:3], v[164:165]
	v_cvt_pk_bf16_f32 v116, v60, v61
	v_lshlrev_b32_e32 v62, 16, v117
	v_and_b32_e32 v63, 0xffff0000, v117
	v_pk_mul_f32 v[62:63], v[62:63], v[44:45]
	v_pk_fma_f32 v[62:63], v[62:63], v[4:5], v[166:167]
	v_cvt_pk_bf16_f32 v117, v62, v63
	v_lshlrev_b32_e32 v64, 16, v118
	v_and_b32_e32 v65, 0xffff0000, v118
	v_pk_mul_f32 v[64:65], v[64:65], v[44:45]
	v_pk_fma_f32 v[64:65], v[64:65], v[6:7], v[168:169]
	v_cvt_pk_bf16_f32 v118, v64, v65
	v_lshlrev_b32_e32 v66, 16, v119
	v_and_b32_e32 v67, 0xffff0000, v119
	v_pk_mul_f32 v[66:67], v[66:67], v[44:45]
	v_pk_fma_f32 v[66:67], v[66:67], v[8:9], v[170:171]
	v_cvt_pk_bf16_f32 v119, v66, v67
	v_lshlrev_b32_e32 v60, 16, v120
	v_and_b32_e32 v61, 0xffff0000, v120
	v_pk_mul_f32 v[60:61], v[60:61], v[44:45]
	v_pk_fma_f32 v[60:61], v[60:61], v[10:11], v[172:173]
	v_cvt_pk_bf16_f32 v120, v60, v61
	v_lshlrev_b32_e32 v62, 16, v121
	v_and_b32_e32 v63, 0xffff0000, v121
	v_pk_mul_f32 v[62:63], v[62:63], v[44:45]
	v_pk_fma_f32 v[62:63], v[62:63], v[12:13], v[174:175]
	v_cvt_pk_bf16_f32 v121, v62, v63
	v_lshlrev_b32_e32 v64, 16, v122
	v_and_b32_e32 v65, 0xffff0000, v122
	v_pk_mul_f32 v[64:65], v[64:65], v[44:45]
	v_pk_fma_f32 v[64:65], v[64:65], v[14:15], v[176:177]
	v_cvt_pk_bf16_f32 v122, v64, v65
	v_lshlrev_b32_e32 v66, 16, v123
	v_and_b32_e32 v67, 0xffff0000, v123
	v_pk_mul_f32 v[66:67], v[66:67], v[44:45]
	v_pk_fma_f32 v[66:67], v[66:67], v[16:17], v[178:179]
	v_cvt_pk_bf16_f32 v123, v66, v67
	v_lshlrev_b32_e32 v60, 16, v124
	v_and_b32_e32 v61, 0xffff0000, v124
	v_pk_mul_f32 v[60:61], v[60:61], v[44:45]
	v_pk_fma_f32 v[60:61], v[60:61], v[18:19], v[180:181]
	v_cvt_pk_bf16_f32 v124, v60, v61
	v_lshlrev_b32_e32 v62, 16, v125
	v_and_b32_e32 v63, 0xffff0000, v125
	v_pk_mul_f32 v[62:63], v[62:63], v[44:45]
	v_pk_fma_f32 v[62:63], v[62:63], v[20:21], v[182:183]
	v_cvt_pk_bf16_f32 v125, v62, v63
	v_lshlrev_b32_e32 v64, 16, v126
	v_and_b32_e32 v65, 0xffff0000, v126
	v_pk_mul_f32 v[64:65], v[64:65], v[44:45]
	v_pk_fma_f32 v[64:65], v[64:65], v[22:23], v[184:185]
	v_cvt_pk_bf16_f32 v126, v64, v65
	v_lshlrev_b32_e32 v66, 16, v127
	v_and_b32_e32 v67, 0xffff0000, v127
	v_pk_mul_f32 v[66:67], v[66:67], v[44:45]
	v_pk_fma_f32 v[66:67], v[66:67], v[24:25], v[186:187]
	v_cvt_pk_bf16_f32 v127, v66, v67
	v_lshlrev_b32_e32 v60, 16, v128
	v_and_b32_e32 v61, 0xffff0000, v128
	v_pk_mul_f32 v[60:61], v[60:61], v[44:45]
	v_pk_fma_f32 v[60:61], v[60:61], v[26:27], v[188:189]
	v_cvt_pk_bf16_f32 v128, v60, v61
	v_lshlrev_b32_e32 v62, 16, v129
	v_and_b32_e32 v63, 0xffff0000, v129
	v_pk_mul_f32 v[62:63], v[62:63], v[44:45]
	v_pk_fma_f32 v[62:63], v[62:63], v[28:29], v[190:191]
	v_cvt_pk_bf16_f32 v129, v62, v63
	v_lshlrev_b32_e32 v64, 16, v130
	v_and_b32_e32 v65, 0xffff0000, v130
	v_pk_mul_f32 v[64:65], v[64:65], v[44:45]
	v_pk_fma_f32 v[64:65], v[64:65], v[30:31], v[192:193]
	v_cvt_pk_bf16_f32 v130, v64, v65
	v_lshlrev_b32_e32 v66, 16, v131
	v_and_b32_e32 v67, 0xffff0000, v131
	v_pk_mul_f32 v[66:67], v[66:67], v[44:45]
	v_pk_fma_f32 v[66:67], v[66:67], v[32:33], v[194:195]
	v_cvt_pk_bf16_f32 v131, v66, v67
	global_store_dwordx4 v39, v[116:119], s[20:21]
	global_store_dwordx4 v39, v[120:123], s[20:21] offset:1024
	global_store_dwordx4 v39, v[124:127], s[20:21] offset:2048
	global_store_dwordx4 v39, v[128:131], s[20:21] offset:3072
	s_add_u32 s20, s20, 0x1000
	s_addc_u32 s21, s21, 0
	global_load_dwordx4 v[116:119], v39, s[10:11]
	global_load_dwordx4 v[120:123], v39, s[10:11] offset:1024
	global_load_dwordx4 v[124:127], v39, s[10:11] offset:2048
	global_load_dwordx4 v[128:131], v39, s[10:11] offset:3072
	s_add_u32 s10, s10, 0x1000
	s_addc_u32 s11, s11, 0
	s_waitcnt vmcnt(20)
	v_lshlrev_b32_e32 v60, 16, v132
	v_and_b32_e32 v61, 0xffff0000, v132
	v_pk_mul_f32 v[42:43], v[60:61], v[60:61]
	v_lshlrev_b32_e32 v62, 16, v133
	v_and_b32_e32 v63, 0xffff0000, v133
	v_pk_fma_f32 v[42:43], v[62:63], v[62:63], v[42:43]
	v_lshlrev_b32_e32 v64, 16, v134
	v_and_b32_e32 v65, 0xffff0000, v134
	v_pk_fma_f32 v[42:43], v[64:65], v[64:65], v[42:43]
	v_lshlrev_b32_e32 v66, 16, v135
	v_and_b32_e32 v67, 0xffff0000, v135
	v_pk_fma_f32 v[42:43], v[66:67], v[66:67], v[42:43]
	v_lshlrev_b32_e32 v60, 16, v136
	v_and_b32_e32 v61, 0xffff0000, v136
	v_pk_fma_f32 v[42:43], v[60:61], v[60:61], v[42:43]
	v_lshlrev_b32_e32 v62, 16, v137
	v_and_b32_e32 v63, 0xffff0000, v137
	v_pk_fma_f32 v[42:43], v[62:63], v[62:63], v[42:43]
	v_lshlrev_b32_e32 v64, 16, v138
	v_and_b32_e32 v65, 0xffff0000, v138
	v_pk_fma_f32 v[42:43], v[64:65], v[64:65], v[42:43]
	v_lshlrev_b32_e32 v66, 16, v139
	v_and_b32_e32 v67, 0xffff0000, v139
	v_pk_fma_f32 v[42:43], v[66:67], v[66:67], v[42:43]
	v_lshlrev_b32_e32 v60, 16, v140
	v_and_b32_e32 v61, 0xffff0000, v140
	v_pk_fma_f32 v[42:43], v[60:61], v[60:61], v[42:43]
	v_lshlrev_b32_e32 v62, 16, v141
	v_and_b32_e32 v63, 0xffff0000, v141
	v_pk_fma_f32 v[42:43], v[62:63], v[62:63], v[42:43]
	v_lshlrev_b32_e32 v64, 16, v142
	v_and_b32_e32 v65, 0xffff0000, v142
	v_pk_fma_f32 v[42:43], v[64:65], v[64:65], v[42:43]
	v_lshlrev_b32_e32 v66, 16, v143
	v_and_b32_e32 v67, 0xffff0000, v143
	v_pk_fma_f32 v[42:43], v[66:67], v[66:67], v[42:43]
	v_lshlrev_b32_e32 v60, 16, v144
	v_and_b32_e32 v61, 0xffff0000, v144
	v_pk_fma_f32 v[42:43], v[60:61], v[60:61], v[42:43]
	v_lshlrev_b32_e32 v62, 16, v145
	v_and_b32_e32 v63, 0xffff0000, v145
	v_pk_fma_f32 v[42:43], v[62:63], v[62:63], v[42:43]
	v_lshlrev_b32_e32 v64, 16, v146
	v_and_b32_e32 v65, 0xffff0000, v146
	v_pk_fma_f32 v[42:43], v[64:65], v[64:65], v[42:43]
	v_lshlrev_b32_e32 v66, 16, v147
	v_and_b32_e32 v67, 0xffff0000, v147
	v_pk_fma_f32 v[42:43], v[66:67], v[66:67], v[42:43]
	v_add_f32_e32 v42, v42, v43
	s_nop 1
	v_add_f32_dpp v42, v42, v42 quad_perm:[1,0,3,2] row_mask:0xf bank_mask:0xf
	s_nop 1
	v_add_f32_dpp v42, v42, v42 quad_perm:[2,3,0,1] row_mask:0xf bank_mask:0xf
	s_nop 1
	v_add_f32_dpp v42, v42, v42 row_half_mirror row_mask:0xf bank_mask:0xf
	s_nop 1
	v_add_f32_dpp v42, v42, v42 row_mirror row_mask:0xf bank_mask:0xf
	s_nop 1
	v_add_f32_dpp v42, v42, v42 row_bcast:15 row_mask:0xa bank_mask:0xf
	s_nop 1
	v_add_f32_dpp v42, v42, v42 row_bcast:31 row_mask:0xc bank_mask:0xf
	s_nop 1
	v_readlane_b32 s100, v42, 63
	s_nop 3
	v_mov_b32_e32 v44, s100
	v_fma_f32 v44, v44, v47, v224
	v_rsq_f32_e32 v45, v44
	s_nop 0
	v_mul_f32_e32 v46, v44, v45
	v_mul_f32_e32 v46, v46, v45
	v_fmaak_f32 v46, -0.5, v46, 0x3fc00000
	v_mul_f32_e32 v44, v45, v46
	v_mov_b32_e32 v45, v44
	v_lshlrev_b32_e32 v60, 16, v132
	v_and_b32_e32 v61, 0xffff0000, v132
	v_pk_mul_f32 v[60:61], v[60:61], v[44:45]
	v_pk_fma_f32 v[60:61], v[60:61], v[2:3], v[164:165]
	v_cvt_pk_bf16_f32 v132, v60, v61
	v_lshlrev_b32_e32 v62, 16, v133
	v_and_b32_e32 v63, 0xffff0000, v133
	v_pk_mul_f32 v[62:63], v[62:63], v[44:45]
	v_pk_fma_f32 v[62:63], v[62:63], v[4:5], v[166:167]
	v_cvt_pk_bf16_f32 v133, v62, v63
	v_lshlrev_b32_e32 v64, 16, v134
	v_and_b32_e32 v65, 0xffff0000, v134
	v_pk_mul_f32 v[64:65], v[64:65], v[44:45]
	v_pk_fma_f32 v[64:65], v[64:65], v[6:7], v[168:169]
	v_cvt_pk_bf16_f32 v134, v64, v65
	v_lshlrev_b32_e32 v66, 16, v135
	v_and_b32_e32 v67, 0xffff0000, v135
	v_pk_mul_f32 v[66:67], v[66:67], v[44:45]
	v_pk_fma_f32 v[66:67], v[66:67], v[8:9], v[170:171]
	v_cvt_pk_bf16_f32 v135, v66, v67
	v_lshlrev_b32_e32 v60, 16, v136
	v_and_b32_e32 v61, 0xffff0000, v136
	v_pk_mul_f32 v[60:61], v[60:61], v[44:45]
	v_pk_fma_f32 v[60:61], v[60:61], v[10:11], v[172:173]
	v_cvt_pk_bf16_f32 v136, v60, v61
	v_lshlrev_b32_e32 v62, 16, v137
	v_and_b32_e32 v63, 0xffff0000, v137
	v_pk_mul_f32 v[62:63], v[62:63], v[44:45]
	v_pk_fma_f32 v[62:63], v[62:63], v[12:13], v[174:175]
	v_cvt_pk_bf16_f32 v137, v62, v63
	v_lshlrev_b32_e32 v64, 16, v138
	v_and_b32_e32 v65, 0xffff0000, v138
	v_pk_mul_f32 v[64:65], v[64:65], v[44:45]
	v_pk_fma_f32 v[64:65], v[64:65], v[14:15], v[176:177]
	v_cvt_pk_bf16_f32 v138, v64, v65
	v_lshlrev_b32_e32 v66, 16, v139
	v_and_b32_e32 v67, 0xffff0000, v139
	v_pk_mul_f32 v[66:67], v[66:67], v[44:45]
	v_pk_fma_f32 v[66:67], v[66:67], v[16:17], v[178:179]
	v_cvt_pk_bf16_f32 v139, v66, v67
	v_lshlrev_b32_e32 v60, 16, v140
	v_and_b32_e32 v61, 0xffff0000, v140
	v_pk_mul_f32 v[60:61], v[60:61], v[44:45]
	v_pk_fma_f32 v[60:61], v[60:61], v[18:19], v[180:181]
	v_cvt_pk_bf16_f32 v140, v60, v61
	v_lshlrev_b32_e32 v62, 16, v141
	v_and_b32_e32 v63, 0xffff0000, v141
	v_pk_mul_f32 v[62:63], v[62:63], v[44:45]
	v_pk_fma_f32 v[62:63], v[62:63], v[20:21], v[182:183]
	v_cvt_pk_bf16_f32 v141, v62, v63
	v_lshlrev_b32_e32 v64, 16, v142
	v_and_b32_e32 v65, 0xffff0000, v142
	v_pk_mul_f32 v[64:65], v[64:65], v[44:45]
	v_pk_fma_f32 v[64:65], v[64:65], v[22:23], v[184:185]
	v_cvt_pk_bf16_f32 v142, v64, v65
	v_lshlrev_b32_e32 v66, 16, v143
	v_and_b32_e32 v67, 0xffff0000, v143
	v_pk_mul_f32 v[66:67], v[66:67], v[44:45]
	v_pk_fma_f32 v[66:67], v[66:67], v[24:25], v[186:187]
	v_cvt_pk_bf16_f32 v143, v66, v67
	v_lshlrev_b32_e32 v60, 16, v144
	v_and_b32_e32 v61, 0xffff0000, v144
	v_pk_mul_f32 v[60:61], v[60:61], v[44:45]
	v_pk_fma_f32 v[60:61], v[60:61], v[26:27], v[188:189]
	v_cvt_pk_bf16_f32 v144, v60, v61
	v_lshlrev_b32_e32 v62, 16, v145
	v_and_b32_e32 v63, 0xffff0000, v145
	v_pk_mul_f32 v[62:63], v[62:63], v[44:45]
	v_pk_fma_f32 v[62:63], v[62:63], v[28:29], v[190:191]
	v_cvt_pk_bf16_f32 v145, v62, v63
	v_lshlrev_b32_e32 v64, 16, v146
	v_and_b32_e32 v65, 0xffff0000, v146
	v_pk_mul_f32 v[64:65], v[64:65], v[44:45]
	v_pk_fma_f32 v[64:65], v[64:65], v[30:31], v[192:193]
	v_cvt_pk_bf16_f32 v146, v64, v65
	v_lshlrev_b32_e32 v66, 16, v147
	v_and_b32_e32 v67, 0xffff0000, v147
	v_pk_mul_f32 v[66:67], v[66:67], v[44:45]
	v_pk_fma_f32 v[66:67], v[66:67], v[32:33], v[194:195]
	v_cvt_pk_bf16_f32 v147, v66, v67
	global_store_dwordx4 v39, v[132:135], s[20:21]
	global_store_dwordx4 v39, v[136:139], s[20:21] offset:1024
	global_store_dwordx4 v39, v[140:143], s[20:21] offset:2048
	global_store_dwordx4 v39, v[144:147], s[20:21] offset:3072
	s_add_u32 s20, s20, 0x1000
	s_addc_u32 s21, s21, 0
	global_load_dwordx4 v[132:135], v39, s[10:11]
	global_load_dwordx4 v[136:139], v39, s[10:11] offset:1024
	global_load_dwordx4 v[140:143], v39, s[10:11] offset:2048
	global_load_dwordx4 v[144:147], v39, s[10:11] offset:3072
	s_add_u32 s10, s10, 0x1000
	s_addc_u32 s11, s11, 0
	s_waitcnt vmcnt(24)
	v_lshlrev_b32_e32 v60, 16, v148
	v_and_b32_e32 v61, 0xffff0000, v148
	v_pk_mul_f32 v[42:43], v[60:61], v[60:61]
	v_lshlrev_b32_e32 v62, 16, v149
	v_and_b32_e32 v63, 0xffff0000, v149
	v_pk_fma_f32 v[42:43], v[62:63], v[62:63], v[42:43]
	v_lshlrev_b32_e32 v64, 16, v150
	v_and_b32_e32 v65, 0xffff0000, v150
	v_pk_fma_f32 v[42:43], v[64:65], v[64:65], v[42:43]
	v_lshlrev_b32_e32 v66, 16, v151
	v_and_b32_e32 v67, 0xffff0000, v151
	v_pk_fma_f32 v[42:43], v[66:67], v[66:67], v[42:43]
	v_lshlrev_b32_e32 v60, 16, v152
	v_and_b32_e32 v61, 0xffff0000, v152
	v_pk_fma_f32 v[42:43], v[60:61], v[60:61], v[42:43]
	v_lshlrev_b32_e32 v62, 16, v153
	v_and_b32_e32 v63, 0xffff0000, v153
	v_pk_fma_f32 v[42:43], v[62:63], v[62:63], v[42:43]
	v_lshlrev_b32_e32 v64, 16, v154
	v_and_b32_e32 v65, 0xffff0000, v154
	v_pk_fma_f32 v[42:43], v[64:65], v[64:65], v[42:43]
	v_lshlrev_b32_e32 v66, 16, v155
	v_and_b32_e32 v67, 0xffff0000, v155
	v_pk_fma_f32 v[42:43], v[66:67], v[66:67], v[42:43]
	v_lshlrev_b32_e32 v60, 16, v156
	v_and_b32_e32 v61, 0xffff0000, v156
	v_pk_fma_f32 v[42:43], v[60:61], v[60:61], v[42:43]
	v_lshlrev_b32_e32 v62, 16, v157
	v_and_b32_e32 v63, 0xffff0000, v157
	v_pk_fma_f32 v[42:43], v[62:63], v[62:63], v[42:43]
	v_lshlrev_b32_e32 v64, 16, v158
	v_and_b32_e32 v65, 0xffff0000, v158
	v_pk_fma_f32 v[42:43], v[64:65], v[64:65], v[42:43]
	v_lshlrev_b32_e32 v66, 16, v159
	v_and_b32_e32 v67, 0xffff0000, v159
	v_pk_fma_f32 v[42:43], v[66:67], v[66:67], v[42:43]
	v_lshlrev_b32_e32 v60, 16, v160
	v_and_b32_e32 v61, 0xffff0000, v160
	v_pk_fma_f32 v[42:43], v[60:61], v[60:61], v[42:43]
	v_lshlrev_b32_e32 v62, 16, v161
	v_and_b32_e32 v63, 0xffff0000, v161
	v_pk_fma_f32 v[42:43], v[62:63], v[62:63], v[42:43]
	v_lshlrev_b32_e32 v64, 16, v162
	v_and_b32_e32 v65, 0xffff0000, v162
	v_pk_fma_f32 v[42:43], v[64:65], v[64:65], v[42:43]
	v_lshlrev_b32_e32 v66, 16, v163
	v_and_b32_e32 v67, 0xffff0000, v163
	v_pk_fma_f32 v[42:43], v[66:67], v[66:67], v[42:43]
	v_add_f32_e32 v42, v42, v43
	s_nop 1
	v_add_f32_dpp v42, v42, v42 quad_perm:[1,0,3,2] row_mask:0xf bank_mask:0xf
	s_nop 1
	v_add_f32_dpp v42, v42, v42 quad_perm:[2,3,0,1] row_mask:0xf bank_mask:0xf
	s_nop 1
	v_add_f32_dpp v42, v42, v42 row_half_mirror row_mask:0xf bank_mask:0xf
	s_nop 1
	v_add_f32_dpp v42, v42, v42 row_mirror row_mask:0xf bank_mask:0xf
	s_nop 1
	v_add_f32_dpp v42, v42, v42 row_bcast:15 row_mask:0xa bank_mask:0xf
	s_nop 1
	v_add_f32_dpp v42, v42, v42 row_bcast:31 row_mask:0xc bank_mask:0xf
	s_nop 1
	v_readlane_b32 s100, v42, 63
	s_nop 3
	v_mov_b32_e32 v44, s100
	v_fma_f32 v44, v44, v47, v224
	v_rsq_f32_e32 v45, v44
	s_nop 0
	v_mul_f32_e32 v46, v44, v45
	v_mul_f32_e32 v46, v46, v45
	v_fmaak_f32 v46, -0.5, v46, 0x3fc00000
	v_mul_f32_e32 v44, v45, v46
	v_mov_b32_e32 v45, v44
	v_lshlrev_b32_e32 v60, 16, v148
	v_and_b32_e32 v61, 0xffff0000, v148
	v_pk_mul_f32 v[60:61], v[60:61], v[44:45]
	v_pk_fma_f32 v[60:61], v[60:61], v[2:3], v[164:165]
	v_cvt_pk_bf16_f32 v148, v60, v61
	v_lshlrev_b32_e32 v62, 16, v149
	v_and_b32_e32 v63, 0xffff0000, v149
	v_pk_mul_f32 v[62:63], v[62:63], v[44:45]
	v_pk_fma_f32 v[62:63], v[62:63], v[4:5], v[166:167]
	v_cvt_pk_bf16_f32 v149, v62, v63
	v_lshlrev_b32_e32 v64, 16, v150
	v_and_b32_e32 v65, 0xffff0000, v150
	v_pk_mul_f32 v[64:65], v[64:65], v[44:45]
	v_pk_fma_f32 v[64:65], v[64:65], v[6:7], v[168:169]
	v_cvt_pk_bf16_f32 v150, v64, v65
	v_lshlrev_b32_e32 v66, 16, v151
	v_and_b32_e32 v67, 0xffff0000, v151
	v_pk_mul_f32 v[66:67], v[66:67], v[44:45]
	v_pk_fma_f32 v[66:67], v[66:67], v[8:9], v[170:171]
	v_cvt_pk_bf16_f32 v151, v66, v67
	v_lshlrev_b32_e32 v60, 16, v152
	v_and_b32_e32 v61, 0xffff0000, v152
	v_pk_mul_f32 v[60:61], v[60:61], v[44:45]
	v_pk_fma_f32 v[60:61], v[60:61], v[10:11], v[172:173]
	v_cvt_pk_bf16_f32 v152, v60, v61
	v_lshlrev_b32_e32 v62, 16, v153
	v_and_b32_e32 v63, 0xffff0000, v153
	v_pk_mul_f32 v[62:63], v[62:63], v[44:45]
	v_pk_fma_f32 v[62:63], v[62:63], v[12:13], v[174:175]
	v_cvt_pk_bf16_f32 v153, v62, v63
	v_lshlrev_b32_e32 v64, 16, v154
	v_and_b32_e32 v65, 0xffff0000, v154
	v_pk_mul_f32 v[64:65], v[64:65], v[44:45]
	v_pk_fma_f32 v[64:65], v[64:65], v[14:15], v[176:177]
	v_cvt_pk_bf16_f32 v154, v64, v65
	v_lshlrev_b32_e32 v66, 16, v155
	v_and_b32_e32 v67, 0xffff0000, v155
	v_pk_mul_f32 v[66:67], v[66:67], v[44:45]
	v_pk_fma_f32 v[66:67], v[66:67], v[16:17], v[178:179]
	v_cvt_pk_bf16_f32 v155, v66, v67
	v_lshlrev_b32_e32 v60, 16, v156
	v_and_b32_e32 v61, 0xffff0000, v156
	v_pk_mul_f32 v[60:61], v[60:61], v[44:45]
	v_pk_fma_f32 v[60:61], v[60:61], v[18:19], v[180:181]
	v_cvt_pk_bf16_f32 v156, v60, v61
	v_lshlrev_b32_e32 v62, 16, v157
	v_and_b32_e32 v63, 0xffff0000, v157
	v_pk_mul_f32 v[62:63], v[62:63], v[44:45]
	v_pk_fma_f32 v[62:63], v[62:63], v[20:21], v[182:183]
	v_cvt_pk_bf16_f32 v157, v62, v63
	v_lshlrev_b32_e32 v64, 16, v158
	v_and_b32_e32 v65, 0xffff0000, v158
	v_pk_mul_f32 v[64:65], v[64:65], v[44:45]
	v_pk_fma_f32 v[64:65], v[64:65], v[22:23], v[184:185]
	v_cvt_pk_bf16_f32 v158, v64, v65
	v_lshlrev_b32_e32 v66, 16, v159
	v_and_b32_e32 v67, 0xffff0000, v159
	v_pk_mul_f32 v[66:67], v[66:67], v[44:45]
	v_pk_fma_f32 v[66:67], v[66:67], v[24:25], v[186:187]
	v_cvt_pk_bf16_f32 v159, v66, v67
	v_lshlrev_b32_e32 v60, 16, v160
	v_and_b32_e32 v61, 0xffff0000, v160
	v_pk_mul_f32 v[60:61], v[60:61], v[44:45]
	v_pk_fma_f32 v[60:61], v[60:61], v[26:27], v[188:189]
	v_cvt_pk_bf16_f32 v160, v60, v61
	v_lshlrev_b32_e32 v62, 16, v161
	v_and_b32_e32 v63, 0xffff0000, v161
	v_pk_mul_f32 v[62:63], v[62:63], v[44:45]
	v_pk_fma_f32 v[62:63], v[62:63], v[28:29], v[190:191]
	v_cvt_pk_bf16_f32 v161, v62, v63
	v_lshlrev_b32_e32 v64, 16, v162
	v_and_b32_e32 v65, 0xffff0000, v162
	v_pk_mul_f32 v[64:65], v[64:65], v[44:45]
	v_pk_fma_f32 v[64:65], v[64:65], v[30:31], v[192:193]
	v_cvt_pk_bf16_f32 v162, v64, v65
	v_lshlrev_b32_e32 v66, 16, v163
	v_and_b32_e32 v67, 0xffff0000, v163
	v_pk_mul_f32 v[66:67], v[66:67], v[44:45]
	v_pk_fma_f32 v[66:67], v[66:67], v[32:33], v[194:195]
	v_cvt_pk_bf16_f32 v163, v66, v67
	global_store_dwordx4 v39, v[148:151], s[20:21]
	global_store_dwordx4 v39, v[152:155], s[20:21] offset:1024
	global_store_dwordx4 v39, v[156:159], s[20:21] offset:2048
	global_store_dwordx4 v39, v[160:163], s[20:21] offset:3072
	s_add_u32 s20, s20, 0x1000
	s_addc_u32 s21, s21, 0
	global_load_dwordx4 v[148:151], v39, s[10:11]
	global_load_dwordx4 v[152:155], v39, s[10:11] offset:1024
	global_load_dwordx4 v[156:159], v39, s[10:11] offset:2048
	global_load_dwordx4 v[160:163], v39, s[10:11] offset:3072
	s_add_u32 s10, s10, 0x1000
	s_addc_u32 s11, s11, 0
	s_waitcnt vmcnt(24)
	v_lshlrev_b32_e32 v60, 16, v100
	v_and_b32_e32 v61, 0xffff0000, v100
	v_pk_mul_f32 v[42:43], v[60:61], v[60:61]
	v_lshlrev_b32_e32 v62, 16, v101
	v_and_b32_e32 v63, 0xffff0000, v101
	v_pk_fma_f32 v[42:43], v[62:63], v[62:63], v[42:43]
	v_lshlrev_b32_e32 v64, 16, v102
	v_and_b32_e32 v65, 0xffff0000, v102
	v_pk_fma_f32 v[42:43], v[64:65], v[64:65], v[42:43]
	v_lshlrev_b32_e32 v66, 16, v103
	v_and_b32_e32 v67, 0xffff0000, v103
	v_pk_fma_f32 v[42:43], v[66:67], v[66:67], v[42:43]
	v_lshlrev_b32_e32 v60, 16, v104
	v_and_b32_e32 v61, 0xffff0000, v104
	v_pk_fma_f32 v[42:43], v[60:61], v[60:61], v[42:43]
	v_lshlrev_b32_e32 v62, 16, v105
	v_and_b32_e32 v63, 0xffff0000, v105
	v_pk_fma_f32 v[42:43], v[62:63], v[62:63], v[42:43]
	v_lshlrev_b32_e32 v64, 16, v106
	v_and_b32_e32 v65, 0xffff0000, v106
	v_pk_fma_f32 v[42:43], v[64:65], v[64:65], v[42:43]
	v_lshlrev_b32_e32 v66, 16, v107
	v_and_b32_e32 v67, 0xffff0000, v107
	v_pk_fma_f32 v[42:43], v[66:67], v[66:67], v[42:43]
	v_lshlrev_b32_e32 v60, 16, v108
	v_and_b32_e32 v61, 0xffff0000, v108
	v_pk_fma_f32 v[42:43], v[60:61], v[60:61], v[42:43]
	v_lshlrev_b32_e32 v62, 16, v109
	v_and_b32_e32 v63, 0xffff0000, v109
	v_pk_fma_f32 v[42:43], v[62:63], v[62:63], v[42:43]
	v_lshlrev_b32_e32 v64, 16, v110
	v_and_b32_e32 v65, 0xffff0000, v110
	v_pk_fma_f32 v[42:43], v[64:65], v[64:65], v[42:43]
	v_lshlrev_b32_e32 v66, 16, v111
	v_and_b32_e32 v67, 0xffff0000, v111
	v_pk_fma_f32 v[42:43], v[66:67], v[66:67], v[42:43]
	v_lshlrev_b32_e32 v60, 16, v112
	v_and_b32_e32 v61, 0xffff0000, v112
	v_pk_fma_f32 v[42:43], v[60:61], v[60:61], v[42:43]
	v_lshlrev_b32_e32 v62, 16, v113
	v_and_b32_e32 v63, 0xffff0000, v113
	v_pk_fma_f32 v[42:43], v[62:63], v[62:63], v[42:43]
	v_lshlrev_b32_e32 v64, 16, v114
	v_and_b32_e32 v65, 0xffff0000, v114
	v_pk_fma_f32 v[42:43], v[64:65], v[64:65], v[42:43]
	v_lshlrev_b32_e32 v66, 16, v115
	v_and_b32_e32 v67, 0xffff0000, v115
	v_pk_fma_f32 v[42:43], v[66:67], v[66:67], v[42:43]
	v_add_f32_e32 v42, v42, v43
	s_nop 1
	v_add_f32_dpp v42, v42, v42 quad_perm:[1,0,3,2] row_mask:0xf bank_mask:0xf
	s_nop 1
	v_add_f32_dpp v42, v42, v42 quad_perm:[2,3,0,1] row_mask:0xf bank_mask:0xf
	s_nop 1
	v_add_f32_dpp v42, v42, v42 row_half_mirror row_mask:0xf bank_mask:0xf
	s_nop 1
	v_add_f32_dpp v42, v42, v42 row_mirror row_mask:0xf bank_mask:0xf
	s_nop 1
	v_add_f32_dpp v42, v42, v42 row_bcast:15 row_mask:0xa bank_mask:0xf
	s_nop 1
	v_add_f32_dpp v42, v42, v42 row_bcast:31 row_mask:0xc bank_mask:0xf
	s_nop 1
	v_readlane_b32 s100, v42, 63
	s_nop 3
	v_mov_b32_e32 v44, s100
	v_fma_f32 v44, v44, v47, v224
	v_rsq_f32_e32 v45, v44
	s_nop 0
	v_mul_f32_e32 v46, v44, v45
	v_mul_f32_e32 v46, v46, v45
	v_fmaak_f32 v46, -0.5, v46, 0x3fc00000
	v_mul_f32_e32 v44, v45, v46
	v_mov_b32_e32 v45, v44
	v_lshlrev_b32_e32 v60, 16, v100
	v_and_b32_e32 v61, 0xffff0000, v100
	v_pk_mul_f32 v[60:61], v[60:61], v[44:45]
	v_pk_fma_f32 v[60:61], v[60:61], v[2:3], v[164:165]
	v_cvt_pk_bf16_f32 v100, v60, v61
	v_lshlrev_b32_e32 v62, 16, v101
	v_and_b32_e32 v63, 0xffff0000, v101
	v_pk_mul_f32 v[62:63], v[62:63], v[44:45]
	v_pk_fma_f32 v[62:63], v[62:63], v[4:5], v[166:167]
	v_cvt_pk_bf16_f32 v101, v62, v63
	v_lshlrev_b32_e32 v64, 16, v102
	v_and_b32_e32 v65, 0xffff0000, v102
	v_pk_mul_f32 v[64:65], v[64:65], v[44:45]
	v_pk_fma_f32 v[64:65], v[64:65], v[6:7], v[168:169]
	v_cvt_pk_bf16_f32 v102, v64, v65
	v_lshlrev_b32_e32 v66, 16, v103
	v_and_b32_e32 v67, 0xffff0000, v103
	v_pk_mul_f32 v[66:67], v[66:67], v[44:45]
	v_pk_fma_f32 v[66:67], v[66:67], v[8:9], v[170:171]
	v_cvt_pk_bf16_f32 v103, v66, v67
	v_lshlrev_b32_e32 v60, 16, v104
	v_and_b32_e32 v61, 0xffff0000, v104
	v_pk_mul_f32 v[60:61], v[60:61], v[44:45]
	v_pk_fma_f32 v[60:61], v[60:61], v[10:11], v[172:173]
	v_cvt_pk_bf16_f32 v104, v60, v61
	v_lshlrev_b32_e32 v62, 16, v105
	v_and_b32_e32 v63, 0xffff0000, v105
	v_pk_mul_f32 v[62:63], v[62:63], v[44:45]
	v_pk_fma_f32 v[62:63], v[62:63], v[12:13], v[174:175]
	v_cvt_pk_bf16_f32 v105, v62, v63
	v_lshlrev_b32_e32 v64, 16, v106
	v_and_b32_e32 v65, 0xffff0000, v106
	v_pk_mul_f32 v[64:65], v[64:65], v[44:45]
	v_pk_fma_f32 v[64:65], v[64:65], v[14:15], v[176:177]
	v_cvt_pk_bf16_f32 v106, v64, v65
	v_lshlrev_b32_e32 v66, 16, v107
	v_and_b32_e32 v67, 0xffff0000, v107
	v_pk_mul_f32 v[66:67], v[66:67], v[44:45]
	v_pk_fma_f32 v[66:67], v[66:67], v[16:17], v[178:179]
	v_cvt_pk_bf16_f32 v107, v66, v67
	v_lshlrev_b32_e32 v60, 16, v108
	v_and_b32_e32 v61, 0xffff0000, v108
	v_pk_mul_f32 v[60:61], v[60:61], v[44:45]
	v_pk_fma_f32 v[60:61], v[60:61], v[18:19], v[180:181]
	v_cvt_pk_bf16_f32 v108, v60, v61
	v_lshlrev_b32_e32 v62, 16, v109
	v_and_b32_e32 v63, 0xffff0000, v109
	v_pk_mul_f32 v[62:63], v[62:63], v[44:45]
	v_pk_fma_f32 v[62:63], v[62:63], v[20:21], v[182:183]
	v_cvt_pk_bf16_f32 v109, v62, v63
	v_lshlrev_b32_e32 v64, 16, v110
	v_and_b32_e32 v65, 0xffff0000, v110
	v_pk_mul_f32 v[64:65], v[64:65], v[44:45]
	v_pk_fma_f32 v[64:65], v[64:65], v[22:23], v[184:185]
	v_cvt_pk_bf16_f32 v110, v64, v65
	v_lshlrev_b32_e32 v66, 16, v111
	v_and_b32_e32 v67, 0xffff0000, v111
	v_pk_mul_f32 v[66:67], v[66:67], v[44:45]
	v_pk_fma_f32 v[66:67], v[66:67], v[24:25], v[186:187]
	v_cvt_pk_bf16_f32 v111, v66, v67
	v_lshlrev_b32_e32 v60, 16, v112
	v_and_b32_e32 v61, 0xffff0000, v112
	v_pk_mul_f32 v[60:61], v[60:61], v[44:45]
	v_pk_fma_f32 v[60:61], v[60:61], v[26:27], v[188:189]
	v_cvt_pk_bf16_f32 v112, v60, v61
	v_lshlrev_b32_e32 v62, 16, v113
	v_and_b32_e32 v63, 0xffff0000, v113
	v_pk_mul_f32 v[62:63], v[62:63], v[44:45]
	v_pk_fma_f32 v[62:63], v[62:63], v[28:29], v[190:191]
	v_cvt_pk_bf16_f32 v113, v62, v63
	v_lshlrev_b32_e32 v64, 16, v114
	v_and_b32_e32 v65, 0xffff0000, v114
	v_pk_mul_f32 v[64:65], v[64:65], v[44:45]
	v_pk_fma_f32 v[64:65], v[64:65], v[30:31], v[192:193]
	v_cvt_pk_bf16_f32 v114, v64, v65
	v_lshlrev_b32_e32 v66, 16, v115
	v_and_b32_e32 v67, 0xffff0000, v115
	v_pk_mul_f32 v[66:67], v[66:67], v[44:45]
	v_pk_fma_f32 v[66:67], v[66:67], v[32:33], v[194:195]
	v_cvt_pk_bf16_f32 v115, v66, v67
	global_store_dwordx4 v39, v[100:103], s[20:21]
	global_store_dwordx4 v39, v[104:107], s[20:21] offset:1024
	global_store_dwordx4 v39, v[108:111], s[20:21] offset:2048
	global_store_dwordx4 v39, v[112:115], s[20:21] offset:3072
	s_add_u32 s20, s20, 0x1000
	s_addc_u32 s21, s21, 0
	s_waitcnt vmcnt(20)
	v_lshlrev_b32_e32 v60, 16, v116
	v_and_b32_e32 v61, 0xffff0000, v116
	v_pk_mul_f32 v[42:43], v[60:61], v[60:61]
	v_lshlrev_b32_e32 v62, 16, v117
	v_and_b32_e32 v63, 0xffff0000, v117
	v_pk_fma_f32 v[42:43], v[62:63], v[62:63], v[42:43]
	v_lshlrev_b32_e32 v64, 16, v118
	v_and_b32_e32 v65, 0xffff0000, v118
	v_pk_fma_f32 v[42:43], v[64:65], v[64:65], v[42:43]
	v_lshlrev_b32_e32 v66, 16, v119
	v_and_b32_e32 v67, 0xffff0000, v119
	v_pk_fma_f32 v[42:43], v[66:67], v[66:67], v[42:43]
	v_lshlrev_b32_e32 v60, 16, v120
	v_and_b32_e32 v61, 0xffff0000, v120
	v_pk_fma_f32 v[42:43], v[60:61], v[60:61], v[42:43]
	v_lshlrev_b32_e32 v62, 16, v121
	v_and_b32_e32 v63, 0xffff0000, v121
	v_pk_fma_f32 v[42:43], v[62:63], v[62:63], v[42:43]
	v_lshlrev_b32_e32 v64, 16, v122
	v_and_b32_e32 v65, 0xffff0000, v122
	v_pk_fma_f32 v[42:43], v[64:65], v[64:65], v[42:43]
	v_lshlrev_b32_e32 v66, 16, v123
	v_and_b32_e32 v67, 0xffff0000, v123
	v_pk_fma_f32 v[42:43], v[66:67], v[66:67], v[42:43]
	v_lshlrev_b32_e32 v60, 16, v124
	v_and_b32_e32 v61, 0xffff0000, v124
	v_pk_fma_f32 v[42:43], v[60:61], v[60:61], v[42:43]
	v_lshlrev_b32_e32 v62, 16, v125
	v_and_b32_e32 v63, 0xffff0000, v125
	v_pk_fma_f32 v[42:43], v[62:63], v[62:63], v[42:43]
	v_lshlrev_b32_e32 v64, 16, v126
	v_and_b32_e32 v65, 0xffff0000, v126
	v_pk_fma_f32 v[42:43], v[64:65], v[64:65], v[42:43]
	v_lshlrev_b32_e32 v66, 16, v127
	v_and_b32_e32 v67, 0xffff0000, v127
	v_pk_fma_f32 v[42:43], v[66:67], v[66:67], v[42:43]
	v_lshlrev_b32_e32 v60, 16, v128
	v_and_b32_e32 v61, 0xffff0000, v128
	v_pk_fma_f32 v[42:43], v[60:61], v[60:61], v[42:43]
	v_lshlrev_b32_e32 v62, 16, v129
	v_and_b32_e32 v63, 0xffff0000, v129
	v_pk_fma_f32 v[42:43], v[62:63], v[62:63], v[42:43]
	v_lshlrev_b32_e32 v64, 16, v130
	v_and_b32_e32 v65, 0xffff0000, v130
	v_pk_fma_f32 v[42:43], v[64:65], v[64:65], v[42:43]
	v_lshlrev_b32_e32 v66, 16, v131
	v_and_b32_e32 v67, 0xffff0000, v131
	v_pk_fma_f32 v[42:43], v[66:67], v[66:67], v[42:43]
	v_add_f32_e32 v42, v42, v43
	s_nop 1
	v_add_f32_dpp v42, v42, v42 quad_perm:[1,0,3,2] row_mask:0xf bank_mask:0xf
	s_nop 1
	v_add_f32_dpp v42, v42, v42 quad_perm:[2,3,0,1] row_mask:0xf bank_mask:0xf
	s_nop 1
	v_add_f32_dpp v42, v42, v42 row_half_mirror row_mask:0xf bank_mask:0xf
	s_nop 1
	v_add_f32_dpp v42, v42, v42 row_mirror row_mask:0xf bank_mask:0xf
	s_nop 1
	v_add_f32_dpp v42, v42, v42 row_bcast:15 row_mask:0xa bank_mask:0xf
	s_nop 1
	v_add_f32_dpp v42, v42, v42 row_bcast:31 row_mask:0xc bank_mask:0xf
	s_nop 1
	v_readlane_b32 s100, v42, 63
	s_nop 3
	v_mov_b32_e32 v44, s100
	v_fma_f32 v44, v44, v47, v224
	v_rsq_f32_e32 v45, v44
	s_nop 0
	v_mul_f32_e32 v46, v44, v45
	v_mul_f32_e32 v46, v46, v45
	v_fmaak_f32 v46, -0.5, v46, 0x3fc00000
	v_mul_f32_e32 v44, v45, v46
	v_mov_b32_e32 v45, v44
	v_lshlrev_b32_e32 v60, 16, v116
	v_and_b32_e32 v61, 0xffff0000, v116
	v_pk_mul_f32 v[60:61], v[60:61], v[44:45]
	v_pk_fma_f32 v[60:61], v[60:61], v[2:3], v[164:165]
	v_cvt_pk_bf16_f32 v116, v60, v61
	v_lshlrev_b32_e32 v62, 16, v117
	v_and_b32_e32 v63, 0xffff0000, v117
	v_pk_mul_f32 v[62:63], v[62:63], v[44:45]
	v_pk_fma_f32 v[62:63], v[62:63], v[4:5], v[166:167]
	v_cvt_pk_bf16_f32 v117, v62, v63
	v_lshlrev_b32_e32 v64, 16, v118
	v_and_b32_e32 v65, 0xffff0000, v118
	v_pk_mul_f32 v[64:65], v[64:65], v[44:45]
	v_pk_fma_f32 v[64:65], v[64:65], v[6:7], v[168:169]
	v_cvt_pk_bf16_f32 v118, v64, v65
	v_lshlrev_b32_e32 v66, 16, v119
	v_and_b32_e32 v67, 0xffff0000, v119
	v_pk_mul_f32 v[66:67], v[66:67], v[44:45]
	v_pk_fma_f32 v[66:67], v[66:67], v[8:9], v[170:171]
	v_cvt_pk_bf16_f32 v119, v66, v67
	v_lshlrev_b32_e32 v60, 16, v120
	v_and_b32_e32 v61, 0xffff0000, v120
	v_pk_mul_f32 v[60:61], v[60:61], v[44:45]
	v_pk_fma_f32 v[60:61], v[60:61], v[10:11], v[172:173]
	v_cvt_pk_bf16_f32 v120, v60, v61
	v_lshlrev_b32_e32 v62, 16, v121
	v_and_b32_e32 v63, 0xffff0000, v121
	v_pk_mul_f32 v[62:63], v[62:63], v[44:45]
	v_pk_fma_f32 v[62:63], v[62:63], v[12:13], v[174:175]
	v_cvt_pk_bf16_f32 v121, v62, v63
	v_lshlrev_b32_e32 v64, 16, v122
	v_and_b32_e32 v65, 0xffff0000, v122
	v_pk_mul_f32 v[64:65], v[64:65], v[44:45]
	v_pk_fma_f32 v[64:65], v[64:65], v[14:15], v[176:177]
	v_cvt_pk_bf16_f32 v122, v64, v65
	v_lshlrev_b32_e32 v66, 16, v123
	v_and_b32_e32 v67, 0xffff0000, v123
	v_pk_mul_f32 v[66:67], v[66:67], v[44:45]
	v_pk_fma_f32 v[66:67], v[66:67], v[16:17], v[178:179]
	v_cvt_pk_bf16_f32 v123, v66, v67
	v_lshlrev_b32_e32 v60, 16, v124
	v_and_b32_e32 v61, 0xffff0000, v124
	v_pk_mul_f32 v[60:61], v[60:61], v[44:45]
	v_pk_fma_f32 v[60:61], v[60:61], v[18:19], v[180:181]
	v_cvt_pk_bf16_f32 v124, v60, v61
	v_lshlrev_b32_e32 v62, 16, v125
	v_and_b32_e32 v63, 0xffff0000, v125
	v_pk_mul_f32 v[62:63], v[62:63], v[44:45]
	v_pk_fma_f32 v[62:63], v[62:63], v[20:21], v[182:183]
	v_cvt_pk_bf16_f32 v125, v62, v63
	v_lshlrev_b32_e32 v64, 16, v126
	v_and_b32_e32 v65, 0xffff0000, v126
	v_pk_mul_f32 v[64:65], v[64:65], v[44:45]
	v_pk_fma_f32 v[64:65], v[64:65], v[22:23], v[184:185]
	v_cvt_pk_bf16_f32 v126, v64, v65
	v_lshlrev_b32_e32 v66, 16, v127
	v_and_b32_e32 v67, 0xffff0000, v127
	v_pk_mul_f32 v[66:67], v[66:67], v[44:45]
	v_pk_fma_f32 v[66:67], v[66:67], v[24:25], v[186:187]
	v_cvt_pk_bf16_f32 v127, v66, v67
	v_lshlrev_b32_e32 v60, 16, v128
	v_and_b32_e32 v61, 0xffff0000, v128
	v_pk_mul_f32 v[60:61], v[60:61], v[44:45]
	v_pk_fma_f32 v[60:61], v[60:61], v[26:27], v[188:189]
	v_cvt_pk_bf16_f32 v128, v60, v61
	v_lshlrev_b32_e32 v62, 16, v129
	v_and_b32_e32 v63, 0xffff0000, v129
	v_pk_mul_f32 v[62:63], v[62:63], v[44:45]
	v_pk_fma_f32 v[62:63], v[62:63], v[28:29], v[190:191]
	v_cvt_pk_bf16_f32 v129, v62, v63
	v_lshlrev_b32_e32 v64, 16, v130
	v_and_b32_e32 v65, 0xffff0000, v130
	v_pk_mul_f32 v[64:65], v[64:65], v[44:45]
	v_pk_fma_f32 v[64:65], v[64:65], v[30:31], v[192:193]
	v_cvt_pk_bf16_f32 v130, v64, v65
	v_lshlrev_b32_e32 v66, 16, v131
	v_and_b32_e32 v67, 0xffff0000, v131
	v_pk_mul_f32 v[66:67], v[66:67], v[44:45]
	v_pk_fma_f32 v[66:67], v[66:67], v[32:33], v[194:195]
	v_cvt_pk_bf16_f32 v131, v66, v67
	global_store_dwordx4 v39, v[116:119], s[20:21]
	global_store_dwordx4 v39, v[120:123], s[20:21] offset:1024
	global_store_dwordx4 v39, v[124:127], s[20:21] offset:2048
	global_store_dwordx4 v39, v[128:131], s[20:21] offset:3072
	s_add_u32 s20, s20, 0x1000
	s_addc_u32 s21, s21, 0
	s_waitcnt vmcnt(16)
	v_lshlrev_b32_e32 v60, 16, v132
	v_and_b32_e32 v61, 0xffff0000, v132
	v_pk_mul_f32 v[42:43], v[60:61], v[60:61]
	v_lshlrev_b32_e32 v62, 16, v133
	v_and_b32_e32 v63, 0xffff0000, v133
	v_pk_fma_f32 v[42:43], v[62:63], v[62:63], v[42:43]
	v_lshlrev_b32_e32 v64, 16, v134
	v_and_b32_e32 v65, 0xffff0000, v134
	v_pk_fma_f32 v[42:43], v[64:65], v[64:65], v[42:43]
	v_lshlrev_b32_e32 v66, 16, v135
	v_and_b32_e32 v67, 0xffff0000, v135
	v_pk_fma_f32 v[42:43], v[66:67], v[66:67], v[42:43]
	v_lshlrev_b32_e32 v60, 16, v136
	v_and_b32_e32 v61, 0xffff0000, v136
	v_pk_fma_f32 v[42:43], v[60:61], v[60:61], v[42:43]
	v_lshlrev_b32_e32 v62, 16, v137
	v_and_b32_e32 v63, 0xffff0000, v137
	v_pk_fma_f32 v[42:43], v[62:63], v[62:63], v[42:43]
	v_lshlrev_b32_e32 v64, 16, v138
	v_and_b32_e32 v65, 0xffff0000, v138
	v_pk_fma_f32 v[42:43], v[64:65], v[64:65], v[42:43]
	v_lshlrev_b32_e32 v66, 16, v139
	v_and_b32_e32 v67, 0xffff0000, v139
	v_pk_fma_f32 v[42:43], v[66:67], v[66:67], v[42:43]
	v_lshlrev_b32_e32 v60, 16, v140
	v_and_b32_e32 v61, 0xffff0000, v140
	v_pk_fma_f32 v[42:43], v[60:61], v[60:61], v[42:43]
	v_lshlrev_b32_e32 v62, 16, v141
	v_and_b32_e32 v63, 0xffff0000, v141
	v_pk_fma_f32 v[42:43], v[62:63], v[62:63], v[42:43]
	v_lshlrev_b32_e32 v64, 16, v142
	v_and_b32_e32 v65, 0xffff0000, v142
	v_pk_fma_f32 v[42:43], v[64:65], v[64:65], v[42:43]
	v_lshlrev_b32_e32 v66, 16, v143
	v_and_b32_e32 v67, 0xffff0000, v143
	v_pk_fma_f32 v[42:43], v[66:67], v[66:67], v[42:43]
	v_lshlrev_b32_e32 v60, 16, v144
	v_and_b32_e32 v61, 0xffff0000, v144
	v_pk_fma_f32 v[42:43], v[60:61], v[60:61], v[42:43]
	v_lshlrev_b32_e32 v62, 16, v145
	v_and_b32_e32 v63, 0xffff0000, v145
	v_pk_fma_f32 v[42:43], v[62:63], v[62:63], v[42:43]
	v_lshlrev_b32_e32 v64, 16, v146
	v_and_b32_e32 v65, 0xffff0000, v146
	v_pk_fma_f32 v[42:43], v[64:65], v[64:65], v[42:43]
	v_lshlrev_b32_e32 v66, 16, v147
	v_and_b32_e32 v67, 0xffff0000, v147
	v_pk_fma_f32 v[42:43], v[66:67], v[66:67], v[42:43]
	v_add_f32_e32 v42, v42, v43
	s_nop 1
	v_add_f32_dpp v42, v42, v42 quad_perm:[1,0,3,2] row_mask:0xf bank_mask:0xf
	s_nop 1
	v_add_f32_dpp v42, v42, v42 quad_perm:[2,3,0,1] row_mask:0xf bank_mask:0xf
	s_nop 1
	v_add_f32_dpp v42, v42, v42 row_half_mirror row_mask:0xf bank_mask:0xf
	s_nop 1
	v_add_f32_dpp v42, v42, v42 row_mirror row_mask:0xf bank_mask:0xf
	s_nop 1
	v_add_f32_dpp v42, v42, v42 row_bcast:15 row_mask:0xa bank_mask:0xf
	s_nop 1
	v_add_f32_dpp v42, v42, v42 row_bcast:31 row_mask:0xc bank_mask:0xf
	s_nop 1
	v_readlane_b32 s100, v42, 63
	s_nop 3
	v_mov_b32_e32 v44, s100
	v_fma_f32 v44, v44, v47, v224
	v_rsq_f32_e32 v45, v44
	s_nop 0
	v_mul_f32_e32 v46, v44, v45
	v_mul_f32_e32 v46, v46, v45
	v_fmaak_f32 v46, -0.5, v46, 0x3fc00000
	v_mul_f32_e32 v44, v45, v46
	v_mov_b32_e32 v45, v44
	v_lshlrev_b32_e32 v60, 16, v132
	v_and_b32_e32 v61, 0xffff0000, v132
	v_pk_mul_f32 v[60:61], v[60:61], v[44:45]
	v_pk_fma_f32 v[60:61], v[60:61], v[2:3], v[164:165]
	v_cvt_pk_bf16_f32 v132, v60, v61
	v_lshlrev_b32_e32 v62, 16, v133
	v_and_b32_e32 v63, 0xffff0000, v133
	v_pk_mul_f32 v[62:63], v[62:63], v[44:45]
	v_pk_fma_f32 v[62:63], v[62:63], v[4:5], v[166:167]
	v_cvt_pk_bf16_f32 v133, v62, v63
	v_lshlrev_b32_e32 v64, 16, v134
	v_and_b32_e32 v65, 0xffff0000, v134
	v_pk_mul_f32 v[64:65], v[64:65], v[44:45]
	v_pk_fma_f32 v[64:65], v[64:65], v[6:7], v[168:169]
	v_cvt_pk_bf16_f32 v134, v64, v65
	v_lshlrev_b32_e32 v66, 16, v135
	v_and_b32_e32 v67, 0xffff0000, v135
	v_pk_mul_f32 v[66:67], v[66:67], v[44:45]
	v_pk_fma_f32 v[66:67], v[66:67], v[8:9], v[170:171]
	v_cvt_pk_bf16_f32 v135, v66, v67
	v_lshlrev_b32_e32 v60, 16, v136
	v_and_b32_e32 v61, 0xffff0000, v136
	v_pk_mul_f32 v[60:61], v[60:61], v[44:45]
	v_pk_fma_f32 v[60:61], v[60:61], v[10:11], v[172:173]
	v_cvt_pk_bf16_f32 v136, v60, v61
	v_lshlrev_b32_e32 v62, 16, v137
	v_and_b32_e32 v63, 0xffff0000, v137
	v_pk_mul_f32 v[62:63], v[62:63], v[44:45]
	v_pk_fma_f32 v[62:63], v[62:63], v[12:13], v[174:175]
	v_cvt_pk_bf16_f32 v137, v62, v63
	v_lshlrev_b32_e32 v64, 16, v138
	v_and_b32_e32 v65, 0xffff0000, v138
	v_pk_mul_f32 v[64:65], v[64:65], v[44:45]
	v_pk_fma_f32 v[64:65], v[64:65], v[14:15], v[176:177]
	v_cvt_pk_bf16_f32 v138, v64, v65
	v_lshlrev_b32_e32 v66, 16, v139
	v_and_b32_e32 v67, 0xffff0000, v139
	v_pk_mul_f32 v[66:67], v[66:67], v[44:45]
	v_pk_fma_f32 v[66:67], v[66:67], v[16:17], v[178:179]
	v_cvt_pk_bf16_f32 v139, v66, v67
	v_lshlrev_b32_e32 v60, 16, v140
	v_and_b32_e32 v61, 0xffff0000, v140
	v_pk_mul_f32 v[60:61], v[60:61], v[44:45]
	v_pk_fma_f32 v[60:61], v[60:61], v[18:19], v[180:181]
	v_cvt_pk_bf16_f32 v140, v60, v61
	v_lshlrev_b32_e32 v62, 16, v141
	v_and_b32_e32 v63, 0xffff0000, v141
	v_pk_mul_f32 v[62:63], v[62:63], v[44:45]
	v_pk_fma_f32 v[62:63], v[62:63], v[20:21], v[182:183]
	v_cvt_pk_bf16_f32 v141, v62, v63
	v_lshlrev_b32_e32 v64, 16, v142
	v_and_b32_e32 v65, 0xffff0000, v142
	v_pk_mul_f32 v[64:65], v[64:65], v[44:45]
	v_pk_fma_f32 v[64:65], v[64:65], v[22:23], v[184:185]
	v_cvt_pk_bf16_f32 v142, v64, v65
	v_lshlrev_b32_e32 v66, 16, v143
	v_and_b32_e32 v67, 0xffff0000, v143
	v_pk_mul_f32 v[66:67], v[66:67], v[44:45]
	v_pk_fma_f32 v[66:67], v[66:67], v[24:25], v[186:187]
	v_cvt_pk_bf16_f32 v143, v66, v67
	v_lshlrev_b32_e32 v60, 16, v144
	v_and_b32_e32 v61, 0xffff0000, v144
	v_pk_mul_f32 v[60:61], v[60:61], v[44:45]
	v_pk_fma_f32 v[60:61], v[60:61], v[26:27], v[188:189]
	v_cvt_pk_bf16_f32 v144, v60, v61
	v_lshlrev_b32_e32 v62, 16, v145
	v_and_b32_e32 v63, 0xffff0000, v145
	v_pk_mul_f32 v[62:63], v[62:63], v[44:45]
	v_pk_fma_f32 v[62:63], v[62:63], v[28:29], v[190:191]
	v_cvt_pk_bf16_f32 v145, v62, v63
	v_lshlrev_b32_e32 v64, 16, v146
	v_and_b32_e32 v65, 0xffff0000, v146
	v_pk_mul_f32 v[64:65], v[64:65], v[44:45]
	v_pk_fma_f32 v[64:65], v[64:65], v[30:31], v[192:193]
	v_cvt_pk_bf16_f32 v146, v64, v65
	v_lshlrev_b32_e32 v66, 16, v147
	v_and_b32_e32 v67, 0xffff0000, v147
	v_pk_mul_f32 v[66:67], v[66:67], v[44:45]
	v_pk_fma_f32 v[66:67], v[66:67], v[32:33], v[194:195]
	v_cvt_pk_bf16_f32 v147, v66, v67
	global_store_dwordx4 v39, v[132:135], s[20:21]
	global_store_dwordx4 v39, v[136:139], s[20:21] offset:1024
	global_store_dwordx4 v39, v[140:143], s[20:21] offset:2048
	global_store_dwordx4 v39, v[144:147], s[20:21] offset:3072
	s_add_u32 s20, s20, 0x1000
	s_addc_u32 s21, s21, 0
	s_waitcnt vmcnt(12)
	v_lshlrev_b32_e32 v60, 16, v148
	v_and_b32_e32 v61, 0xffff0000, v148
	v_pk_mul_f32 v[42:43], v[60:61], v[60:61]
	v_lshlrev_b32_e32 v62, 16, v149
	v_and_b32_e32 v63, 0xffff0000, v149
	v_pk_fma_f32 v[42:43], v[62:63], v[62:63], v[42:43]
	v_lshlrev_b32_e32 v64, 16, v150
	v_and_b32_e32 v65, 0xffff0000, v150
	v_pk_fma_f32 v[42:43], v[64:65], v[64:65], v[42:43]
	v_lshlrev_b32_e32 v66, 16, v151
	v_and_b32_e32 v67, 0xffff0000, v151
	v_pk_fma_f32 v[42:43], v[66:67], v[66:67], v[42:43]
	v_lshlrev_b32_e32 v60, 16, v152
	v_and_b32_e32 v61, 0xffff0000, v152
	v_pk_fma_f32 v[42:43], v[60:61], v[60:61], v[42:43]
	v_lshlrev_b32_e32 v62, 16, v153
	v_and_b32_e32 v63, 0xffff0000, v153
	v_pk_fma_f32 v[42:43], v[62:63], v[62:63], v[42:43]
	v_lshlrev_b32_e32 v64, 16, v154
	v_and_b32_e32 v65, 0xffff0000, v154
	v_pk_fma_f32 v[42:43], v[64:65], v[64:65], v[42:43]
	v_lshlrev_b32_e32 v66, 16, v155
	v_and_b32_e32 v67, 0xffff0000, v155
	v_pk_fma_f32 v[42:43], v[66:67], v[66:67], v[42:43]
	v_lshlrev_b32_e32 v60, 16, v156
	v_and_b32_e32 v61, 0xffff0000, v156
	v_pk_fma_f32 v[42:43], v[60:61], v[60:61], v[42:43]
	v_lshlrev_b32_e32 v62, 16, v157
	v_and_b32_e32 v63, 0xffff0000, v157
	v_pk_fma_f32 v[42:43], v[62:63], v[62:63], v[42:43]
	v_lshlrev_b32_e32 v64, 16, v158
	v_and_b32_e32 v65, 0xffff0000, v158
	v_pk_fma_f32 v[42:43], v[64:65], v[64:65], v[42:43]
	v_lshlrev_b32_e32 v66, 16, v159
	v_and_b32_e32 v67, 0xffff0000, v159
	v_pk_fma_f32 v[42:43], v[66:67], v[66:67], v[42:43]
	v_lshlrev_b32_e32 v60, 16, v160
	v_and_b32_e32 v61, 0xffff0000, v160
	v_pk_fma_f32 v[42:43], v[60:61], v[60:61], v[42:43]
	v_lshlrev_b32_e32 v62, 16, v161
	v_and_b32_e32 v63, 0xffff0000, v161
	v_pk_fma_f32 v[42:43], v[62:63], v[62:63], v[42:43]
	v_lshlrev_b32_e32 v64, 16, v162
	v_and_b32_e32 v65, 0xffff0000, v162
	v_pk_fma_f32 v[42:43], v[64:65], v[64:65], v[42:43]
	v_lshlrev_b32_e32 v66, 16, v163
	v_and_b32_e32 v67, 0xffff0000, v163
	v_pk_fma_f32 v[42:43], v[66:67], v[66:67], v[42:43]
	v_add_f32_e32 v42, v42, v43
	s_nop 1
	v_add_f32_dpp v42, v42, v42 quad_perm:[1,0,3,2] row_mask:0xf bank_mask:0xf
	s_nop 1
	v_add_f32_dpp v42, v42, v42 quad_perm:[2,3,0,1] row_mask:0xf bank_mask:0xf
	s_nop 1
	v_add_f32_dpp v42, v42, v42 row_half_mirror row_mask:0xf bank_mask:0xf
	s_nop 1
	v_add_f32_dpp v42, v42, v42 row_mirror row_mask:0xf bank_mask:0xf
	s_nop 1
	v_add_f32_dpp v42, v42, v42 row_bcast:15 row_mask:0xa bank_mask:0xf
	s_nop 1
	v_add_f32_dpp v42, v42, v42 row_bcast:31 row_mask:0xc bank_mask:0xf
	s_nop 1
	v_readlane_b32 s100, v42, 63
	s_nop 3
	v_mov_b32_e32 v44, s100
	v_fma_f32 v44, v44, v47, v224
	v_rsq_f32_e32 v45, v44
	s_nop 0
	v_mul_f32_e32 v46, v44, v45
	v_mul_f32_e32 v46, v46, v45
	v_fmaak_f32 v46, -0.5, v46, 0x3fc00000
	v_mul_f32_e32 v44, v45, v46
	v_mov_b32_e32 v45, v44
	v_lshlrev_b32_e32 v60, 16, v148
	v_and_b32_e32 v61, 0xffff0000, v148
	v_pk_mul_f32 v[60:61], v[60:61], v[44:45]
	v_pk_fma_f32 v[60:61], v[60:61], v[2:3], v[164:165]
	v_cvt_pk_bf16_f32 v148, v60, v61
	v_lshlrev_b32_e32 v62, 16, v149
	v_and_b32_e32 v63, 0xffff0000, v149
	v_pk_mul_f32 v[62:63], v[62:63], v[44:45]
	v_pk_fma_f32 v[62:63], v[62:63], v[4:5], v[166:167]
	v_cvt_pk_bf16_f32 v149, v62, v63
	v_lshlrev_b32_e32 v64, 16, v150
	v_and_b32_e32 v65, 0xffff0000, v150
	v_pk_mul_f32 v[64:65], v[64:65], v[44:45]
	v_pk_fma_f32 v[64:65], v[64:65], v[6:7], v[168:169]
	v_cvt_pk_bf16_f32 v150, v64, v65
	v_lshlrev_b32_e32 v66, 16, v151
	v_and_b32_e32 v67, 0xffff0000, v151
	v_pk_mul_f32 v[66:67], v[66:67], v[44:45]
	v_pk_fma_f32 v[66:67], v[66:67], v[8:9], v[170:171]
	v_cvt_pk_bf16_f32 v151, v66, v67
	v_lshlrev_b32_e32 v60, 16, v152
	v_and_b32_e32 v61, 0xffff0000, v152
	v_pk_mul_f32 v[60:61], v[60:61], v[44:45]
	v_pk_fma_f32 v[60:61], v[60:61], v[10:11], v[172:173]
	v_cvt_pk_bf16_f32 v152, v60, v61
	v_lshlrev_b32_e32 v62, 16, v153
	v_and_b32_e32 v63, 0xffff0000, v153
	v_pk_mul_f32 v[62:63], v[62:63], v[44:45]
	v_pk_fma_f32 v[62:63], v[62:63], v[12:13], v[174:175]
	v_cvt_pk_bf16_f32 v153, v62, v63
	v_lshlrev_b32_e32 v64, 16, v154
	v_and_b32_e32 v65, 0xffff0000, v154
	v_pk_mul_f32 v[64:65], v[64:65], v[44:45]
	v_pk_fma_f32 v[64:65], v[64:65], v[14:15], v[176:177]
	v_cvt_pk_bf16_f32 v154, v64, v65
	v_lshlrev_b32_e32 v66, 16, v155
	v_and_b32_e32 v67, 0xffff0000, v155
	v_pk_mul_f32 v[66:67], v[66:67], v[44:45]
	v_pk_fma_f32 v[66:67], v[66:67], v[16:17], v[178:179]
	v_cvt_pk_bf16_f32 v155, v66, v67
	v_lshlrev_b32_e32 v60, 16, v156
	v_and_b32_e32 v61, 0xffff0000, v156
	v_pk_mul_f32 v[60:61], v[60:61], v[44:45]
	v_pk_fma_f32 v[60:61], v[60:61], v[18:19], v[180:181]
	v_cvt_pk_bf16_f32 v156, v60, v61
	v_lshlrev_b32_e32 v62, 16, v157
	v_and_b32_e32 v63, 0xffff0000, v157
	v_pk_mul_f32 v[62:63], v[62:63], v[44:45]
	v_pk_fma_f32 v[62:63], v[62:63], v[20:21], v[182:183]
	v_cvt_pk_bf16_f32 v157, v62, v63
	v_lshlrev_b32_e32 v64, 16, v158
	v_and_b32_e32 v65, 0xffff0000, v158
	v_pk_mul_f32 v[64:65], v[64:65], v[44:45]
	v_pk_fma_f32 v[64:65], v[64:65], v[22:23], v[184:185]
	v_cvt_pk_bf16_f32 v158, v64, v65
	v_lshlrev_b32_e32 v66, 16, v159
	v_and_b32_e32 v67, 0xffff0000, v159
	v_pk_mul_f32 v[66:67], v[66:67], v[44:45]
	v_pk_fma_f32 v[66:67], v[66:67], v[24:25], v[186:187]
	v_cvt_pk_bf16_f32 v159, v66, v67
	v_lshlrev_b32_e32 v60, 16, v160
	v_and_b32_e32 v61, 0xffff0000, v160
	v_pk_mul_f32 v[60:61], v[60:61], v[44:45]
	v_pk_fma_f32 v[60:61], v[60:61], v[26:27], v[188:189]
	v_cvt_pk_bf16_f32 v160, v60, v61
	v_lshlrev_b32_e32 v62, 16, v161
	v_and_b32_e32 v63, 0xffff0000, v161
	v_pk_mul_f32 v[62:63], v[62:63], v[44:45]
	v_pk_fma_f32 v[62:63], v[62:63], v[28:29], v[190:191]
	v_cvt_pk_bf16_f32 v161, v62, v63
	v_lshlrev_b32_e32 v64, 16, v162
	v_and_b32_e32 v65, 0xffff0000, v162
	v_pk_mul_f32 v[64:65], v[64:65], v[44:45]
	v_pk_fma_f32 v[64:65], v[64:65], v[30:31], v[192:193]
	v_cvt_pk_bf16_f32 v162, v64, v65
	v_lshlrev_b32_e32 v66, 16, v163
	v_and_b32_e32 v67, 0xffff0000, v163
	v_pk_mul_f32 v[66:67], v[66:67], v[44:45]
	v_pk_fma_f32 v[66:67], v[66:67], v[32:33], v[194:195]
	v_cvt_pk_bf16_f32 v163, v66, v67
	global_store_dwordx4 v39, v[148:151], s[20:21]
	global_store_dwordx4 v39, v[152:155], s[20:21] offset:1024
	global_store_dwordx4 v39, v[156:159], s[20:21] offset:2048
	global_store_dwordx4 v39, v[160:163], s[20:21] offset:3072
	s_add_u32 s20, s20, 0x1000
	s_addc_u32 s21, s21, 0
	s_cmpk_gt_u32 s7, 0x3ff
	s_cbranch_scc1 .Lnf1_ctxdone
	s_load_dwordx2 s[40:41], s[4:5], 0xb8
	s_lshl_b32 s10, s7, 12
	s_lshl_b32 s48, s7, 13
	s_waitcnt lgkmcnt(0)
	s_add_u32 s10, s40, s10
	s_addc_u32 s11, s41, 0
	s_add_u32 s10, s10, 0x1d624000
	s_addc_u32 s11, s11, 0
	s_add_u32 s20, s10, 0x4400000
	s_addc_u32 s21, s11, 0
	s_add_u32 s48, s40, s48
	s_addc_u32 s49, s41, 0
	s_add_u32 s48, s48, 0x3bce8000
	s_addc_u32 s49, s49, 0
	s_add_u32 s40, s8, 0x8000
	s_addc_u32 s41, s9, 0
	global_load_dwordx4 v[208:211], v39, s[10:11]
	global_load_dwordx4 v[212:215], v39, s[10:11] offset:1024
	global_load_dwordx4 v[216:219], v39, s[10:11] offset:2048
	global_load_dwordx4 v[220:223], v39, s[10:11] offset:3072
	global_load_dwordx4 v[132:135], v40, s[48:49]
	global_load_dwordx4 v[136:139], v40, s[48:49] offset:16
	global_load_dwordx4 v[140:143], v40, s[48:49] offset:2048
	global_load_dwordx4 v[144:147], v40, s[48:49] offset:2064
	s_add_u32 s48, s48, 0x1000
	s_addc_u32 s49, s49, 0
	global_load_dwordx4 v[148:151], v40, s[48:49]
	global_load_dwordx4 v[152:155], v40, s[48:49] offset:16
	global_load_dwordx4 v[156:159], v40, s[48:49] offset:2048
	global_load_dwordx4 v[160:163], v40, s[48:49] offset:2064
	s_add_u32 s48, s48, 0x7ff000
	s_addc_u32 s49, s49, 0
	global_load_dwordx4 v[60:63], v40, s[48:49]
	global_load_dwordx4 v[64:67], v40, s[48:49] offset:16
	global_load_dwordx4 v[68:71], v40, s[48:49] offset:2048
	global_load_dwordx4 v[72:75], v40, s[48:49] offset:2064
	s_add_u32 s48, s48, 0x1000
	s_addc_u32 s49, s49, 0
	global_load_dwordx4 v[76:79], v40, s[48:49]
	global_load_dwordx4 v[80:83], v40, s[48:49] offset:16
	global_load_dwordx4 v[84:87], v40, s[48:49] offset:2048
	global_load_dwordx4 v[88:91], v40, s[48:49] offset:2064
	s_add_u32 s48, s48, 0x7ff000
	s_addc_u32 s49, s49, 0
	global_load_dwordx4 v[2:5], v40, s[40:41]
	global_load_dwordx4 v[6:9], v40, s[40:41] offset:16
	global_load_dwordx4 v[10:13], v40, s[40:41] offset:2048
	global_load_dwordx4 v[14:17], v40, s[40:41] offset:2064
	s_add_u32 s40, s40, 0x1000
	s_addc_u32 s41, s41, 0
	global_load_dwordx4 v[18:21], v40, s[40:41]
	global_load_dwordx4 v[22:25], v40, s[40:41] offset:16
	global_load_dwordx4 v[26:29], v40, s[40:41] offset:2048
	global_load_dwordx4 v[30:33], v40, s[40:41] offset:2064
	s_add_u32 s40, s54, 0x30000
	s_addc_u32 s41, s55, 0
	global_load_dwordx4 v[164:167], v40, s[40:41]
	global_load_dwordx4 v[168:171], v40, s[40:41] offset:16
	global_load_dwordx4 v[172:175], v40, s[40:41] offset:2048
	global_load_dwordx4 v[176:179], v40, s[40:41] offset:2064
	s_add_u32 s40, s40, 0x1000
	s_addc_u32 s41, s41, 0
	global_load_dwordx4 v[180:183], v40, s[40:41]
	global_load_dwordx4 v[184:187], v40, s[40:41] offset:16
	global_load_dwordx4 v[188:191], v40, s[40:41] offset:2048
	global_load_dwordx4 v[192:195], v40, s[40:41] offset:2064
	s_waitcnt vmcnt(32)
	v_lshlrev_b32_e32 v100, 16, v208
	v_and_b32_e32 v101, 0xffff0000, v208
	v_lshlrev_b32_e32 v102, 16, v209
	v_and_b32_e32 v103, 0xffff0000, v209
	v_lshlrev_b32_e32 v104, 16, v210
	v_and_b32_e32 v105, 0xffff0000, v210
	v_lshlrev_b32_e32 v106, 16, v211
	v_and_b32_e32 v107, 0xffff0000, v211
	v_lshlrev_b32_e32 v108, 16, v212
	v_and_b32_e32 v109, 0xffff0000, v212
	v_lshlrev_b32_e32 v110, 16, v213
	v_and_b32_e32 v111, 0xffff0000, v213
	v_lshlrev_b32_e32 v112, 16, v214
	v_and_b32_e32 v113, 0xffff0000, v214
	v_lshlrev_b32_e32 v114, 16, v215
	v_and_b32_e32 v115, 0xffff0000, v215
	v_lshlrev_b32_e32 v116, 16, v216
	v_and_b32_e32 v117, 0xffff0000, v216
	v_lshlrev_b32_e32 v118, 16, v217
	v_and_b32_e32 v119, 0xffff0000, v217
	v_lshlrev_b32_e32 v120, 16, v218
	v_and_b32_e32 v121, 0xffff0000, v218
	v_lshlrev_b32_e32 v122, 16, v219
	v_and_b32_e32 v123, 0xffff0000, v219
	v_lshlrev_b32_e32 v124, 16, v220
	v_and_b32_e32 v125, 0xffff0000, v220
	v_lshlrev_b32_e32 v126, 16, v221
	v_and_b32_e32 v127, 0xffff0000, v221
	v_lshlrev_b32_e32 v128, 16, v222
	v_and_b32_e32 v129, 0xffff0000, v222
	v_lshlrev_b32_e32 v130, 16, v223
	v_and_b32_e32 v131, 0xffff0000, v223
	s_waitcnt vmcnt(24)
	v_pk_add_f32 v[100:101], v[100:101], v[132:133]
	v_pk_add_f32 v[102:103], v[102:103], v[134:135]
	v_pk_add_f32 v[104:105], v[104:105], v[136:137]
	v_pk_add_f32 v[106:107], v[106:107], v[138:139]
	v_pk_add_f32 v[108:109], v[108:109], v[140:141]
	v_pk_add_f32 v[110:111], v[110:111], v[142:143]
	v_pk_add_f32 v[112:113], v[112:113], v[144:145]
	v_pk_add_f32 v[114:115], v[114:115], v[146:147]
	v_pk_add_f32 v[116:117], v[116:117], v[148:149]
	v_pk_add_f32 v[118:119], v[118:119], v[150:151]
	v_pk_add_f32 v[120:121], v[120:121], v[152:153]
	v_pk_add_f32 v[122:123], v[122:123], v[154:155]
	v_pk_add_f32 v[124:125], v[124:125], v[156:157]
	v_pk_add_f32 v[126:127], v[126:127], v[158:159]
	v_pk_add_f32 v[128:129], v[128:129], v[160:161]
	v_pk_add_f32 v[130:131], v[130:131], v[162:163]
	global_load_dwordx4 v[132:135], v40, s[48:49]
	global_load_dwordx4 v[136:139], v40, s[48:49] offset:16
	global_load_dwordx4 v[140:143], v40, s[48:49] offset:2048
	global_load_dwordx4 v[144:147], v40, s[48:49] offset:2064
	s_add_u32 s48, s48, 0x1000
	s_addc_u32 s49, s49, 0
	global_load_dwordx4 v[148:151], v40, s[48:49]
	global_load_dwordx4 v[152:155], v40, s[48:49] offset:16
	global_load_dwordx4 v[156:159], v40, s[48:49] offset:2048
	global_load_dwordx4 v[160:163], v40, s[48:49] offset:2064
	s_add_u32 s48, s48, 0x7ff000
	s_addc_u32 s49, s49, 0
	s_waitcnt vmcnt(24)
	v_pk_add_f32 v[100:101], v[100:101], v[60:61]
	v_pk_add_f32 v[102:103], v[102:103], v[62:63]
	v_pk_add_f32 v[104:105], v[104:105], v[64:65]
	v_pk_add_f32 v[106:107], v[106:107], v[66:67]
	v_pk_add_f32 v[108:109], v[108:109], v[68:69]
	v_pk_add_f32 v[110:111], v[110:111], v[70:71]
	v_pk_add_f32 v[112:113], v[112:113], v[72:73]
	v_pk_add_f32 v[114:115], v[114:115], v[74:75]
	v_pk_add_f32 v[116:117], v[116:117], v[76:77]
	v_pk_add_f32 v[118:119], v[118:119], v[78:79]
	v_pk_add_f32 v[120:121], v[120:121], v[80:81]
	v_pk_add_f32 v[122:123], v[122:123], v[82:83]
	v_pk_add_f32 v[124:125], v[124:125], v[84:85]
	v_pk_add_f32 v[126:127], v[126:127], v[86:87]
	v_pk_add_f32 v[128:129], v[128:129], v[88:89]
	v_pk_add_f32 v[130:131], v[130:131], v[90:91]
	global_load_dwordx4 v[60:63], v40, s[48:49]
	global_load_dwordx4 v[64:67], v40, s[48:49] offset:16
	global_load_dwordx4 v[68:71], v40, s[48:49] offset:2048
	global_load_dwordx4 v[72:75], v40, s[48:49] offset:2064
	s_add_u32 s48, s48, 0x1000
	s_addc_u32 s49, s49, 0
	global_load_dwordx4 v[76:79], v40, s[48:49]
	global_load_dwordx4 v[80:83], v40, s[48:49] offset:16
	global_load_dwordx4 v[84:87], v40, s[48:49] offset:2048
	global_load_dwordx4 v[88:91], v40, s[48:49] offset:2064
	s_waitcnt vmcnt(8)
	v_pk_add_f32 v[100:101], v[100:101], v[132:133]
	v_pk_add_f32 v[102:103], v[102:103], v[134:135]
	v_pk_add_f32 v[104:105], v[104:105], v[136:137]
	v_pk_add_f32 v[106:107], v[106:107], v[138:139]
	v_pk_add_f32 v[108:109], v[108:109], v[140:141]
	v_pk_add_f32 v[110:111], v[110:111], v[142:143]
	v_pk_add_f32 v[112:113], v[112:113], v[144:145]
	v_pk_add_f32 v[114:115], v[114:115], v[146:147]
	v_pk_add_f32 v[116:117], v[116:117], v[148:149]
	v_pk_add_f32 v[118:119], v[118:119], v[150:151]
	v_pk_add_f32 v[120:121], v[120:121], v[152:153]
	v_pk_add_f32 v[122:123], v[122:123], v[154:155]
	v_pk_add_f32 v[124:125], v[124:125], v[156:157]
	v_pk_add_f32 v[126:127], v[126:127], v[158:159]
	v_pk_add_f32 v[128:129], v[128:129], v[160:161]
	v_pk_add_f32 v[130:131], v[130:131], v[162:163]
	s_waitcnt vmcnt(0)
	v_pk_add_f32 v[100:101], v[100:101], v[60:61]
	v_pk_add_f32 v[102:103], v[102:103], v[62:63]
	v_pk_add_f32 v[104:105], v[104:105], v[64:65]
	v_pk_add_f32 v[106:107], v[106:107], v[66:67]
	v_pk_add_f32 v[108:109], v[108:109], v[68:69]
	v_pk_add_f32 v[110:111], v[110:111], v[70:71]
	v_pk_add_f32 v[112:113], v[112:113], v[72:73]
	v_pk_add_f32 v[114:115], v[114:115], v[74:75]
	v_pk_add_f32 v[116:117], v[116:117], v[76:77]
	v_pk_add_f32 v[118:119], v[118:119], v[78:79]
	v_pk_add_f32 v[120:121], v[120:121], v[80:81]
	v_pk_add_f32 v[122:123], v[122:123], v[82:83]
	v_pk_add_f32 v[124:125], v[124:125], v[84:85]
	v_pk_add_f32 v[126:127], v[126:127], v[86:87]
	v_pk_add_f32 v[128:129], v[128:129], v[88:89]
	v_pk_add_f32 v[130:131], v[130:131], v[90:91]
	v_cvt_pk_bf16_f32 v208, v100, v101
	v_cvt_pk_bf16_f32 v209, v102, v103
	v_cvt_pk_bf16_f32 v210, v104, v105
	v_cvt_pk_bf16_f32 v211, v106, v107
	v_cvt_pk_bf16_f32 v212, v108, v109
	v_cvt_pk_bf16_f32 v213, v110, v111
	v_cvt_pk_bf16_f32 v214, v112, v113
	v_cvt_pk_bf16_f32 v215, v114, v115
	v_cvt_pk_bf16_f32 v216, v116, v117
	v_cvt_pk_bf16_f32 v217, v118, v119
	v_cvt_pk_bf16_f32 v218, v120, v121
	v_cvt_pk_bf16_f32 v219, v122, v123
	v_cvt_pk_bf16_f32 v220, v124, v125
	v_cvt_pk_bf16_f32 v221, v126, v127
	v_cvt_pk_bf16_f32 v222, v128, v129
	v_cvt_pk_bf16_f32 v223, v130, v131
	global_store_dwordx4 v39, v[208:211], s[10:11]
	global_store_dwordx4 v39, v[212:215], s[10:11] offset:1024
	global_store_dwordx4 v39, v[216:219], s[10:11] offset:2048
	global_store_dwordx4 v39, v[220:223], s[10:11] offset:3072
	v_pk_mul_f32 v[42:43], v[100:101], v[100:101]
	v_pk_fma_f32 v[42:43], v[102:103], v[102:103], v[42:43]
	v_pk_fma_f32 v[42:43], v[104:105], v[104:105], v[42:43]
	v_pk_fma_f32 v[42:43], v[106:107], v[106:107], v[42:43]
	v_pk_fma_f32 v[42:43], v[108:109], v[108:109], v[42:43]
	v_pk_fma_f32 v[42:43], v[110:111], v[110:111], v[42:43]
	v_pk_fma_f32 v[42:43], v[112:113], v[112:113], v[42:43]
	v_pk_fma_f32 v[42:43], v[114:115], v[114:115], v[42:43]
	v_pk_fma_f32 v[42:43], v[116:117], v[116:117], v[42:43]
	v_pk_fma_f32 v[42:43], v[118:119], v[118:119], v[42:43]
	v_pk_fma_f32 v[42:43], v[120:121], v[120:121], v[42:43]
	v_pk_fma_f32 v[42:43], v[122:123], v[122:123], v[42:43]
	v_pk_fma_f32 v[42:43], v[124:125], v[124:125], v[42:43]
	v_pk_fma_f32 v[42:43], v[126:127], v[126:127], v[42:43]
	v_pk_fma_f32 v[42:43], v[128:129], v[128:129], v[42:43]
	v_pk_fma_f32 v[42:43], v[130:131], v[130:131], v[42:43]
	v_add_f32_e32 v42, v42, v43
	s_nop 1
	v_add_f32_dpp v42, v42, v42 quad_perm:[1,0,3,2] row_mask:0xf bank_mask:0xf
	s_nop 1
	v_add_f32_dpp v42, v42, v42 quad_perm:[2,3,0,1] row_mask:0xf bank_mask:0xf
	s_nop 1
	v_add_f32_dpp v42, v42, v42 row_half_mirror row_mask:0xf bank_mask:0xf
	s_nop 1
	v_add_f32_dpp v42, v42, v42 row_mirror row_mask:0xf bank_mask:0xf
	s_nop 1
	v_add_f32_dpp v42, v42, v42 row_bcast:15 row_mask:0xa bank_mask:0xf
	s_nop 1
	v_add_f32_dpp v42, v42, v42 row_bcast:31 row_mask:0xc bank_mask:0xf
	s_nop 1
	v_readlane_b32 s100, v42, 63
	s_nop 3
	v_mov_b32_e32 v44, s100
	v_fma_f32 v44, v44, v47, v224
	v_rsq_f32_e32 v45, v44
	s_nop 0
	v_mul_f32_e32 v46, v44, v45
	v_mul_f32_e32 v46, v46, v45
	v_fmaak_f32 v46, -0.5, v46, 0x3fc00000
	v_mul_f32_e32 v44, v45, v46
	v_mov_b32_e32 v45, v44
	v_pk_mul_f32 v[92:93], v[100:101], v[44:45]
	v_pk_fma_f32 v[92:93], v[92:93], v[2:3], v[164:165]
	v_cvt_pk_bf16_f32 v132, v92, v93
	v_pk_mul_f32 v[94:95], v[102:103], v[44:45]
	v_pk_fma_f32 v[94:95], v[94:95], v[4:5], v[166:167]
	v_cvt_pk_bf16_f32 v133, v94, v95
	v_pk_mul_f32 v[96:97], v[104:105], v[44:45]
	v_pk_fma_f32 v[96:97], v[96:97], v[6:7], v[168:169]
	v_cvt_pk_bf16_f32 v134, v96, v97
	v_pk_mul_f32 v[92:93], v[106:107], v[44:45]
	v_pk_fma_f32 v[92:93], v[92:93], v[8:9], v[170:171]
	v_cvt_pk_bf16_f32 v135, v92, v93
	v_pk_mul_f32 v[94:95], v[108:109], v[44:45]
	v_pk_fma_f32 v[94:95], v[94:95], v[10:11], v[172:173]
	v_cvt_pk_bf16_f32 v136, v94, v95
	v_pk_mul_f32 v[96:97], v[110:111], v[44:45]
	v_pk_fma_f32 v[96:97], v[96:97], v[12:13], v[174:175]
	v_cvt_pk_bf16_f32 v137, v96, v97
	v_pk_mul_f32 v[92:93], v[112:113], v[44:45]
	v_pk_fma_f32 v[92:93], v[92:93], v[14:15], v[176:177]
	v_cvt_pk_bf16_f32 v138, v92, v93
	v_pk_mul_f32 v[94:95], v[114:115], v[44:45]
	v_pk_fma_f32 v[94:95], v[94:95], v[16:17], v[178:179]
	v_cvt_pk_bf16_f32 v139, v94, v95
	v_pk_mul_f32 v[96:97], v[116:117], v[44:45]
	v_pk_fma_f32 v[96:97], v[96:97], v[18:19], v[180:181]
	v_cvt_pk_bf16_f32 v140, v96, v97
	v_pk_mul_f32 v[92:93], v[118:119], v[44:45]
	v_pk_fma_f32 v[92:93], v[92:93], v[20:21], v[182:183]
	v_cvt_pk_bf16_f32 v141, v92, v93
	v_pk_mul_f32 v[94:95], v[120:121], v[44:45]
	v_pk_fma_f32 v[94:95], v[94:95], v[22:23], v[184:185]
	v_cvt_pk_bf16_f32 v142, v94, v95
	v_pk_mul_f32 v[96:97], v[122:123], v[44:45]
	v_pk_fma_f32 v[96:97], v[96:97], v[24:25], v[186:187]
	v_cvt_pk_bf16_f32 v143, v96, v97
	v_pk_mul_f32 v[92:93], v[124:125], v[44:45]
	v_pk_fma_f32 v[92:93], v[92:93], v[26:27], v[188:189]
	v_cvt_pk_bf16_f32 v144, v92, v93
	v_pk_mul_f32 v[94:95], v[126:127], v[44:45]
	v_pk_fma_f32 v[94:95], v[94:95], v[28:29], v[190:191]
	v_cvt_pk_bf16_f32 v145, v94, v95
	v_pk_mul_f32 v[96:97], v[128:129], v[44:45]
	v_pk_fma_f32 v[96:97], v[96:97], v[30:31], v[192:193]
	v_cvt_pk_bf16_f32 v146, v96, v97
	v_pk_mul_f32 v[92:93], v[130:131], v[44:45]
	v_pk_fma_f32 v[92:93], v[92:93], v[32:33], v[194:195]
	v_cvt_pk_bf16_f32 v147, v92, v93
	global_store_dwordx4 v39, v[132:135], s[20:21]
	global_store_dwordx4 v39, v[136:139], s[20:21] offset:1024
	global_store_dwordx4 v39, v[140:143], s[20:21] offset:2048
	global_store_dwordx4 v39, v[144:147], s[20:21] offset:3072
.Lnf1_ctxdone:
	s_mov_b32 s101, 2

.LBB0_225:
	s_cmp_eq_u32 s101, 0
	s_cbranch_scc1 .Lnf1_orig
	s_cmp_eq_u32 s101, 2
	s_cbranch_scc1 .LBB0_235
	s_cmpk_lt_i32 s7, 0x4000
	s_cbranch_scc0 .Lnf1_orig
	s_add_i32 s7, s7, s36
	s_add_u32 s42, s42, s44
	s_addc_u32 s43, s43, s45
	v_lshl_add_u64 v[36:37], v[36:37], 0, s[38:39]
	s_cmpk_lt_i32 s7, 0x4400
	s_cbranch_scc1 .LBB0_225
	s_branch .LBB0_235

.LBB0_898:
	s_andn2_b64 vcc, exec, s[4:5]
	s_cbranch_vccnz .LBB0_962
	v_readlane_b32 s8, v253, 2
	s_mov_b64 s[4:5], s[96:97]
	s_mov_b64 s[36:37], s[96:97]
	s_mov_b64 s[20:21], s[96:97]
	v_mov_b32_e32 v2, v0
	v_readlane_b32 s9, v253, 3
	s_load_dword s6, s[8:9], 0x0
	v_readfirstlane_b32 s7, v2
	s_ashr_i32 s10, s7, 6
	v_readlane_b32 s7, v254, 16
	s_add_i32 s7, s10, s7
	s_cmp_ge_i32 s7, s81
	s_cbranch_scc1 .LBB0_908
	s_load_dwordx2 s[8:9], s[36:37], 0xb8
	s_waitcnt lgkmcnt(0)
	s_mul_i32 s52, s80, 0x5000
	s_lshl_b64 s[36:37], s[52:53], 2
	s_load_dwordx2 s[20:21], s[20:21], 0xb8
	s_mul_i32 s52, s80, 0xf000
	s_add_u32 s8, s8, s36
	s_addc_u32 s9, s9, s37
	s_add_u32 s8, s8, 0x195de000
	s_addc_u32 s9, s9, 0
	s_cmp_lg_u32 s80, 3
	s_cselect_b64 s[36:37], -1, 0
	s_cmp_eq_u32 s80, 0
	s_load_dwordx2 s[40:41], s[4:5], 0xb8
	s_cselect_b64 s[38:39], -1, 0
	s_lshl_b32 s42, s6, 3
	s_lshl_b64 s[44:45], s[52:53], 2
	s_waitcnt lgkmcnt(0)
	s_add_u32 s11, s20, s44
	s_addc_u32 s12, s21, s45
	v_and_b32_e32 v3, 63, v2
	s_add_u32 s54, s11, 0x194e6000
	v_lshlrev_b32_e32 v98, 5, v3
	s_addc_u32 s55, s12, 0
	v_lshl_add_u64 v[4:5], s[40:41], 0, v[98:99]
	s_mov_b64 s[12:13], 0x3bce8000
	v_lshl_add_u64 v[34:35], v[4:5], 0, s[12:13]
	s_ashr_i32 s11, s10, 31
	v_readlane_b32 s12, v254, 16
	s_add_u32 s10, s12, s10
	v_readlane_b32 s12, v254, 58
	s_addc_u32 s11, s12, s11
	s_lshl_b64 s[10:11], s[10:11], 12
	s_add_u32 s10, s40, s10
	v_lshlrev_b32_e32 v4, 3, v3
	v_lshlrev_b32_e32 v98, 4, v3
	s_addc_u32 s11, s41, s11
	v_lshlrev_b32_e32 v2, 1, v3
	v_or_b32_e32 v6, 0x400, v4
	v_or_b32_e32 v8, 0x600, v4
	v_lshl_add_u64 v[10:11], s[10:11], 0, v[98:99]
	s_mov_b64 s[10:11], 0x1da24c00
	s_ashr_i32 s43, s42, 31
	v_lshl_add_u64 v[36:37], v[10:11], 0, s[10:11]
	s_lshl_b64 s[44:45], s[42:43], 12
	v_lshlrev_b32_e32 v98, 4, v2
	v_lshlrev_b32_e32 v48, 2, v4
	v_lshlrev_b32_e32 v49, 2, v6
	v_lshlrev_b32_e32 v50, 2, v8
	s_mov_b32 s101, 0
	s_cmp_lg_u32 s6, 0x100
	s_cbranch_scc1 .Lnf2_skip
	s_mov_b32 s101, 1
	s_load_dwordx2 s[40:41], s[4:5], 0xb8
	v_and_b32_e32 v38, 63, v0
	v_lshlrev_b32_e32 v39, 4, v38
	v_lshlrev_b32_e32 v40, 5, v38
	s_lshr_b32 s20, s7, 3
	s_and_b32 s21, s20, 7
	s_lshl_b32 s21, s21, 5
	s_lshr_b32 s20, s20, 3
	s_or_b32 s20, s20, s21
	s_lshl_b32 s20, s20, 3
	s_and_b32 s21, s7, 7
	s_or_b32 s49, s20, s21
	s_lshl_b32 s10, s49, 15
	s_lshr_b32 s48, s49, 9
	s_lshl_b32 s20, s48, 13
	s_mul_i32 s49, s48, 0xc000
	s_waitcnt lgkmcnt(0)
	s_add_u32 s10, s40, s10
	s_addc_u32 s11, s41, 0
	s_add_u32 s10, s10, 0x19624000
	s_addc_u32 s11, s11, 0
	s_add_u32 s40, s8, s20
	s_addc_u32 s41, s9, 0
	s_add_u32 s48, s54, s49
	s_addc_u32 s49, s55, 0
	s_add_u32 s20, s10, 0x4400000
	s_addc_u32 s21, s11, 0
	global_load_dwordx4 v[100:103], v39, s[10:11]
	global_load_dwordx4 v[104:107], v39, s[10:11] offset:1024
	global_load_dwordx4 v[108:111], v39, s[10:11] offset:2048
	global_load_dwordx4 v[112:115], v39, s[10:11] offset:3072
	s_add_u32 s10, s10, 0x1000
	s_addc_u32 s11, s11, 0
	global_load_dwordx4 v[2:5], v40, s[40:41]
	global_load_dwordx4 v[6:9], v40, s[40:41] offset:16
	global_load_dwordx4 v[10:13], v40, s[40:41] offset:2048
	global_load_dwordx4 v[14:17], v40, s[40:41] offset:2064
	s_add_u32 s40, s40, 0x1000
	s_addc_u32 s41, s41, 0
	global_load_dwordx4 v[18:21], v40, s[40:41]
	global_load_dwordx4 v[22:25], v40, s[40:41] offset:16
	global_load_dwordx4 v[26:29], v40, s[40:41] offset:2048
	global_load_dwordx4 v[30:33], v40, s[40:41] offset:2064
	global_load_dwordx4 v[164:167], v40, s[48:49]
	global_load_dwordx4 v[168:171], v40, s[48:49] offset:16
	global_load_dwordx4 v[172:175], v40, s[48:49] offset:2048
	global_load_dwordx4 v[176:179], v40, s[48:49] offset:2064
	s_add_u32 s48, s48, 0x1000
	s_addc_u32 s49, s49, 0
	global_load_dwordx4 v[180:183], v40, s[48:49]
	global_load_dwordx4 v[184:187], v40, s[48:49] offset:16
	global_load_dwordx4 v[188:191], v40, s[48:49] offset:2048
	global_load_dwordx4 v[192:195], v40, s[48:49] offset:2064
	global_load_dwordx4 v[116:119], v39, s[10:11]
	global_load_dwordx4 v[120:123], v39, s[10:11] offset:1024
	global_load_dwordx4 v[124:127], v39, s[10:11] offset:2048
	global_load_dwordx4 v[128:131], v39, s[10:11] offset:3072
	s_add_u32 s10, s10, 0x1000
	s_addc_u32 s11, s11, 0
	global_load_dwordx4 v[132:135], v39, s[10:11]
	global_load_dwordx4 v[136:139], v39, s[10:11] offset:1024
	global_load_dwordx4 v[140:143], v39, s[10:11] offset:2048
	global_load_dwordx4 v[144:147], v39, s[10:11] offset:3072
	s_add_u32 s10, s10, 0x1000
	s_addc_u32 s11, s11, 0
	global_load_dwordx4 v[148:151], v39, s[10:11]
	global_load_dwordx4 v[152:155], v39, s[10:11] offset:1024
	global_load_dwordx4 v[156:159], v39, s[10:11] offset:2048
	global_load_dwordx4 v[160:163], v39, s[10:11] offset:3072
	s_add_u32 s10, s10, 0x1000
	s_addc_u32 s11, s11, 0
	v_mov_b32_e32 v47, 0x3a000000
	s_waitcnt vmcnt(28)
	v_lshlrev_b32_e32 v60, 16, v100
	v_and_b32_e32 v61, 0xffff0000, v100
	v_pk_mul_f32 v[42:43], v[60:61], v[60:61]
	v_lshlrev_b32_e32 v62, 16, v101
	v_and_b32_e32 v63, 0xffff0000, v101
	v_pk_fma_f32 v[42:43], v[62:63], v[62:63], v[42:43]
	v_lshlrev_b32_e32 v64, 16, v102
	v_and_b32_e32 v65, 0xffff0000, v102
	v_pk_fma_f32 v[42:43], v[64:65], v[64:65], v[42:43]
	v_lshlrev_b32_e32 v66, 16, v103
	v_and_b32_e32 v67, 0xffff0000, v103
	v_pk_fma_f32 v[42:43], v[66:67], v[66:67], v[42:43]
	v_lshlrev_b32_e32 v60, 16, v104
	v_and_b32_e32 v61, 0xffff0000, v104
	v_pk_fma_f32 v[42:43], v[60:61], v[60:61], v[42:43]
	v_lshlrev_b32_e32 v62, 16, v105
	v_and_b32_e32 v63, 0xffff0000, v105
	v_pk_fma_f32 v[42:43], v[62:63], v[62:63], v[42:43]
	v_lshlrev_b32_e32 v64, 16, v106
	v_and_b32_e32 v65, 0xffff0000, v106
	v_pk_fma_f32 v[42:43], v[64:65], v[64:65], v[42:43]
	v_lshlrev_b32_e32 v66, 16, v107
	v_and_b32_e32 v67, 0xffff0000, v107
	v_pk_fma_f32 v[42:43], v[66:67], v[66:67], v[42:43]
	v_lshlrev_b32_e32 v60, 16, v108
	v_and_b32_e32 v61, 0xffff0000, v108
	v_pk_fma_f32 v[42:43], v[60:61], v[60:61], v[42:43]
	v_lshlrev_b32_e32 v62, 16, v109
	v_and_b32_e32 v63, 0xffff0000, v109
	v_pk_fma_f32 v[42:43], v[62:63], v[62:63], v[42:43]
	v_lshlrev_b32_e32 v64, 16, v110
	v_and_b32_e32 v65, 0xffff0000, v110
	v_pk_fma_f32 v[42:43], v[64:65], v[64:65], v[42:43]
	v_lshlrev_b32_e32 v66, 16, v111
	v_and_b32_e32 v67, 0xffff0000, v111
	v_pk_fma_f32 v[42:43], v[66:67], v[66:67], v[42:43]
	v_lshlrev_b32_e32 v60, 16, v112
	v_and_b32_e32 v61, 0xffff0000, v112
	v_pk_fma_f32 v[42:43], v[60:61], v[60:61], v[42:43]
	v_lshlrev_b32_e32 v62, 16, v113
	v_and_b32_e32 v63, 0xffff0000, v113
	v_pk_fma_f32 v[42:43], v[62:63], v[62:63], v[42:43]
	v_lshlrev_b32_e32 v64, 16, v114
	v_and_b32_e32 v65, 0xffff0000, v114
	v_pk_fma_f32 v[42:43], v[64:65], v[64:65], v[42:43]
	v_lshlrev_b32_e32 v66, 16, v115
	v_and_b32_e32 v67, 0xffff0000, v115
	v_pk_fma_f32 v[42:43], v[66:67], v[66:67], v[42:43]
	v_add_f32_e32 v42, v42, v43
	s_nop 1
	v_add_f32_dpp v42, v42, v42 quad_perm:[1,0,3,2] row_mask:0xf bank_mask:0xf
	s_nop 1
	v_add_f32_dpp v42, v42, v42 quad_perm:[2,3,0,1] row_mask:0xf bank_mask:0xf
	s_nop 1
	v_add_f32_dpp v42, v42, v42 row_half_mirror row_mask:0xf bank_mask:0xf
	s_nop 1
	v_add_f32_dpp v42, v42, v42 row_mirror row_mask:0xf bank_mask:0xf
	s_nop 1
	v_add_f32_dpp v42, v42, v42 row_bcast:15 row_mask:0xa bank_mask:0xf
	s_nop 1
	v_add_f32_dpp v42, v42, v42 row_bcast:31 row_mask:0xc bank_mask:0xf
	s_nop 1
	v_readlane_b32 s100, v42, 63
	s_nop 3
	v_mov_b32_e32 v44, s100
	v_fma_f32 v44, v44, v47, v224
	v_rsq_f32_e32 v45, v44
	s_nop 0
	v_mul_f32_e32 v46, v44, v45
	v_mul_f32_e32 v46, v46, v45
	v_fmaak_f32 v46, -0.5, v46, 0x3fc00000
	v_mul_f32_e32 v44, v45, v46
	v_mov_b32_e32 v45, v44
	s_waitcnt vmcnt(12)
	v_lshlrev_b32_e32 v60, 16, v100
	v_and_b32_e32 v61, 0xffff0000, v100
	v_pk_mul_f32 v[60:61], v[60:61], v[44:45]
	v_pk_fma_f32 v[60:61], v[60:61], v[2:3], v[164:165]
	v_cvt_pk_bf16_f32 v100, v60, v61
	v_lshlrev_b32_e32 v62, 16, v101
	v_and_b32_e32 v63, 0xffff0000, v101
	v_pk_mul_f32 v[62:63], v[62:63], v[44:45]
	v_pk_fma_f32 v[62:63], v[62:63], v[4:5], v[166:167]
	v_cvt_pk_bf16_f32 v101, v62, v63
	v_lshlrev_b32_e32 v64, 16, v102
	v_and_b32_e32 v65, 0xffff0000, v102
	v_pk_mul_f32 v[64:65], v[64:65], v[44:45]
	v_pk_fma_f32 v[64:65], v[64:65], v[6:7], v[168:169]
	v_cvt_pk_bf16_f32 v102, v64, v65
	v_lshlrev_b32_e32 v66, 16, v103
	v_and_b32_e32 v67, 0xffff0000, v103
	v_pk_mul_f32 v[66:67], v[66:67], v[44:45]
	v_pk_fma_f32 v[66:67], v[66:67], v[8:9], v[170:171]
	v_cvt_pk_bf16_f32 v103, v66, v67
	v_lshlrev_b32_e32 v60, 16, v104
	v_and_b32_e32 v61, 0xffff0000, v104
	v_pk_mul_f32 v[60:61], v[60:61], v[44:45]
	v_pk_fma_f32 v[60:61], v[60:61], v[10:11], v[172:173]
	v_cvt_pk_bf16_f32 v104, v60, v61
	v_lshlrev_b32_e32 v62, 16, v105
	v_and_b32_e32 v63, 0xffff0000, v105
	v_pk_mul_f32 v[62:63], v[62:63], v[44:45]
	v_pk_fma_f32 v[62:63], v[62:63], v[12:13], v[174:175]
	v_cvt_pk_bf16_f32 v105, v62, v63
	v_lshlrev_b32_e32 v64, 16, v106
	v_and_b32_e32 v65, 0xffff0000, v106
	v_pk_mul_f32 v[64:65], v[64:65], v[44:45]
	v_pk_fma_f32 v[64:65], v[64:65], v[14:15], v[176:177]
	v_cvt_pk_bf16_f32 v106, v64, v65
	v_lshlrev_b32_e32 v66, 16, v107
	v_and_b32_e32 v67, 0xffff0000, v107
	v_pk_mul_f32 v[66:67], v[66:67], v[44:45]
	v_pk_fma_f32 v[66:67], v[66:67], v[16:17], v[178:179]
	v_cvt_pk_bf16_f32 v107, v66, v67
	v_lshlrev_b32_e32 v60, 16, v108
	v_and_b32_e32 v61, 0xffff0000, v108
	v_pk_mul_f32 v[60:61], v[60:61], v[44:45]
	v_pk_fma_f32 v[60:61], v[60:61], v[18:19], v[180:181]
	v_cvt_pk_bf16_f32 v108, v60, v61
	v_lshlrev_b32_e32 v62, 16, v109
	v_and_b32_e32 v63, 0xffff0000, v109
	v_pk_mul_f32 v[62:63], v[62:63], v[44:45]
	v_pk_fma_f32 v[62:63], v[62:63], v[20:21], v[182:183]
	v_cvt_pk_bf16_f32 v109, v62, v63
	v_lshlrev_b32_e32 v64, 16, v110
	v_and_b32_e32 v65, 0xffff0000, v110
	v_pk_mul_f32 v[64:65], v[64:65], v[44:45]
	v_pk_fma_f32 v[64:65], v[64:65], v[22:23], v[184:185]
	v_cvt_pk_bf16_f32 v110, v64, v65
	v_lshlrev_b32_e32 v66, 16, v111
	v_and_b32_e32 v67, 0xffff0000, v111
	v_pk_mul_f32 v[66:67], v[66:67], v[44:45]
	v_pk_fma_f32 v[66:67], v[66:67], v[24:25], v[186:187]
	v_cvt_pk_bf16_f32 v111, v66, v67
	v_lshlrev_b32_e32 v60, 16, v112
	v_and_b32_e32 v61, 0xffff0000, v112
	v_pk_mul_f32 v[60:61], v[60:61], v[44:45]
	v_pk_fma_f32 v[60:61], v[60:61], v[26:27], v[188:189]
	v_cvt_pk_bf16_f32 v112, v60, v61
	v_lshlrev_b32_e32 v62, 16, v113
	v_and_b32_e32 v63, 0xffff0000, v113
	v_pk_mul_f32 v[62:63], v[62:63], v[44:45]
	v_pk_fma_f32 v[62:63], v[62:63], v[28:29], v[190:191]
	v_cvt_pk_bf16_f32 v113, v62, v63
	v_lshlrev_b32_e32 v64, 16, v114
	v_and_b32_e32 v65, 0xffff0000, v114
	v_pk_mul_f32 v[64:65], v[64:65], v[44:45]
	v_pk_fma_f32 v[64:65], v[64:65], v[30:31], v[192:193]
	v_cvt_pk_bf16_f32 v114, v64, v65
	v_lshlrev_b32_e32 v66, 16, v115
	v_and_b32_e32 v67, 0xffff0000, v115
	v_pk_mul_f32 v[66:67], v[66:67], v[44:45]
	v_pk_fma_f32 v[66:67], v[66:67], v[32:33], v[194:195]
	v_cvt_pk_bf16_f32 v115, v66, v67
	global_store_dwordx4 v39, v[100:103], s[20:21]
	global_store_dwordx4 v39, v[104:107], s[20:21] offset:1024
	global_store_dwordx4 v39, v[108:111], s[20:21] offset:2048
	global_store_dwordx4 v39, v[112:115], s[20:21] offset:3072
	s_add_u32 s20, s20, 0x1000
	s_addc_u32 s21, s21, 0
	global_load_dwordx4 v[100:103], v39, s[10:11]
	global_load_dwordx4 v[104:107], v39, s[10:11] offset:1024
	global_load_dwordx4 v[108:111], v39, s[10:11] offset:2048
	global_load_dwordx4 v[112:115], v39, s[10:11] offset:3072
	s_add_u32 s10, s10, 0x1000
	s_addc_u32 s11, s11, 0
	s_waitcnt vmcnt(16)
	v_lshlrev_b32_e32 v60, 16, v116
	v_and_b32_e32 v61, 0xffff0000, v116
	v_pk_mul_f32 v[42:43], v[60:61], v[60:61]
	v_lshlrev_b32_e32 v62, 16, v117
	v_and_b32_e32 v63, 0xffff0000, v117
	v_pk_fma_f32 v[42:43], v[62:63], v[62:63], v[42:43]
	v_lshlrev_b32_e32 v64, 16, v118
	v_and_b32_e32 v65, 0xffff0000, v118
	v_pk_fma_f32 v[42:43], v[64:65], v[64:65], v[42:43]
	v_lshlrev_b32_e32 v66, 16, v119
	v_and_b32_e32 v67, 0xffff0000, v119
	v_pk_fma_f32 v[42:43], v[66:67], v[66:67], v[42:43]
	v_lshlrev_b32_e32 v60, 16, v120
	v_and_b32_e32 v61, 0xffff0000, v120
	v_pk_fma_f32 v[42:43], v[60:61], v[60:61], v[42:43]
	v_lshlrev_b32_e32 v62, 16, v121
	v_and_b32_e32 v63, 0xffff0000, v121
	v_pk_fma_f32 v[42:43], v[62:63], v[62:63], v[42:43]
	v_lshlrev_b32_e32 v64, 16, v122
	v_and_b32_e32 v65, 0xffff0000, v122
	v_pk_fma_f32 v[42:43], v[64:65], v[64:65], v[42:43]
	v_lshlrev_b32_e32 v66, 16, v123
	v_and_b32_e32 v67, 0xffff0000, v123
	v_pk_fma_f32 v[42:43], v[66:67], v[66:67], v[42:43]
	v_lshlrev_b32_e32 v60, 16, v124
	v_and_b32_e32 v61, 0xffff0000, v124
	v_pk_fma_f32 v[42:43], v[60:61], v[60:61], v[42:43]
	v_lshlrev_b32_e32 v62, 16, v125
	v_and_b32_e32 v63, 0xffff0000, v125
	v_pk_fma_f32 v[42:43], v[62:63], v[62:63], v[42:43]
	v_lshlrev_b32_e32 v64, 16, v126
	v_and_b32_e32 v65, 0xffff0000, v126
	v_pk_fma_f32 v[42:43], v[64:65], v[64:65], v[42:43]
	v_lshlrev_b32_e32 v66, 16, v127
	v_and_b32_e32 v67, 0xffff0000, v127
	v_pk_fma_f32 v[42:43], v[66:67], v[66:67], v[42:43]
	v_lshlrev_b32_e32 v60, 16, v128
	v_and_b32_e32 v61, 0xffff0000, v128
	v_pk_fma_f32 v[42:43], v[60:61], v[60:61], v[42:43]
	v_lshlrev_b32_e32 v62, 16, v129
	v_and_b32_e32 v63, 0xffff0000, v129
	v_pk_fma_f32 v[42:43], v[62:63], v[62:63], v[42:43]
	v_lshlrev_b32_e32 v64, 16, v130
	v_and_b32_e32 v65, 0xffff0000, v130
	v_pk_fma_f32 v[42:43], v[64:65], v[64:65], v[42:43]
	v_lshlrev_b32_e32 v66, 16, v131
	v_and_b32_e32 v67, 0xffff0000, v131
	v_pk_fma_f32 v[42:43], v[66:67], v[66:67], v[42:43]
	v_add_f32_e32 v42, v42, v43
	s_nop 1
	v_add_f32_dpp v42, v42, v42 quad_perm:[1,0,3,2] row_mask:0xf bank_mask:0xf
	s_nop 1
	v_add_f32_dpp v42, v42, v42 quad_perm:[2,3,0,1] row_mask:0xf bank_mask:0xf
	s_nop 1
	v_add_f32_dpp v42, v42, v42 row_half_mirror row_mask:0xf bank_mask:0xf
	s_nop 1
	v_add_f32_dpp v42, v42, v42 row_mirror row_mask:0xf bank_mask:0xf
	s_nop 1
	v_add_f32_dpp v42, v42, v42 row_bcast:15 row_mask:0xa bank_mask:0xf
	s_nop 1
	v_add_f32_dpp v42, v42, v42 row_bcast:31 row_mask:0xc bank_mask:0xf
	s_nop 1
	v_readlane_b32 s100, v42, 63
	s_nop 3
	v_mov_b32_e32 v44, s100
	v_fma_f32 v44, v44, v47, v224
	v_rsq_f32_e32 v45, v44
	s_nop 0
	v_mul_f32_e32 v46, v44, v45
	v_mul_f32_e32 v46, v46, v45
	v_fmaak_f32 v46, -0.5, v46, 0x3fc00000
	v_mul_f32_e32 v44, v45, v46
	v_mov_b32_e32 v45, v44
	v_lshlrev_b32_e32 v60, 16, v116
	v_and_b32_e32 v61, 0xffff0000, v116
	v_pk_mul_f32 v[60:61], v[60:61], v[44:45]
	v_pk_fma_f32 v[60:61], v[60:61], v[2:3], v[164:165]
	v_cvt_pk_bf16_f32 v116, v60, v61
	v_lshlrev_b32_e32 v62, 16, v117
	v_and_b32_e32 v63, 0xffff0000, v117
	v_pk_mul_f32 v[62:63], v[62:63], v[44:45]
	v_pk_fma_f32 v[62:63], v[62:63], v[4:5], v[166:167]
	v_cvt_pk_bf16_f32 v117, v62, v63
	v_lshlrev_b32_e32 v64, 16, v118
	v_and_b32_e32 v65, 0xffff0000, v118
	v_pk_mul_f32 v[64:65], v[64:65], v[44:45]
	v_pk_fma_f32 v[64:65], v[64:65], v[6:7], v[168:169]
	v_cvt_pk_bf16_f32 v118, v64, v65
	v_lshlrev_b32_e32 v66, 16, v119
	v_and_b32_e32 v67, 0xffff0000, v119
	v_pk_mul_f32 v[66:67], v[66:67], v[44:45]
	v_pk_fma_f32 v[66:67], v[66:67], v[8:9], v[170:171]
	v_cvt_pk_bf16_f32 v119, v66, v67
	v_lshlrev_b32_e32 v60, 16, v120
	v_and_b32_e32 v61, 0xffff0000, v120
	v_pk_mul_f32 v[60:61], v[60:61], v[44:45]
	v_pk_fma_f32 v[60:61], v[60:61], v[10:11], v[172:173]
	v_cvt_pk_bf16_f32 v120, v60, v61
	v_lshlrev_b32_e32 v62, 16, v121
	v_and_b32_e32 v63, 0xffff0000, v121
	v_pk_mul_f32 v[62:63], v[62:63], v[44:45]
	v_pk_fma_f32 v[62:63], v[62:63], v[12:13], v[174:175]
	v_cvt_pk_bf16_f32 v121, v62, v63
	v_lshlrev_b32_e32 v64, 16, v122
	v_and_b32_e32 v65, 0xffff0000, v122
	v_pk_mul_f32 v[64:65], v[64:65], v[44:45]
	v_pk_fma_f32 v[64:65], v[64:65], v[14:15], v[176:177]
	v_cvt_pk_bf16_f32 v122, v64, v65
	v_lshlrev_b32_e32 v66, 16, v123
	v_and_b32_e32 v67, 0xffff0000, v123
	v_pk_mul_f32 v[66:67], v[66:67], v[44:45]
	v_pk_fma_f32 v[66:67], v[66:67], v[16:17], v[178:179]
	v_cvt_pk_bf16_f32 v123, v66, v67
	v_lshlrev_b32_e32 v60, 16, v124
	v_and_b32_e32 v61, 0xffff0000, v124
	v_pk_mul_f32 v[60:61], v[60:61], v[44:45]
	v_pk_fma_f32 v[60:61], v[60:61], v[18:19], v[180:181]
	v_cvt_pk_bf16_f32 v124, v60, v61
	v_lshlrev_b32_e32 v62, 16, v125
	v_and_b32_e32 v63, 0xffff0000, v125
	v_pk_mul_f32 v[62:63], v[62:63], v[44:45]
	v_pk_fma_f32 v[62:63], v[62:63], v[20:21], v[182:183]
	v_cvt_pk_bf16_f32 v125, v62, v63
	v_lshlrev_b32_e32 v64, 16, v126
	v_and_b32_e32 v65, 0xffff0000, v126
	v_pk_mul_f32 v[64:65], v[64:65], v[44:45]
	v_pk_fma_f32 v[64:65], v[64:65], v[22:23], v[184:185]
	v_cvt_pk_bf16_f32 v126, v64, v65
	v_lshlrev_b32_e32 v66, 16, v127
	v_and_b32_e32 v67, 0xffff0000, v127
	v_pk_mul_f32 v[66:67], v[66:67], v[44:45]
	v_pk_fma_f32 v[66:67], v[66:67], v[24:25], v[186:187]
	v_cvt_pk_bf16_f32 v127, v66, v67
	v_lshlrev_b32_e32 v60, 16, v128
	v_and_b32_e32 v61, 0xffff0000, v128
	v_pk_mul_f32 v[60:61], v[60:61], v[44:45]
	v_pk_fma_f32 v[60:61], v[60:61], v[26:27], v[188:189]
	v_cvt_pk_bf16_f32 v128, v60, v61
	v_lshlrev_b32_e32 v62, 16, v129
	v_and_b32_e32 v63, 0xffff0000, v129
	v_pk_mul_f32 v[62:63], v[62:63], v[44:45]
	v_pk_fma_f32 v[62:63], v[62:63], v[28:29], v[190:191]
	v_cvt_pk_bf16_f32 v129, v62, v63
	v_lshlrev_b32_e32 v64, 16, v130
	v_and_b32_e32 v65, 0xffff0000, v130
	v_pk_mul_f32 v[64:65], v[64:65], v[44:45]
	v_pk_fma_f32 v[64:65], v[64:65], v[30:31], v[192:193]
	v_cvt_pk_bf16_f32 v130, v64, v65
	v_lshlrev_b32_e32 v66, 16, v131
	v_and_b32_e32 v67, 0xffff0000, v131
	v_pk_mul_f32 v[66:67], v[66:67], v[44:45]
	v_pk_fma_f32 v[66:67], v[66:67], v[32:33], v[194:195]
	v_cvt_pk_bf16_f32 v131, v66, v67
	global_store_dwordx4 v39, v[116:119], s[20:21]
	global_store_dwordx4 v39, v[120:123], s[20:21] offset:1024
	global_store_dwordx4 v39, v[124:127], s[20:21] offset:2048
	global_store_dwordx4 v39, v[128:131], s[20:21] offset:3072
	s_add_u32 s20, s20, 0x1000
	s_addc_u32 s21, s21, 0
	global_load_dwordx4 v[116:119], v39, s[10:11]
	global_load_dwordx4 v[120:123], v39, s[10:11] offset:1024
	global_load_dwordx4 v[124:127], v39, s[10:11] offset:2048
	global_load_dwordx4 v[128:131], v39, s[10:11] offset:3072
	s_add_u32 s10, s10, 0x1000
	s_addc_u32 s11, s11, 0
	s_waitcnt vmcnt(20)
	v_lshlrev_b32_e32 v60, 16, v132
	v_and_b32_e32 v61, 0xffff0000, v132
	v_pk_mul_f32 v[42:43], v[60:61], v[60:61]
	v_lshlrev_b32_e32 v62, 16, v133
	v_and_b32_e32 v63, 0xffff0000, v133
	v_pk_fma_f32 v[42:43], v[62:63], v[62:63], v[42:43]
	v_lshlrev_b32_e32 v64, 16, v134
	v_and_b32_e32 v65, 0xffff0000, v134
	v_pk_fma_f32 v[42:43], v[64:65], v[64:65], v[42:43]
	v_lshlrev_b32_e32 v66, 16, v135
	v_and_b32_e32 v67, 0xffff0000, v135
	v_pk_fma_f32 v[42:43], v[66:67], v[66:67], v[42:43]
	v_lshlrev_b32_e32 v60, 16, v136
	v_and_b32_e32 v61, 0xffff0000, v136
	v_pk_fma_f32 v[42:43], v[60:61], v[60:61], v[42:43]
	v_lshlrev_b32_e32 v62, 16, v137
	v_and_b32_e32 v63, 0xffff0000, v137
	v_pk_fma_f32 v[42:43], v[62:63], v[62:63], v[42:43]
	v_lshlrev_b32_e32 v64, 16, v138
	v_and_b32_e32 v65, 0xffff0000, v138
	v_pk_fma_f32 v[42:43], v[64:65], v[64:65], v[42:43]
	v_lshlrev_b32_e32 v66, 16, v139
	v_and_b32_e32 v67, 0xffff0000, v139
	v_pk_fma_f32 v[42:43], v[66:67], v[66:67], v[42:43]
	v_lshlrev_b32_e32 v60, 16, v140
	v_and_b32_e32 v61, 0xffff0000, v140
	v_pk_fma_f32 v[42:43], v[60:61], v[60:61], v[42:43]
	v_lshlrev_b32_e32 v62, 16, v141
	v_and_b32_e32 v63, 0xffff0000, v141
	v_pk_fma_f32 v[42:43], v[62:63], v[62:63], v[42:43]
	v_lshlrev_b32_e32 v64, 16, v142
	v_and_b32_e32 v65, 0xffff0000, v142
	v_pk_fma_f32 v[42:43], v[64:65], v[64:65], v[42:43]
	v_lshlrev_b32_e32 v66, 16, v143
	v_and_b32_e32 v67, 0xffff0000, v143
	v_pk_fma_f32 v[42:43], v[66:67], v[66:67], v[42:43]
	v_lshlrev_b32_e32 v60, 16, v144
	v_and_b32_e32 v61, 0xffff0000, v144
	v_pk_fma_f32 v[42:43], v[60:61], v[60:61], v[42:43]
	v_lshlrev_b32_e32 v62, 16, v145
	v_and_b32_e32 v63, 0xffff0000, v145
	v_pk_fma_f32 v[42:43], v[62:63], v[62:63], v[42:43]
	v_lshlrev_b32_e32 v64, 16, v146
	v_and_b32_e32 v65, 0xffff0000, v146
	v_pk_fma_f32 v[42:43], v[64:65], v[64:65], v[42:43]
	v_lshlrev_b32_e32 v66, 16, v147
	v_and_b32_e32 v67, 0xffff0000, v147
	v_pk_fma_f32 v[42:43], v[66:67], v[66:67], v[42:43]
	v_add_f32_e32 v42, v42, v43
	s_nop 1
	v_add_f32_dpp v42, v42, v42 quad_perm:[1,0,3,2] row_mask:0xf bank_mask:0xf
	s_nop 1
	v_add_f32_dpp v42, v42, v42 quad_perm:[2,3,0,1] row_mask:0xf bank_mask:0xf
	s_nop 1
	v_add_f32_dpp v42, v42, v42 row_half_mirror row_mask:0xf bank_mask:0xf
	s_nop 1
	v_add_f32_dpp v42, v42, v42 row_mirror row_mask:0xf bank_mask:0xf
	s_nop 1
	v_add_f32_dpp v42, v42, v42 row_bcast:15 row_mask:0xa bank_mask:0xf
	s_nop 1
	v_add_f32_dpp v42, v42, v42 row_bcast:31 row_mask:0xc bank_mask:0xf
	s_nop 1
	v_readlane_b32 s100, v42, 63
	s_nop 3
	v_mov_b32_e32 v44, s100
	v_fma_f32 v44, v44, v47, v224
	v_rsq_f32_e32 v45, v44
	s_nop 0
	v_mul_f32_e32 v46, v44, v45
	v_mul_f32_e32 v46, v46, v45
	v_fmaak_f32 v46, -0.5, v46, 0x3fc00000
	v_mul_f32_e32 v44, v45, v46
	v_mov_b32_e32 v45, v44
	v_lshlrev_b32_e32 v60, 16, v132
	v_and_b32_e32 v61, 0xffff0000, v132
	v_pk_mul_f32 v[60:61], v[60:61], v[44:45]
	v_pk_fma_f32 v[60:61], v[60:61], v[2:3], v[164:165]
	v_cvt_pk_bf16_f32 v132, v60, v61
	v_lshlrev_b32_e32 v62, 16, v133
	v_and_b32_e32 v63, 0xffff0000, v133
	v_pk_mul_f32 v[62:63], v[62:63], v[44:45]
	v_pk_fma_f32 v[62:63], v[62:63], v[4:5], v[166:167]
	v_cvt_pk_bf16_f32 v133, v62, v63
	v_lshlrev_b32_e32 v64, 16, v134
	v_and_b32_e32 v65, 0xffff0000, v134
	v_pk_mul_f32 v[64:65], v[64:65], v[44:45]
	v_pk_fma_f32 v[64:65], v[64:65], v[6:7], v[168:169]
	v_cvt_pk_bf16_f32 v134, v64, v65
	v_lshlrev_b32_e32 v66, 16, v135
	v_and_b32_e32 v67, 0xffff0000, v135
	v_pk_mul_f32 v[66:67], v[66:67], v[44:45]
	v_pk_fma_f32 v[66:67], v[66:67], v[8:9], v[170:171]
	v_cvt_pk_bf16_f32 v135, v66, v67
	v_lshlrev_b32_e32 v60, 16, v136
	v_and_b32_e32 v61, 0xffff0000, v136
	v_pk_mul_f32 v[60:61], v[60:61], v[44:45]
	v_pk_fma_f32 v[60:61], v[60:61], v[10:11], v[172:173]
	v_cvt_pk_bf16_f32 v136, v60, v61
	v_lshlrev_b32_e32 v62, 16, v137
	v_and_b32_e32 v63, 0xffff0000, v137
	v_pk_mul_f32 v[62:63], v[62:63], v[44:45]
	v_pk_fma_f32 v[62:63], v[62:63], v[12:13], v[174:175]
	v_cvt_pk_bf16_f32 v137, v62, v63
	v_lshlrev_b32_e32 v64, 16, v138
	v_and_b32_e32 v65, 0xffff0000, v138
	v_pk_mul_f32 v[64:65], v[64:65], v[44:45]
	v_pk_fma_f32 v[64:65], v[64:65], v[14:15], v[176:177]
	v_cvt_pk_bf16_f32 v138, v64, v65
	v_lshlrev_b32_e32 v66, 16, v139
	v_and_b32_e32 v67, 0xffff0000, v139
	v_pk_mul_f32 v[66:67], v[66:67], v[44:45]
	v_pk_fma_f32 v[66:67], v[66:67], v[16:17], v[178:179]
	v_cvt_pk_bf16_f32 v139, v66, v67
	v_lshlrev_b32_e32 v60, 16, v140
	v_and_b32_e32 v61, 0xffff0000, v140
	v_pk_mul_f32 v[60:61], v[60:61], v[44:45]
	v_pk_fma_f32 v[60:61], v[60:61], v[18:19], v[180:181]
	v_cvt_pk_bf16_f32 v140, v60, v61
	v_lshlrev_b32_e32 v62, 16, v141
	v_and_b32_e32 v63, 0xffff0000, v141
	v_pk_mul_f32 v[62:63], v[62:63], v[44:45]
	v_pk_fma_f32 v[62:63], v[62:63], v[20:21], v[182:183]
	v_cvt_pk_bf16_f32 v141, v62, v63
	v_lshlrev_b32_e32 v64, 16, v142
	v_and_b32_e32 v65, 0xffff0000, v142
	v_pk_mul_f32 v[64:65], v[64:65], v[44:45]
	v_pk_fma_f32 v[64:65], v[64:65], v[22:23], v[184:185]
	v_cvt_pk_bf16_f32 v142, v64, v65
	v_lshlrev_b32_e32 v66, 16, v143
	v_and_b32_e32 v67, 0xffff0000, v143
	v_pk_mul_f32 v[66:67], v[66:67], v[44:45]
	v_pk_fma_f32 v[66:67], v[66:67], v[24:25], v[186:187]
	v_cvt_pk_bf16_f32 v143, v66, v67
	v_lshlrev_b32_e32 v60, 16, v144
	v_and_b32_e32 v61, 0xffff0000, v144
	v_pk_mul_f32 v[60:61], v[60:61], v[44:45]
	v_pk_fma_f32 v[60:61], v[60:61], v[26:27], v[188:189]
	v_cvt_pk_bf16_f32 v144, v60, v61
	v_lshlrev_b32_e32 v62, 16, v145
	v_and_b32_e32 v63, 0xffff0000, v145
	v_pk_mul_f32 v[62:63], v[62:63], v[44:45]
	v_pk_fma_f32 v[62:63], v[62:63], v[28:29], v[190:191]
	v_cvt_pk_bf16_f32 v145, v62, v63
	v_lshlrev_b32_e32 v64, 16, v146
	v_and_b32_e32 v65, 0xffff0000, v146
	v_pk_mul_f32 v[64:65], v[64:65], v[44:45]
	v_pk_fma_f32 v[64:65], v[64:65], v[30:31], v[192:193]
	v_cvt_pk_bf16_f32 v146, v64, v65
	v_lshlrev_b32_e32 v66, 16, v147
	v_and_b32_e32 v67, 0xffff0000, v147
	v_pk_mul_f32 v[66:67], v[66:67], v[44:45]
	v_pk_fma_f32 v[66:67], v[66:67], v[32:33], v[194:195]
	v_cvt_pk_bf16_f32 v147, v66, v67
	global_store_dwordx4 v39, v[132:135], s[20:21]
	global_store_dwordx4 v39, v[136:139], s[20:21] offset:1024
	global_store_dwordx4 v39, v[140:143], s[20:21] offset:2048
	global_store_dwordx4 v39, v[144:147], s[20:21] offset:3072
	s_add_u32 s20, s20, 0x1000
	s_addc_u32 s21, s21, 0
	global_load_dwordx4 v[132:135], v39, s[10:11]
	global_load_dwordx4 v[136:139], v39, s[10:11] offset:1024
	global_load_dwordx4 v[140:143], v39, s[10:11] offset:2048
	global_load_dwordx4 v[144:147], v39, s[10:11] offset:3072
	s_add_u32 s10, s10, 0x1000
	s_addc_u32 s11, s11, 0
	s_waitcnt vmcnt(24)
	v_lshlrev_b32_e32 v60, 16, v148
	v_and_b32_e32 v61, 0xffff0000, v148
	v_pk_mul_f32 v[42:43], v[60:61], v[60:61]
	v_lshlrev_b32_e32 v62, 16, v149
	v_and_b32_e32 v63, 0xffff0000, v149
	v_pk_fma_f32 v[42:43], v[62:63], v[62:63], v[42:43]
	v_lshlrev_b32_e32 v64, 16, v150
	v_and_b32_e32 v65, 0xffff0000, v150
	v_pk_fma_f32 v[42:43], v[64:65], v[64:65], v[42:43]
	v_lshlrev_b32_e32 v66, 16, v151
	v_and_b32_e32 v67, 0xffff0000, v151
	v_pk_fma_f32 v[42:43], v[66:67], v[66:67], v[42:43]
	v_lshlrev_b32_e32 v60, 16, v152
	v_and_b32_e32 v61, 0xffff0000, v152
	v_pk_fma_f32 v[42:43], v[60:61], v[60:61], v[42:43]
	v_lshlrev_b32_e32 v62, 16, v153
	v_and_b32_e32 v63, 0xffff0000, v153
	v_pk_fma_f32 v[42:43], v[62:63], v[62:63], v[42:43]
	v_lshlrev_b32_e32 v64, 16, v154
	v_and_b32_e32 v65, 0xffff0000, v154
	v_pk_fma_f32 v[42:43], v[64:65], v[64:65], v[42:43]
	v_lshlrev_b32_e32 v66, 16, v155
	v_and_b32_e32 v67, 0xffff0000, v155
	v_pk_fma_f32 v[42:43], v[66:67], v[66:67], v[42:43]
	v_lshlrev_b32_e32 v60, 16, v156
	v_and_b32_e32 v61, 0xffff0000, v156
	v_pk_fma_f32 v[42:43], v[60:61], v[60:61], v[42:43]
	v_lshlrev_b32_e32 v62, 16, v157
	v_and_b32_e32 v63, 0xffff0000, v157
	v_pk_fma_f32 v[42:43], v[62:63], v[62:63], v[42:43]
	v_lshlrev_b32_e32 v64, 16, v158
	v_and_b32_e32 v65, 0xffff0000, v158
	v_pk_fma_f32 v[42:43], v[64:65], v[64:65], v[42:43]
	v_lshlrev_b32_e32 v66, 16, v159
	v_and_b32_e32 v67, 0xffff0000, v159
	v_pk_fma_f32 v[42:43], v[66:67], v[66:67], v[42:43]
	v_lshlrev_b32_e32 v60, 16, v160
	v_and_b32_e32 v61, 0xffff0000, v160
	v_pk_fma_f32 v[42:43], v[60:61], v[60:61], v[42:43]
	v_lshlrev_b32_e32 v62, 16, v161
	v_and_b32_e32 v63, 0xffff0000, v161
	v_pk_fma_f32 v[42:43], v[62:63], v[62:63], v[42:43]
	v_lshlrev_b32_e32 v64, 16, v162
	v_and_b32_e32 v65, 0xffff0000, v162
	v_pk_fma_f32 v[42:43], v[64:65], v[64:65], v[42:43]
	v_lshlrev_b32_e32 v66, 16, v163
	v_and_b32_e32 v67, 0xffff0000, v163
	v_pk_fma_f32 v[42:43], v[66:67], v[66:67], v[42:43]
	v_add_f32_e32 v42, v42, v43
	s_nop 1
	v_add_f32_dpp v42, v42, v42 quad_perm:[1,0,3,2] row_mask:0xf bank_mask:0xf
	s_nop 1
	v_add_f32_dpp v42, v42, v42 quad_perm:[2,3,0,1] row_mask:0xf bank_mask:0xf
	s_nop 1
	v_add_f32_dpp v42, v42, v42 row_half_mirror row_mask:0xf bank_mask:0xf
	s_nop 1
	v_add_f32_dpp v42, v42, v42 row_mirror row_mask:0xf bank_mask:0xf
	s_nop 1
	v_add_f32_dpp v42, v42, v42 row_bcast:15 row_mask:0xa bank_mask:0xf
	s_nop 1
	v_add_f32_dpp v42, v42, v42 row_bcast:31 row_mask:0xc bank_mask:0xf
	s_nop 1
	v_readlane_b32 s100, v42, 63
	s_nop 3
	v_mov_b32_e32 v44, s100
	v_fma_f32 v44, v44, v47, v224
	v_rsq_f32_e32 v45, v44
	s_nop 0
	v_mul_f32_e32 v46, v44, v45
	v_mul_f32_e32 v46, v46, v45
	v_fmaak_f32 v46, -0.5, v46, 0x3fc00000
	v_mul_f32_e32 v44, v45, v46
	v_mov_b32_e32 v45, v44
	v_lshlrev_b32_e32 v60, 16, v148
	v_and_b32_e32 v61, 0xffff0000, v148
	v_pk_mul_f32 v[60:61], v[60:61], v[44:45]
	v_pk_fma_f32 v[60:61], v[60:61], v[2:3], v[164:165]
	v_cvt_pk_bf16_f32 v148, v60, v61
	v_lshlrev_b32_e32 v62, 16, v149
	v_and_b32_e32 v63, 0xffff0000, v149
	v_pk_mul_f32 v[62:63], v[62:63], v[44:45]
	v_pk_fma_f32 v[62:63], v[62:63], v[4:5], v[166:167]
	v_cvt_pk_bf16_f32 v149, v62, v63
	v_lshlrev_b32_e32 v64, 16, v150
	v_and_b32_e32 v65, 0xffff0000, v150
	v_pk_mul_f32 v[64:65], v[64:65], v[44:45]
	v_pk_fma_f32 v[64:65], v[64:65], v[6:7], v[168:169]
	v_cvt_pk_bf16_f32 v150, v64, v65
	v_lshlrev_b32_e32 v66, 16, v151
	v_and_b32_e32 v67, 0xffff0000, v151
	v_pk_mul_f32 v[66:67], v[66:67], v[44:45]
	v_pk_fma_f32 v[66:67], v[66:67], v[8:9], v[170:171]
	v_cvt_pk_bf16_f32 v151, v66, v67
	v_lshlrev_b32_e32 v60, 16, v152
	v_and_b32_e32 v61, 0xffff0000, v152
	v_pk_mul_f32 v[60:61], v[60:61], v[44:45]
	v_pk_fma_f32 v[60:61], v[60:61], v[10:11], v[172:173]
	v_cvt_pk_bf16_f32 v152, v60, v61
	v_lshlrev_b32_e32 v62, 16, v153
	v_and_b32_e32 v63, 0xffff0000, v153
	v_pk_mul_f32 v[62:63], v[62:63], v[44:45]
	v_pk_fma_f32 v[62:63], v[62:63], v[12:13], v[174:175]
	v_cvt_pk_bf16_f32 v153, v62, v63
	v_lshlrev_b32_e32 v64, 16, v154
	v_and_b32_e32 v65, 0xffff0000, v154
	v_pk_mul_f32 v[64:65], v[64:65], v[44:45]
	v_pk_fma_f32 v[64:65], v[64:65], v[14:15], v[176:177]
	v_cvt_pk_bf16_f32 v154, v64, v65
	v_lshlrev_b32_e32 v66, 16, v155
	v_and_b32_e32 v67, 0xffff0000, v155
	v_pk_mul_f32 v[66:67], v[66:67], v[44:45]
	v_pk_fma_f32 v[66:67], v[66:67], v[16:17], v[178:179]
	v_cvt_pk_bf16_f32 v155, v66, v67
	v_lshlrev_b32_e32 v60, 16, v156
	v_and_b32_e32 v61, 0xffff0000, v156
	v_pk_mul_f32 v[60:61], v[60:61], v[44:45]
	v_pk_fma_f32 v[60:61], v[60:61], v[18:19], v[180:181]
	v_cvt_pk_bf16_f32 v156, v60, v61
	v_lshlrev_b32_e32 v62, 16, v157
	v_and_b32_e32 v63, 0xffff0000, v157
	v_pk_mul_f32 v[62:63], v[62:63], v[44:45]
	v_pk_fma_f32 v[62:63], v[62:63], v[20:21], v[182:183]
	v_cvt_pk_bf16_f32 v157, v62, v63
	v_lshlrev_b32_e32 v64, 16, v158
	v_and_b32_e32 v65, 0xffff0000, v158
	v_pk_mul_f32 v[64:65], v[64:65], v[44:45]
	v_pk_fma_f32 v[64:65], v[64:65], v[22:23], v[184:185]
	v_cvt_pk_bf16_f32 v158, v64, v65
	v_lshlrev_b32_e32 v66, 16, v159
	v_and_b32_e32 v67, 0xffff0000, v159
	v_pk_mul_f32 v[66:67], v[66:67], v[44:45]
	v_pk_fma_f32 v[66:67], v[66:67], v[24:25], v[186:187]
	v_cvt_pk_bf16_f32 v159, v66, v67
	v_lshlrev_b32_e32 v60, 16, v160
	v_and_b32_e32 v61, 0xffff0000, v160
	v_pk_mul_f32 v[60:61], v[60:61], v[44:45]
	v_pk_fma_f32 v[60:61], v[60:61], v[26:27], v[188:189]
	v_cvt_pk_bf16_f32 v160, v60, v61
	v_lshlrev_b32_e32 v62, 16, v161
	v_and_b32_e32 v63, 0xffff0000, v161
	v_pk_mul_f32 v[62:63], v[62:63], v[44:45]
	v_pk_fma_f32 v[62:63], v[62:63], v[28:29], v[190:191]
	v_cvt_pk_bf16_f32 v161, v62, v63
	v_lshlrev_b32_e32 v64, 16, v162
	v_and_b32_e32 v65, 0xffff0000, v162
	v_pk_mul_f32 v[64:65], v[64:65], v[44:45]
	v_pk_fma_f32 v[64:65], v[64:65], v[30:31], v[192:193]
	v_cvt_pk_bf16_f32 v162, v64, v65
	v_lshlrev_b32_e32 v66, 16, v163
	v_and_b32_e32 v67, 0xffff0000, v163
	v_pk_mul_f32 v[66:67], v[66:67], v[44:45]
	v_pk_fma_f32 v[66:67], v[66:67], v[32:33], v[194:195]
	v_cvt_pk_bf16_f32 v163, v66, v67
	global_store_dwordx4 v39, v[148:151], s[20:21]
	global_store_dwordx4 v39, v[152:155], s[20:21] offset:1024
	global_store_dwordx4 v39, v[156:159], s[20:21] offset:2048
	global_store_dwordx4 v39, v[160:163], s[20:21] offset:3072
	s_add_u32 s20, s20, 0x1000
	s_addc_u32 s21, s21, 0
	global_load_dwordx4 v[148:151], v39, s[10:11]
	global_load_dwordx4 v[152:155], v39, s[10:11] offset:1024
	global_load_dwordx4 v[156:159], v39, s[10:11] offset:2048
	global_load_dwordx4 v[160:163], v39, s[10:11] offset:3072
	s_add_u32 s10, s10, 0x1000
	s_addc_u32 s11, s11, 0
	s_waitcnt vmcnt(24)
	v_lshlrev_b32_e32 v60, 16, v100
	v_and_b32_e32 v61, 0xffff0000, v100
	v_pk_mul_f32 v[42:43], v[60:61], v[60:61]
	v_lshlrev_b32_e32 v62, 16, v101
	v_and_b32_e32 v63, 0xffff0000, v101
	v_pk_fma_f32 v[42:43], v[62:63], v[62:63], v[42:43]
	v_lshlrev_b32_e32 v64, 16, v102
	v_and_b32_e32 v65, 0xffff0000, v102
	v_pk_fma_f32 v[42:43], v[64:65], v[64:65], v[42:43]
	v_lshlrev_b32_e32 v66, 16, v103
	v_and_b32_e32 v67, 0xffff0000, v103
	v_pk_fma_f32 v[42:43], v[66:67], v[66:67], v[42:43]
	v_lshlrev_b32_e32 v60, 16, v104
	v_and_b32_e32 v61, 0xffff0000, v104
	v_pk_fma_f32 v[42:43], v[60:61], v[60:61], v[42:43]
	v_lshlrev_b32_e32 v62, 16, v105
	v_and_b32_e32 v63, 0xffff0000, v105
	v_pk_fma_f32 v[42:43], v[62:63], v[62:63], v[42:43]
	v_lshlrev_b32_e32 v64, 16, v106
	v_and_b32_e32 v65, 0xffff0000, v106
	v_pk_fma_f32 v[42:43], v[64:65], v[64:65], v[42:43]
	v_lshlrev_b32_e32 v66, 16, v107
	v_and_b32_e32 v67, 0xffff0000, v107
	v_pk_fma_f32 v[42:43], v[66:67], v[66:67], v[42:43]
	v_lshlrev_b32_e32 v60, 16, v108
	v_and_b32_e32 v61, 0xffff0000, v108
	v_pk_fma_f32 v[42:43], v[60:61], v[60:61], v[42:43]
	v_lshlrev_b32_e32 v62, 16, v109
	v_and_b32_e32 v63, 0xffff0000, v109
	v_pk_fma_f32 v[42:43], v[62:63], v[62:63], v[42:43]
	v_lshlrev_b32_e32 v64, 16, v110
	v_and_b32_e32 v65, 0xffff0000, v110
	v_pk_fma_f32 v[42:43], v[64:65], v[64:65], v[42:43]
	v_lshlrev_b32_e32 v66, 16, v111
	v_and_b32_e32 v67, 0xffff0000, v111
	v_pk_fma_f32 v[42:43], v[66:67], v[66:67], v[42:43]
	v_lshlrev_b32_e32 v60, 16, v112
	v_and_b32_e32 v61, 0xffff0000, v112
	v_pk_fma_f32 v[42:43], v[60:61], v[60:61], v[42:43]
	v_lshlrev_b32_e32 v62, 16, v113
	v_and_b32_e32 v63, 0xffff0000, v113
	v_pk_fma_f32 v[42:43], v[62:63], v[62:63], v[42:43]
	v_lshlrev_b32_e32 v64, 16, v114
	v_and_b32_e32 v65, 0xffff0000, v114
	v_pk_fma_f32 v[42:43], v[64:65], v[64:65], v[42:43]
	v_lshlrev_b32_e32 v66, 16, v115
	v_and_b32_e32 v67, 0xffff0000, v115
	v_pk_fma_f32 v[42:43], v[66:67], v[66:67], v[42:43]
	v_add_f32_e32 v42, v42, v43
	s_nop 1
	v_add_f32_dpp v42, v42, v42 quad_perm:[1,0,3,2] row_mask:0xf bank_mask:0xf
	s_nop 1
	v_add_f32_dpp v42, v42, v42 quad_perm:[2,3,0,1] row_mask:0xf bank_mask:0xf
	s_nop 1
	v_add_f32_dpp v42, v42, v42 row_half_mirror row_mask:0xf bank_mask:0xf
	s_nop 1
	v_add_f32_dpp v42, v42, v42 row_mirror row_mask:0xf bank_mask:0xf
	s_nop 1
	v_add_f32_dpp v42, v42, v42 row_bcast:15 row_mask:0xa bank_mask:0xf
	s_nop 1
	v_add_f32_dpp v42, v42, v42 row_bcast:31 row_mask:0xc bank_mask:0xf
	s_nop 1
	v_readlane_b32 s100, v42, 63
	s_nop 3
	v_mov_b32_e32 v44, s100
	v_fma_f32 v44, v44, v47, v224
	v_rsq_f32_e32 v45, v44
	s_nop 0
	v_mul_f32_e32 v46, v44, v45
	v_mul_f32_e32 v46, v46, v45
	v_fmaak_f32 v46, -0.5, v46, 0x3fc00000
	v_mul_f32_e32 v44, v45, v46
	v_mov_b32_e32 v45, v44
	v_lshlrev_b32_e32 v60, 16, v100
	v_and_b32_e32 v61, 0xffff0000, v100
	v_pk_mul_f32 v[60:61], v[60:61], v[44:45]
	v_pk_fma_f32 v[60:61], v[60:61], v[2:3], v[164:165]
	v_cvt_pk_bf16_f32 v100, v60, v61
	v_lshlrev_b32_e32 v62, 16, v101
	v_and_b32_e32 v63, 0xffff0000, v101
	v_pk_mul_f32 v[62:63], v[62:63], v[44:45]
	v_pk_fma_f32 v[62:63], v[62:63], v[4:5], v[166:167]
	v_cvt_pk_bf16_f32 v101, v62, v63
	v_lshlrev_b32_e32 v64, 16, v102
	v_and_b32_e32 v65, 0xffff0000, v102
	v_pk_mul_f32 v[64:65], v[64:65], v[44:45]
	v_pk_fma_f32 v[64:65], v[64:65], v[6:7], v[168:169]
	v_cvt_pk_bf16_f32 v102, v64, v65
	v_lshlrev_b32_e32 v66, 16, v103
	v_and_b32_e32 v67, 0xffff0000, v103
	v_pk_mul_f32 v[66:67], v[66:67], v[44:45]
	v_pk_fma_f32 v[66:67], v[66:67], v[8:9], v[170:171]
	v_cvt_pk_bf16_f32 v103, v66, v67
	v_lshlrev_b32_e32 v60, 16, v104
	v_and_b32_e32 v61, 0xffff0000, v104
	v_pk_mul_f32 v[60:61], v[60:61], v[44:45]
	v_pk_fma_f32 v[60:61], v[60:61], v[10:11], v[172:173]
	v_cvt_pk_bf16_f32 v104, v60, v61
	v_lshlrev_b32_e32 v62, 16, v105
	v_and_b32_e32 v63, 0xffff0000, v105
	v_pk_mul_f32 v[62:63], v[62:63], v[44:45]
	v_pk_fma_f32 v[62:63], v[62:63], v[12:13], v[174:175]
	v_cvt_pk_bf16_f32 v105, v62, v63
	v_lshlrev_b32_e32 v64, 16, v106
	v_and_b32_e32 v65, 0xffff0000, v106
	v_pk_mul_f32 v[64:65], v[64:65], v[44:45]
	v_pk_fma_f32 v[64:65], v[64:65], v[14:15], v[176:177]
	v_cvt_pk_bf16_f32 v106, v64, v65
	v_lshlrev_b32_e32 v66, 16, v107
	v_and_b32_e32 v67, 0xffff0000, v107
	v_pk_mul_f32 v[66:67], v[66:67], v[44:45]
	v_pk_fma_f32 v[66:67], v[66:67], v[16:17], v[178:179]
	v_cvt_pk_bf16_f32 v107, v66, v67
	v_lshlrev_b32_e32 v60, 16, v108
	v_and_b32_e32 v61, 0xffff0000, v108
	v_pk_mul_f32 v[60:61], v[60:61], v[44:45]
	v_pk_fma_f32 v[60:61], v[60:61], v[18:19], v[180:181]
	v_cvt_pk_bf16_f32 v108, v60, v61
	v_lshlrev_b32_e32 v62, 16, v109
	v_and_b32_e32 v63, 0xffff0000, v109
	v_pk_mul_f32 v[62:63], v[62:63], v[44:45]
	v_pk_fma_f32 v[62:63], v[62:63], v[20:21], v[182:183]
	v_cvt_pk_bf16_f32 v109, v62, v63
	v_lshlrev_b32_e32 v64, 16, v110
	v_and_b32_e32 v65, 0xffff0000, v110
	v_pk_mul_f32 v[64:65], v[64:65], v[44:45]
	v_pk_fma_f32 v[64:65], v[64:65], v[22:23], v[184:185]
	v_cvt_pk_bf16_f32 v110, v64, v65
	v_lshlrev_b32_e32 v66, 16, v111
	v_and_b32_e32 v67, 0xffff0000, v111
	v_pk_mul_f32 v[66:67], v[66:67], v[44:45]
	v_pk_fma_f32 v[66:67], v[66:67], v[24:25], v[186:187]
	v_cvt_pk_bf16_f32 v111, v66, v67
	v_lshlrev_b32_e32 v60, 16, v112
	v_and_b32_e32 v61, 0xffff0000, v112
	v_pk_mul_f32 v[60:61], v[60:61], v[44:45]
	v_pk_fma_f32 v[60:61], v[60:61], v[26:27], v[188:189]
	v_cvt_pk_bf16_f32 v112, v60, v61
	v_lshlrev_b32_e32 v62, 16, v113
	v_and_b32_e32 v63, 0xffff0000, v113
	v_pk_mul_f32 v[62:63], v[62:63], v[44:45]
	v_pk_fma_f32 v[62:63], v[62:63], v[28:29], v[190:191]
	v_cvt_pk_bf16_f32 v113, v62, v63
	v_lshlrev_b32_e32 v64, 16, v114
	v_and_b32_e32 v65, 0xffff0000, v114
	v_pk_mul_f32 v[64:65], v[64:65], v[44:45]
	v_pk_fma_f32 v[64:65], v[64:65], v[30:31], v[192:193]
	v_cvt_pk_bf16_f32 v114, v64, v65
	v_lshlrev_b32_e32 v66, 16, v115
	v_and_b32_e32 v67, 0xffff0000, v115
	v_pk_mul_f32 v[66:67], v[66:67], v[44:45]
	v_pk_fma_f32 v[66:67], v[66:67], v[32:33], v[194:195]
	v_cvt_pk_bf16_f32 v115, v66, v67
	global_store_dwordx4 v39, v[100:103], s[20:21]
	global_store_dwordx4 v39, v[104:107], s[20:21] offset:1024
	global_store_dwordx4 v39, v[108:111], s[20:21] offset:2048
	global_store_dwordx4 v39, v[112:115], s[20:21] offset:3072
	s_add_u32 s20, s20, 0x1000
	s_addc_u32 s21, s21, 0
	s_waitcnt vmcnt(20)
	v_lshlrev_b32_e32 v60, 16, v116
	v_and_b32_e32 v61, 0xffff0000, v116
	v_pk_mul_f32 v[42:43], v[60:61], v[60:61]
	v_lshlrev_b32_e32 v62, 16, v117
	v_and_b32_e32 v63, 0xffff0000, v117
	v_pk_fma_f32 v[42:43], v[62:63], v[62:63], v[42:43]
	v_lshlrev_b32_e32 v64, 16, v118
	v_and_b32_e32 v65, 0xffff0000, v118
	v_pk_fma_f32 v[42:43], v[64:65], v[64:65], v[42:43]
	v_lshlrev_b32_e32 v66, 16, v119
	v_and_b32_e32 v67, 0xffff0000, v119
	v_pk_fma_f32 v[42:43], v[66:67], v[66:67], v[42:43]
	v_lshlrev_b32_e32 v60, 16, v120
	v_and_b32_e32 v61, 0xffff0000, v120
	v_pk_fma_f32 v[42:43], v[60:61], v[60:61], v[42:43]
	v_lshlrev_b32_e32 v62, 16, v121
	v_and_b32_e32 v63, 0xffff0000, v121
	v_pk_fma_f32 v[42:43], v[62:63], v[62:63], v[42:43]
	v_lshlrev_b32_e32 v64, 16, v122
	v_and_b32_e32 v65, 0xffff0000, v122
	v_pk_fma_f32 v[42:43], v[64:65], v[64:65], v[42:43]
	v_lshlrev_b32_e32 v66, 16, v123
	v_and_b32_e32 v67, 0xffff0000, v123
	v_pk_fma_f32 v[42:43], v[66:67], v[66:67], v[42:43]
	v_lshlrev_b32_e32 v60, 16, v124
	v_and_b32_e32 v61, 0xffff0000, v124
	v_pk_fma_f32 v[42:43], v[60:61], v[60:61], v[42:43]
	v_lshlrev_b32_e32 v62, 16, v125
	v_and_b32_e32 v63, 0xffff0000, v125
	v_pk_fma_f32 v[42:43], v[62:63], v[62:63], v[42:43]
	v_lshlrev_b32_e32 v64, 16, v126
	v_and_b32_e32 v65, 0xffff0000, v126
	v_pk_fma_f32 v[42:43], v[64:65], v[64:65], v[42:43]
	v_lshlrev_b32_e32 v66, 16, v127
	v_and_b32_e32 v67, 0xffff0000, v127
	v_pk_fma_f32 v[42:43], v[66:67], v[66:67], v[42:43]
	v_lshlrev_b32_e32 v60, 16, v128
	v_and_b32_e32 v61, 0xffff0000, v128
	v_pk_fma_f32 v[42:43], v[60:61], v[60:61], v[42:43]
	v_lshlrev_b32_e32 v62, 16, v129
	v_and_b32_e32 v63, 0xffff0000, v129
	v_pk_fma_f32 v[42:43], v[62:63], v[62:63], v[42:43]
	v_lshlrev_b32_e32 v64, 16, v130
	v_and_b32_e32 v65, 0xffff0000, v130
	v_pk_fma_f32 v[42:43], v[64:65], v[64:65], v[42:43]
	v_lshlrev_b32_e32 v66, 16, v131
	v_and_b32_e32 v67, 0xffff0000, v131
	v_pk_fma_f32 v[42:43], v[66:67], v[66:67], v[42:43]
	v_add_f32_e32 v42, v42, v43
	s_nop 1
	v_add_f32_dpp v42, v42, v42 quad_perm:[1,0,3,2] row_mask:0xf bank_mask:0xf
	s_nop 1
	v_add_f32_dpp v42, v42, v42 quad_perm:[2,3,0,1] row_mask:0xf bank_mask:0xf
	s_nop 1
	v_add_f32_dpp v42, v42, v42 row_half_mirror row_mask:0xf bank_mask:0xf
	s_nop 1
	v_add_f32_dpp v42, v42, v42 row_mirror row_mask:0xf bank_mask:0xf
	s_nop 1
	v_add_f32_dpp v42, v42, v42 row_bcast:15 row_mask:0xa bank_mask:0xf
	s_nop 1
	v_add_f32_dpp v42, v42, v42 row_bcast:31 row_mask:0xc bank_mask:0xf
	s_nop 1
	v_readlane_b32 s100, v42, 63
	s_nop 3
	v_mov_b32_e32 v44, s100
	v_fma_f32 v44, v44, v47, v224
	v_rsq_f32_e32 v45, v44
	s_nop 0
	v_mul_f32_e32 v46, v44, v45
	v_mul_f32_e32 v46, v46, v45
	v_fmaak_f32 v46, -0.5, v46, 0x3fc00000
	v_mul_f32_e32 v44, v45, v46
	v_mov_b32_e32 v45, v44
	v_lshlrev_b32_e32 v60, 16, v116
	v_and_b32_e32 v61, 0xffff0000, v116
	v_pk_mul_f32 v[60:61], v[60:61], v[44:45]
	v_pk_fma_f32 v[60:61], v[60:61], v[2:3], v[164:165]
	v_cvt_pk_bf16_f32 v116, v60, v61
	v_lshlrev_b32_e32 v62, 16, v117
	v_and_b32_e32 v63, 0xffff0000, v117
	v_pk_mul_f32 v[62:63], v[62:63], v[44:45]
	v_pk_fma_f32 v[62:63], v[62:63], v[4:5], v[166:167]
	v_cvt_pk_bf16_f32 v117, v62, v63
	v_lshlrev_b32_e32 v64, 16, v118
	v_and_b32_e32 v65, 0xffff0000, v118
	v_pk_mul_f32 v[64:65], v[64:65], v[44:45]
	v_pk_fma_f32 v[64:65], v[64:65], v[6:7], v[168:169]
	v_cvt_pk_bf16_f32 v118, v64, v65
	v_lshlrev_b32_e32 v66, 16, v119
	v_and_b32_e32 v67, 0xffff0000, v119
	v_pk_mul_f32 v[66:67], v[66:67], v[44:45]
	v_pk_fma_f32 v[66:67], v[66:67], v[8:9], v[170:171]
	v_cvt_pk_bf16_f32 v119, v66, v67
	v_lshlrev_b32_e32 v60, 16, v120
	v_and_b32_e32 v61, 0xffff0000, v120
	v_pk_mul_f32 v[60:61], v[60:61], v[44:45]
	v_pk_fma_f32 v[60:61], v[60:61], v[10:11], v[172:173]
	v_cvt_pk_bf16_f32 v120, v60, v61
	v_lshlrev_b32_e32 v62, 16, v121
	v_and_b32_e32 v63, 0xffff0000, v121
	v_pk_mul_f32 v[62:63], v[62:63], v[44:45]
	v_pk_fma_f32 v[62:63], v[62:63], v[12:13], v[174:175]
	v_cvt_pk_bf16_f32 v121, v62, v63
	v_lshlrev_b32_e32 v64, 16, v122
	v_and_b32_e32 v65, 0xffff0000, v122
	v_pk_mul_f32 v[64:65], v[64:65], v[44:45]
	v_pk_fma_f32 v[64:65], v[64:65], v[14:15], v[176:177]
	v_cvt_pk_bf16_f32 v122, v64, v65
	v_lshlrev_b32_e32 v66, 16, v123
	v_and_b32_e32 v67, 0xffff0000, v123
	v_pk_mul_f32 v[66:67], v[66:67], v[44:45]
	v_pk_fma_f32 v[66:67], v[66:67], v[16:17], v[178:179]
	v_cvt_pk_bf16_f32 v123, v66, v67
	v_lshlrev_b32_e32 v60, 16, v124
	v_and_b32_e32 v61, 0xffff0000, v124
	v_pk_mul_f32 v[60:61], v[60:61], v[44:45]
	v_pk_fma_f32 v[60:61], v[60:61], v[18:19], v[180:181]
	v_cvt_pk_bf16_f32 v124, v60, v61
	v_lshlrev_b32_e32 v62, 16, v125
	v_and_b32_e32 v63, 0xffff0000, v125
	v_pk_mul_f32 v[62:63], v[62:63], v[44:45]
	v_pk_fma_f32 v[62:63], v[62:63], v[20:21], v[182:183]
	v_cvt_pk_bf16_f32 v125, v62, v63
	v_lshlrev_b32_e32 v64, 16, v126
	v_and_b32_e32 v65, 0xffff0000, v126
	v_pk_mul_f32 v[64:65], v[64:65], v[44:45]
	v_pk_fma_f32 v[64:65], v[64:65], v[22:23], v[184:185]
	v_cvt_pk_bf16_f32 v126, v64, v65
	v_lshlrev_b32_e32 v66, 16, v127
	v_and_b32_e32 v67, 0xffff0000, v127
	v_pk_mul_f32 v[66:67], v[66:67], v[44:45]
	v_pk_fma_f32 v[66:67], v[66:67], v[24:25], v[186:187]
	v_cvt_pk_bf16_f32 v127, v66, v67
	v_lshlrev_b32_e32 v60, 16, v128
	v_and_b32_e32 v61, 0xffff0000, v128
	v_pk_mul_f32 v[60:61], v[60:61], v[44:45]
	v_pk_fma_f32 v[60:61], v[60:61], v[26:27], v[188:189]
	v_cvt_pk_bf16_f32 v128, v60, v61
	v_lshlrev_b32_e32 v62, 16, v129
	v_and_b32_e32 v63, 0xffff0000, v129
	v_pk_mul_f32 v[62:63], v[62:63], v[44:45]
	v_pk_fma_f32 v[62:63], v[62:63], v[28:29], v[190:191]
	v_cvt_pk_bf16_f32 v129, v62, v63
	v_lshlrev_b32_e32 v64, 16, v130
	v_and_b32_e32 v65, 0xffff0000, v130
	v_pk_mul_f32 v[64:65], v[64:65], v[44:45]
	v_pk_fma_f32 v[64:65], v[64:65], v[30:31], v[192:193]
	v_cvt_pk_bf16_f32 v130, v64, v65
	v_lshlrev_b32_e32 v66, 16, v131
	v_and_b32_e32 v67, 0xffff0000, v131
	v_pk_mul_f32 v[66:67], v[66:67], v[44:45]
	v_pk_fma_f32 v[66:67], v[66:67], v[32:33], v[194:195]
	v_cvt_pk_bf16_f32 v131, v66, v67
	global_store_dwordx4 v39, v[116:119], s[20:21]
	global_store_dwordx4 v39, v[120:123], s[20:21] offset:1024
	global_store_dwordx4 v39, v[124:127], s[20:21] offset:2048
	global_store_dwordx4 v39, v[128:131], s[20:21] offset:3072
	s_add_u32 s20, s20, 0x1000
	s_addc_u32 s21, s21, 0
	s_waitcnt vmcnt(16)
	v_lshlrev_b32_e32 v60, 16, v132
	v_and_b32_e32 v61, 0xffff0000, v132
	v_pk_mul_f32 v[42:43], v[60:61], v[60:61]
	v_lshlrev_b32_e32 v62, 16, v133
	v_and_b32_e32 v63, 0xffff0000, v133
	v_pk_fma_f32 v[42:43], v[62:63], v[62:63], v[42:43]
	v_lshlrev_b32_e32 v64, 16, v134
	v_and_b32_e32 v65, 0xffff0000, v134
	v_pk_fma_f32 v[42:43], v[64:65], v[64:65], v[42:43]
	v_lshlrev_b32_e32 v66, 16, v135
	v_and_b32_e32 v67, 0xffff0000, v135
	v_pk_fma_f32 v[42:43], v[66:67], v[66:67], v[42:43]
	v_lshlrev_b32_e32 v60, 16, v136
	v_and_b32_e32 v61, 0xffff0000, v136
	v_pk_fma_f32 v[42:43], v[60:61], v[60:61], v[42:43]
	v_lshlrev_b32_e32 v62, 16, v137
	v_and_b32_e32 v63, 0xffff0000, v137
	v_pk_fma_f32 v[42:43], v[62:63], v[62:63], v[42:43]
	v_lshlrev_b32_e32 v64, 16, v138
	v_and_b32_e32 v65, 0xffff0000, v138
	v_pk_fma_f32 v[42:43], v[64:65], v[64:65], v[42:43]
	v_lshlrev_b32_e32 v66, 16, v139
	v_and_b32_e32 v67, 0xffff0000, v139
	v_pk_fma_f32 v[42:43], v[66:67], v[66:67], v[42:43]
	v_lshlrev_b32_e32 v60, 16, v140
	v_and_b32_e32 v61, 0xffff0000, v140
	v_pk_fma_f32 v[42:43], v[60:61], v[60:61], v[42:43]
	v_lshlrev_b32_e32 v62, 16, v141
	v_and_b32_e32 v63, 0xffff0000, v141
	v_pk_fma_f32 v[42:43], v[62:63], v[62:63], v[42:43]
	v_lshlrev_b32_e32 v64, 16, v142
	v_and_b32_e32 v65, 0xffff0000, v142
	v_pk_fma_f32 v[42:43], v[64:65], v[64:65], v[42:43]
	v_lshlrev_b32_e32 v66, 16, v143
	v_and_b32_e32 v67, 0xffff0000, v143
	v_pk_fma_f32 v[42:43], v[66:67], v[66:67], v[42:43]
	v_lshlrev_b32_e32 v60, 16, v144
	v_and_b32_e32 v61, 0xffff0000, v144
	v_pk_fma_f32 v[42:43], v[60:61], v[60:61], v[42:43]
	v_lshlrev_b32_e32 v62, 16, v145
	v_and_b32_e32 v63, 0xffff0000, v145
	v_pk_fma_f32 v[42:43], v[62:63], v[62:63], v[42:43]
	v_lshlrev_b32_e32 v64, 16, v146
	v_and_b32_e32 v65, 0xffff0000, v146
	v_pk_fma_f32 v[42:43], v[64:65], v[64:65], v[42:43]
	v_lshlrev_b32_e32 v66, 16, v147
	v_and_b32_e32 v67, 0xffff0000, v147
	v_pk_fma_f32 v[42:43], v[66:67], v[66:67], v[42:43]
	v_add_f32_e32 v42, v42, v43
	s_nop 1
	v_add_f32_dpp v42, v42, v42 quad_perm:[1,0,3,2] row_mask:0xf bank_mask:0xf
	s_nop 1
	v_add_f32_dpp v42, v42, v42 quad_perm:[2,3,0,1] row_mask:0xf bank_mask:0xf
	s_nop 1
	v_add_f32_dpp v42, v42, v42 row_half_mirror row_mask:0xf bank_mask:0xf
	s_nop 1
	v_add_f32_dpp v42, v42, v42 row_mirror row_mask:0xf bank_mask:0xf
	s_nop 1
	v_add_f32_dpp v42, v42, v42 row_bcast:15 row_mask:0xa bank_mask:0xf
	s_nop 1
	v_add_f32_dpp v42, v42, v42 row_bcast:31 row_mask:0xc bank_mask:0xf
	s_nop 1
	v_readlane_b32 s100, v42, 63
	s_nop 3
	v_mov_b32_e32 v44, s100
	v_fma_f32 v44, v44, v47, v224
	v_rsq_f32_e32 v45, v44
	s_nop 0
	v_mul_f32_e32 v46, v44, v45
	v_mul_f32_e32 v46, v46, v45
	v_fmaak_f32 v46, -0.5, v46, 0x3fc00000
	v_mul_f32_e32 v44, v45, v46
	v_mov_b32_e32 v45, v44
	v_lshlrev_b32_e32 v60, 16, v132
	v_and_b32_e32 v61, 0xffff0000, v132
	v_pk_mul_f32 v[60:61], v[60:61], v[44:45]
	v_pk_fma_f32 v[60:61], v[60:61], v[2:3], v[164:165]
	v_cvt_pk_bf16_f32 v132, v60, v61
	v_lshlrev_b32_e32 v62, 16, v133
	v_and_b32_e32 v63, 0xffff0000, v133
	v_pk_mul_f32 v[62:63], v[62:63], v[44:45]
	v_pk_fma_f32 v[62:63], v[62:63], v[4:5], v[166:167]
	v_cvt_pk_bf16_f32 v133, v62, v63
	v_lshlrev_b32_e32 v64, 16, v134
	v_and_b32_e32 v65, 0xffff0000, v134
	v_pk_mul_f32 v[64:65], v[64:65], v[44:45]
	v_pk_fma_f32 v[64:65], v[64:65], v[6:7], v[168:169]
	v_cvt_pk_bf16_f32 v134, v64, v65
	v_lshlrev_b32_e32 v66, 16, v135
	v_and_b32_e32 v67, 0xffff0000, v135
	v_pk_mul_f32 v[66:67], v[66:67], v[44:45]
	v_pk_fma_f32 v[66:67], v[66:67], v[8:9], v[170:171]
	v_cvt_pk_bf16_f32 v135, v66, v67
	v_lshlrev_b32_e32 v60, 16, v136
	v_and_b32_e32 v61, 0xffff0000, v136
	v_pk_mul_f32 v[60:61], v[60:61], v[44:45]
	v_pk_fma_f32 v[60:61], v[60:61], v[10:11], v[172:173]
	v_cvt_pk_bf16_f32 v136, v60, v61
	v_lshlrev_b32_e32 v62, 16, v137
	v_and_b32_e32 v63, 0xffff0000, v137
	v_pk_mul_f32 v[62:63], v[62:63], v[44:45]
	v_pk_fma_f32 v[62:63], v[62:63], v[12:13], v[174:175]
	v_cvt_pk_bf16_f32 v137, v62, v63
	v_lshlrev_b32_e32 v64, 16, v138
	v_and_b32_e32 v65, 0xffff0000, v138
	v_pk_mul_f32 v[64:65], v[64:65], v[44:45]
	v_pk_fma_f32 v[64:65], v[64:65], v[14:15], v[176:177]
	v_cvt_pk_bf16_f32 v138, v64, v65
	v_lshlrev_b32_e32 v66, 16, v139
	v_and_b32_e32 v67, 0xffff0000, v139
	v_pk_mul_f32 v[66:67], v[66:67], v[44:45]
	v_pk_fma_f32 v[66:67], v[66:67], v[16:17], v[178:179]
	v_cvt_pk_bf16_f32 v139, v66, v67
	v_lshlrev_b32_e32 v60, 16, v140
	v_and_b32_e32 v61, 0xffff0000, v140
	v_pk_mul_f32 v[60:61], v[60:61], v[44:45]
	v_pk_fma_f32 v[60:61], v[60:61], v[18:19], v[180:181]
	v_cvt_pk_bf16_f32 v140, v60, v61
	v_lshlrev_b32_e32 v62, 16, v141
	v_and_b32_e32 v63, 0xffff0000, v141
	v_pk_mul_f32 v[62:63], v[62:63], v[44:45]
	v_pk_fma_f32 v[62:63], v[62:63], v[20:21], v[182:183]
	v_cvt_pk_bf16_f32 v141, v62, v63
	v_lshlrev_b32_e32 v64, 16, v142
	v_and_b32_e32 v65, 0xffff0000, v142
	v_pk_mul_f32 v[64:65], v[64:65], v[44:45]
	v_pk_fma_f32 v[64:65], v[64:65], v[22:23], v[184:185]
	v_cvt_pk_bf16_f32 v142, v64, v65
	v_lshlrev_b32_e32 v66, 16, v143
	v_and_b32_e32 v67, 0xffff0000, v143
	v_pk_mul_f32 v[66:67], v[66:67], v[44:45]
	v_pk_fma_f32 v[66:67], v[66:67], v[24:25], v[186:187]
	v_cvt_pk_bf16_f32 v143, v66, v67
	v_lshlrev_b32_e32 v60, 16, v144
	v_and_b32_e32 v61, 0xffff0000, v144
	v_pk_mul_f32 v[60:61], v[60:61], v[44:45]
	v_pk_fma_f32 v[60:61], v[60:61], v[26:27], v[188:189]
	v_cvt_pk_bf16_f32 v144, v60, v61
	v_lshlrev_b32_e32 v62, 16, v145
	v_and_b32_e32 v63, 0xffff0000, v145
	v_pk_mul_f32 v[62:63], v[62:63], v[44:45]
	v_pk_fma_f32 v[62:63], v[62:63], v[28:29], v[190:191]
	v_cvt_pk_bf16_f32 v145, v62, v63
	v_lshlrev_b32_e32 v64, 16, v146
	v_and_b32_e32 v65, 0xffff0000, v146
	v_pk_mul_f32 v[64:65], v[64:65], v[44:45]
	v_pk_fma_f32 v[64:65], v[64:65], v[30:31], v[192:193]
	v_cvt_pk_bf16_f32 v146, v64, v65
	v_lshlrev_b32_e32 v66, 16, v147
	v_and_b32_e32 v67, 0xffff0000, v147
	v_pk_mul_f32 v[66:67], v[66:67], v[44:45]
	v_pk_fma_f32 v[66:67], v[66:67], v[32:33], v[194:195]
	v_cvt_pk_bf16_f32 v147, v66, v67
	global_store_dwordx4 v39, v[132:135], s[20:21]
	global_store_dwordx4 v39, v[136:139], s[20:21] offset:1024
	global_store_dwordx4 v39, v[140:143], s[20:21] offset:2048
	global_store_dwordx4 v39, v[144:147], s[20:21] offset:3072
	s_add_u32 s20, s20, 0x1000
	s_addc_u32 s21, s21, 0
	s_waitcnt vmcnt(12)
	v_lshlrev_b32_e32 v60, 16, v148
	v_and_b32_e32 v61, 0xffff0000, v148
	v_pk_mul_f32 v[42:43], v[60:61], v[60:61]
	v_lshlrev_b32_e32 v62, 16, v149
	v_and_b32_e32 v63, 0xffff0000, v149
	v_pk_fma_f32 v[42:43], v[62:63], v[62:63], v[42:43]
	v_lshlrev_b32_e32 v64, 16, v150
	v_and_b32_e32 v65, 0xffff0000, v150
	v_pk_fma_f32 v[42:43], v[64:65], v[64:65], v[42:43]
	v_lshlrev_b32_e32 v66, 16, v151
	v_and_b32_e32 v67, 0xffff0000, v151
	v_pk_fma_f32 v[42:43], v[66:67], v[66:67], v[42:43]
	v_lshlrev_b32_e32 v60, 16, v152
	v_and_b32_e32 v61, 0xffff0000, v152
	v_pk_fma_f32 v[42:43], v[60:61], v[60:61], v[42:43]
	v_lshlrev_b32_e32 v62, 16, v153
	v_and_b32_e32 v63, 0xffff0000, v153
	v_pk_fma_f32 v[42:43], v[62:63], v[62:63], v[42:43]
	v_lshlrev_b32_e32 v64, 16, v154
	v_and_b32_e32 v65, 0xffff0000, v154
	v_pk_fma_f32 v[42:43], v[64:65], v[64:65], v[42:43]
	v_lshlrev_b32_e32 v66, 16, v155
	v_and_b32_e32 v67, 0xffff0000, v155
	v_pk_fma_f32 v[42:43], v[66:67], v[66:67], v[42:43]
	v_lshlrev_b32_e32 v60, 16, v156
	v_and_b32_e32 v61, 0xffff0000, v156
	v_pk_fma_f32 v[42:43], v[60:61], v[60:61], v[42:43]
	v_lshlrev_b32_e32 v62, 16, v157
	v_and_b32_e32 v63, 0xffff0000, v157
	v_pk_fma_f32 v[42:43], v[62:63], v[62:63], v[42:43]
	v_lshlrev_b32_e32 v64, 16, v158
	v_and_b32_e32 v65, 0xffff0000, v158
	v_pk_fma_f32 v[42:43], v[64:65], v[64:65], v[42:43]
	v_lshlrev_b32_e32 v66, 16, v159
	v_and_b32_e32 v67, 0xffff0000, v159
	v_pk_fma_f32 v[42:43], v[66:67], v[66:67], v[42:43]
	v_lshlrev_b32_e32 v60, 16, v160
	v_and_b32_e32 v61, 0xffff0000, v160
	v_pk_fma_f32 v[42:43], v[60:61], v[60:61], v[42:43]
	v_lshlrev_b32_e32 v62, 16, v161
	v_and_b32_e32 v63, 0xffff0000, v161
	v_pk_fma_f32 v[42:43], v[62:63], v[62:63], v[42:43]
	v_lshlrev_b32_e32 v64, 16, v162
	v_and_b32_e32 v65, 0xffff0000, v162
	v_pk_fma_f32 v[42:43], v[64:65], v[64:65], v[42:43]
	v_lshlrev_b32_e32 v66, 16, v163
	v_and_b32_e32 v67, 0xffff0000, v163
	v_pk_fma_f32 v[42:43], v[66:67], v[66:67], v[42:43]
	v_add_f32_e32 v42, v42, v43
	s_nop 1
	v_add_f32_dpp v42, v42, v42 quad_perm:[1,0,3,2] row_mask:0xf bank_mask:0xf
	s_nop 1
	v_add_f32_dpp v42, v42, v42 quad_perm:[2,3,0,1] row_mask:0xf bank_mask:0xf
	s_nop 1
	v_add_f32_dpp v42, v42, v42 row_half_mirror row_mask:0xf bank_mask:0xf
	s_nop 1
	v_add_f32_dpp v42, v42, v42 row_mirror row_mask:0xf bank_mask:0xf
	s_nop 1
	v_add_f32_dpp v42, v42, v42 row_bcast:15 row_mask:0xa bank_mask:0xf
	s_nop 1
	v_add_f32_dpp v42, v42, v42 row_bcast:31 row_mask:0xc bank_mask:0xf
	s_nop 1
	v_readlane_b32 s100, v42, 63
	s_nop 3
	v_mov_b32_e32 v44, s100
	v_fma_f32 v44, v44, v47, v224
	v_rsq_f32_e32 v45, v44
	s_nop 0
	v_mul_f32_e32 v46, v44, v45
	v_mul_f32_e32 v46, v46, v45
	v_fmaak_f32 v46, -0.5, v46, 0x3fc00000
	v_mul_f32_e32 v44, v45, v46
	v_mov_b32_e32 v45, v44
	v_lshlrev_b32_e32 v60, 16, v148
	v_and_b32_e32 v61, 0xffff0000, v148
	v_pk_mul_f32 v[60:61], v[60:61], v[44:45]
	v_pk_fma_f32 v[60:61], v[60:61], v[2:3], v[164:165]
	v_cvt_pk_bf16_f32 v148, v60, v61
	v_lshlrev_b32_e32 v62, 16, v149
	v_and_b32_e32 v63, 0xffff0000, v149
	v_pk_mul_f32 v[62:63], v[62:63], v[44:45]
	v_pk_fma_f32 v[62:63], v[62:63], v[4:5], v[166:167]
	v_cvt_pk_bf16_f32 v149, v62, v63
	v_lshlrev_b32_e32 v64, 16, v150
	v_and_b32_e32 v65, 0xffff0000, v150
	v_pk_mul_f32 v[64:65], v[64:65], v[44:45]
	v_pk_fma_f32 v[64:65], v[64:65], v[6:7], v[168:169]
	v_cvt_pk_bf16_f32 v150, v64, v65
	v_lshlrev_b32_e32 v66, 16, v151
	v_and_b32_e32 v67, 0xffff0000, v151
	v_pk_mul_f32 v[66:67], v[66:67], v[44:45]
	v_pk_fma_f32 v[66:67], v[66:67], v[8:9], v[170:171]
	v_cvt_pk_bf16_f32 v151, v66, v67
	v_lshlrev_b32_e32 v60, 16, v152
	v_and_b32_e32 v61, 0xffff0000, v152
	v_pk_mul_f32 v[60:61], v[60:61], v[44:45]
	v_pk_fma_f32 v[60:61], v[60:61], v[10:11], v[172:173]
	v_cvt_pk_bf16_f32 v152, v60, v61
	v_lshlrev_b32_e32 v62, 16, v153
	v_and_b32_e32 v63, 0xffff0000, v153
	v_pk_mul_f32 v[62:63], v[62:63], v[44:45]
	v_pk_fma_f32 v[62:63], v[62:63], v[12:13], v[174:175]
	v_cvt_pk_bf16_f32 v153, v62, v63
	v_lshlrev_b32_e32 v64, 16, v154
	v_and_b32_e32 v65, 0xffff0000, v154
	v_pk_mul_f32 v[64:65], v[64:65], v[44:45]
	v_pk_fma_f32 v[64:65], v[64:65], v[14:15], v[176:177]
	v_cvt_pk_bf16_f32 v154, v64, v65
	v_lshlrev_b32_e32 v66, 16, v155
	v_and_b32_e32 v67, 0xffff0000, v155
	v_pk_mul_f32 v[66:67], v[66:67], v[44:45]
	v_pk_fma_f32 v[66:67], v[66:67], v[16:17], v[178:179]
	v_cvt_pk_bf16_f32 v155, v66, v67
	v_lshlrev_b32_e32 v60, 16, v156
	v_and_b32_e32 v61, 0xffff0000, v156
	v_pk_mul_f32 v[60:61], v[60:61], v[44:45]
	v_pk_fma_f32 v[60:61], v[60:61], v[18:19], v[180:181]
	v_cvt_pk_bf16_f32 v156, v60, v61
	v_lshlrev_b32_e32 v62, 16, v157
	v_and_b32_e32 v63, 0xffff0000, v157
	v_pk_mul_f32 v[62:63], v[62:63], v[44:45]
	v_pk_fma_f32 v[62:63], v[62:63], v[20:21], v[182:183]
	v_cvt_pk_bf16_f32 v157, v62, v63
	v_lshlrev_b32_e32 v64, 16, v158
	v_and_b32_e32 v65, 0xffff0000, v158
	v_pk_mul_f32 v[64:65], v[64:65], v[44:45]
	v_pk_fma_f32 v[64:65], v[64:65], v[22:23], v[184:185]
	v_cvt_pk_bf16_f32 v158, v64, v65
	v_lshlrev_b32_e32 v66, 16, v159
	v_and_b32_e32 v67, 0xffff0000, v159
	v_pk_mul_f32 v[66:67], v[66:67], v[44:45]
	v_pk_fma_f32 v[66:67], v[66:67], v[24:25], v[186:187]
	v_cvt_pk_bf16_f32 v159, v66, v67
	v_lshlrev_b32_e32 v60, 16, v160
	v_and_b32_e32 v61, 0xffff0000, v160
	v_pk_mul_f32 v[60:61], v[60:61], v[44:45]
	v_pk_fma_f32 v[60:61], v[60:61], v[26:27], v[188:189]
	v_cvt_pk_bf16_f32 v160, v60, v61
	v_lshlrev_b32_e32 v62, 16, v161
	v_and_b32_e32 v63, 0xffff0000, v161
	v_pk_mul_f32 v[62:63], v[62:63], v[44:45]
	v_pk_fma_f32 v[62:63], v[62:63], v[28:29], v[190:191]
	v_cvt_pk_bf16_f32 v161, v62, v63
	v_lshlrev_b32_e32 v64, 16, v162
	v_and_b32_e32 v65, 0xffff0000, v162
	v_pk_mul_f32 v[64:65], v[64:65], v[44:45]
	v_pk_fma_f32 v[64:65], v[64:65], v[30:31], v[192:193]
	v_cvt_pk_bf16_f32 v162, v64, v65
	v_lshlrev_b32_e32 v66, 16, v163
	v_and_b32_e32 v67, 0xffff0000, v163
	v_pk_mul_f32 v[66:67], v[66:67], v[44:45]
	v_pk_fma_f32 v[66:67], v[66:67], v[32:33], v[194:195]
	v_cvt_pk_bf16_f32 v163, v66, v67
	global_store_dwordx4 v39, v[148:151], s[20:21]
	global_store_dwordx4 v39, v[152:155], s[20:21] offset:1024
	global_store_dwordx4 v39, v[156:159], s[20:21] offset:2048
	global_store_dwordx4 v39, v[160:163], s[20:21] offset:3072
	s_add_u32 s20, s20, 0x1000
	s_addc_u32 s21, s21, 0
	s_cmpk_gt_u32 s7, 0x3ff
	s_cbranch_scc1 .Lnf2_ctxdone
	s_cmp_eq_u32 s80, 0
	s_cbranch_scc1 .Lnf2_skip
	s_cmp_eq_u32 s80, 3
	s_cbranch_scc1 .Lnf2_skip
	s_load_dwordx2 s[40:41], s[4:5], 0xb8
	s_lshl_b32 s10, s7, 12
	s_lshl_b32 s48, s7, 13
	s_waitcnt lgkmcnt(0)
	s_add_u32 s10, s40, s10
	s_addc_u32 s11, s41, 0
	s_add_u32 s10, s10, 0x1d624000
	s_addc_u32 s11, s11, 0
	s_add_u32 s20, s10, 0x4400000
	s_addc_u32 s21, s11, 0
	s_add_u32 s48, s40, s48
	s_addc_u32 s49, s41, 0
	s_add_u32 s48, s48, 0x3bce8000
	s_addc_u32 s49, s49, 0
	s_add_u32 s40, s8, 0x8000
	s_addc_u32 s41, s9, 0
	global_load_dwordx4 v[208:211], v39, s[10:11]
	global_load_dwordx4 v[212:215], v39, s[10:11] offset:1024
	global_load_dwordx4 v[216:219], v39, s[10:11] offset:2048
	global_load_dwordx4 v[220:223], v39, s[10:11] offset:3072
	global_load_dwordx4 v[132:135], v40, s[48:49]
	global_load_dwordx4 v[136:139], v40, s[48:49] offset:16
	global_load_dwordx4 v[140:143], v40, s[48:49] offset:2048
	global_load_dwordx4 v[144:147], v40, s[48:49] offset:2064
	s_add_u32 s48, s48, 0x1000
	s_addc_u32 s49, s49, 0
	global_load_dwordx4 v[148:151], v40, s[48:49]
	global_load_dwordx4 v[152:155], v40, s[48:49] offset:16
	global_load_dwordx4 v[156:159], v40, s[48:49] offset:2048
	global_load_dwordx4 v[160:163], v40, s[48:49] offset:2064
	s_add_u32 s48, s48, 0x7ff000
	s_addc_u32 s49, s49, 0
	global_load_dwordx4 v[60:63], v40, s[48:49]
	global_load_dwordx4 v[64:67], v40, s[48:49] offset:16
	global_load_dwordx4 v[68:71], v40, s[48:49] offset:2048
	global_load_dwordx4 v[72:75], v40, s[48:49] offset:2064
	s_add_u32 s48, s48, 0x1000
	s_addc_u32 s49, s49, 0
	global_load_dwordx4 v[76:79], v40, s[48:49]
	global_load_dwordx4 v[80:83], v40, s[48:49] offset:16
	global_load_dwordx4 v[84:87], v40, s[48:49] offset:2048
	global_load_dwordx4 v[88:91], v40, s[48:49] offset:2064
	s_add_u32 s48, s48, 0x7ff000
	s_addc_u32 s49, s49, 0
	global_load_dwordx4 v[2:5], v40, s[40:41]
	global_load_dwordx4 v[6:9], v40, s[40:41] offset:16
	global_load_dwordx4 v[10:13], v40, s[40:41] offset:2048
	global_load_dwordx4 v[14:17], v40, s[40:41] offset:2064
	s_add_u32 s40, s40, 0x1000
	s_addc_u32 s41, s41, 0
	global_load_dwordx4 v[18:21], v40, s[40:41]
	global_load_dwordx4 v[22:25], v40, s[40:41] offset:16
	global_load_dwordx4 v[26:29], v40, s[40:41] offset:2048
	global_load_dwordx4 v[30:33], v40, s[40:41] offset:2064
	s_add_u32 s40, s54, 0x30000
	s_addc_u32 s41, s55, 0
	global_load_dwordx4 v[164:167], v40, s[40:41]
	global_load_dwordx4 v[168:171], v40, s[40:41] offset:16
	global_load_dwordx4 v[172:175], v40, s[40:41] offset:2048
	global_load_dwordx4 v[176:179], v40, s[40:41] offset:2064
	s_add_u32 s40, s40, 0x1000
	s_addc_u32 s41, s41, 0
	global_load_dwordx4 v[180:183], v40, s[40:41]
	global_load_dwordx4 v[184:187], v40, s[40:41] offset:16
	global_load_dwordx4 v[188:191], v40, s[40:41] offset:2048
	global_load_dwordx4 v[192:195], v40, s[40:41] offset:2064
	s_waitcnt vmcnt(32)
	v_lshlrev_b32_e32 v100, 16, v208
	v_and_b32_e32 v101, 0xffff0000, v208
	v_lshlrev_b32_e32 v102, 16, v209
	v_and_b32_e32 v103, 0xffff0000, v209
	v_lshlrev_b32_e32 v104, 16, v210
	v_and_b32_e32 v105, 0xffff0000, v210
	v_lshlrev_b32_e32 v106, 16, v211
	v_and_b32_e32 v107, 0xffff0000, v211
	v_lshlrev_b32_e32 v108, 16, v212
	v_and_b32_e32 v109, 0xffff0000, v212
	v_lshlrev_b32_e32 v110, 16, v213
	v_and_b32_e32 v111, 0xffff0000, v213
	v_lshlrev_b32_e32 v112, 16, v214
	v_and_b32_e32 v113, 0xffff0000, v214
	v_lshlrev_b32_e32 v114, 16, v215
	v_and_b32_e32 v115, 0xffff0000, v215
	v_lshlrev_b32_e32 v116, 16, v216
	v_and_b32_e32 v117, 0xffff0000, v216
	v_lshlrev_b32_e32 v118, 16, v217
	v_and_b32_e32 v119, 0xffff0000, v217
	v_lshlrev_b32_e32 v120, 16, v218
	v_and_b32_e32 v121, 0xffff0000, v218
	v_lshlrev_b32_e32 v122, 16, v219
	v_and_b32_e32 v123, 0xffff0000, v219
	v_lshlrev_b32_e32 v124, 16, v220
	v_and_b32_e32 v125, 0xffff0000, v220
	v_lshlrev_b32_e32 v126, 16, v221
	v_and_b32_e32 v127, 0xffff0000, v221
	v_lshlrev_b32_e32 v128, 16, v222
	v_and_b32_e32 v129, 0xffff0000, v222
	v_lshlrev_b32_e32 v130, 16, v223
	v_and_b32_e32 v131, 0xffff0000, v223
	s_waitcnt vmcnt(24)
	v_pk_add_f32 v[100:101], v[100:101], v[132:133]
	v_pk_add_f32 v[102:103], v[102:103], v[134:135]
	v_pk_add_f32 v[104:105], v[104:105], v[136:137]
	v_pk_add_f32 v[106:107], v[106:107], v[138:139]
	v_pk_add_f32 v[108:109], v[108:109], v[140:141]
	v_pk_add_f32 v[110:111], v[110:111], v[142:143]
	v_pk_add_f32 v[112:113], v[112:113], v[144:145]
	v_pk_add_f32 v[114:115], v[114:115], v[146:147]
	v_pk_add_f32 v[116:117], v[116:117], v[148:149]
	v_pk_add_f32 v[118:119], v[118:119], v[150:151]
	v_pk_add_f32 v[120:121], v[120:121], v[152:153]
	v_pk_add_f32 v[122:123], v[122:123], v[154:155]
	v_pk_add_f32 v[124:125], v[124:125], v[156:157]
	v_pk_add_f32 v[126:127], v[126:127], v[158:159]
	v_pk_add_f32 v[128:129], v[128:129], v[160:161]
	v_pk_add_f32 v[130:131], v[130:131], v[162:163]
	global_load_dwordx4 v[132:135], v40, s[48:49]
	global_load_dwordx4 v[136:139], v40, s[48:49] offset:16
	global_load_dwordx4 v[140:143], v40, s[48:49] offset:2048
	global_load_dwordx4 v[144:147], v40, s[48:49] offset:2064
	s_add_u32 s48, s48, 0x1000
	s_addc_u32 s49, s49, 0
	global_load_dwordx4 v[148:151], v40, s[48:49]
	global_load_dwordx4 v[152:155], v40, s[48:49] offset:16
	global_load_dwordx4 v[156:159], v40, s[48:49] offset:2048
	global_load_dwordx4 v[160:163], v40, s[48:49] offset:2064
	s_add_u32 s48, s48, 0x7ff000
	s_addc_u32 s49, s49, 0
	s_waitcnt vmcnt(24)
	v_pk_add_f32 v[100:101], v[100:101], v[60:61]
	v_pk_add_f32 v[102:103], v[102:103], v[62:63]
	v_pk_add_f32 v[104:105], v[104:105], v[64:65]
	v_pk_add_f32 v[106:107], v[106:107], v[66:67]
	v_pk_add_f32 v[108:109], v[108:109], v[68:69]
	v_pk_add_f32 v[110:111], v[110:111], v[70:71]
	v_pk_add_f32 v[112:113], v[112:113], v[72:73]
	v_pk_add_f32 v[114:115], v[114:115], v[74:75]
	v_pk_add_f32 v[116:117], v[116:117], v[76:77]
	v_pk_add_f32 v[118:119], v[118:119], v[78:79]
	v_pk_add_f32 v[120:121], v[120:121], v[80:81]
	v_pk_add_f32 v[122:123], v[122:123], v[82:83]
	v_pk_add_f32 v[124:125], v[124:125], v[84:85]
	v_pk_add_f32 v[126:127], v[126:127], v[86:87]
	v_pk_add_f32 v[128:129], v[128:129], v[88:89]
	v_pk_add_f32 v[130:131], v[130:131], v[90:91]
	global_load_dwordx4 v[60:63], v40, s[48:49]
	global_load_dwordx4 v[64:67], v40, s[48:49] offset:16
	global_load_dwordx4 v[68:71], v40, s[48:49] offset:2048
	global_load_dwordx4 v[72:75], v40, s[48:49] offset:2064
	s_add_u32 s48, s48, 0x1000
	s_addc_u32 s49, s49, 0
	global_load_dwordx4 v[76:79], v40, s[48:49]
	global_load_dwordx4 v[80:83], v40, s[48:49] offset:16
	global_load_dwordx4 v[84:87], v40, s[48:49] offset:2048
	global_load_dwordx4 v[88:91], v40, s[48:49] offset:2064
	s_waitcnt vmcnt(8)
	v_pk_add_f32 v[100:101], v[100:101], v[132:133]
	v_pk_add_f32 v[102:103], v[102:103], v[134:135]
	v_pk_add_f32 v[104:105], v[104:105], v[136:137]
	v_pk_add_f32 v[106:107], v[106:107], v[138:139]
	v_pk_add_f32 v[108:109], v[108:109], v[140:141]
	v_pk_add_f32 v[110:111], v[110:111], v[142:143]
	v_pk_add_f32 v[112:113], v[112:113], v[144:145]
	v_pk_add_f32 v[114:115], v[114:115], v[146:147]
	v_pk_add_f32 v[116:117], v[116:117], v[148:149]
	v_pk_add_f32 v[118:119], v[118:119], v[150:151]
	v_pk_add_f32 v[120:121], v[120:121], v[152:153]
	v_pk_add_f32 v[122:123], v[122:123], v[154:155]
	v_pk_add_f32 v[124:125], v[124:125], v[156:157]
	v_pk_add_f32 v[126:127], v[126:127], v[158:159]
	v_pk_add_f32 v[128:129], v[128:129], v[160:161]
	v_pk_add_f32 v[130:131], v[130:131], v[162:163]
	s_waitcnt vmcnt(0)
	v_pk_add_f32 v[100:101], v[100:101], v[60:61]
	v_pk_add_f32 v[102:103], v[102:103], v[62:63]
	v_pk_add_f32 v[104:105], v[104:105], v[64:65]
	v_pk_add_f32 v[106:107], v[106:107], v[66:67]
	v_pk_add_f32 v[108:109], v[108:109], v[68:69]
	v_pk_add_f32 v[110:111], v[110:111], v[70:71]
	v_pk_add_f32 v[112:113], v[112:113], v[72:73]
	v_pk_add_f32 v[114:115], v[114:115], v[74:75]
	v_pk_add_f32 v[116:117], v[116:117], v[76:77]
	v_pk_add_f32 v[118:119], v[118:119], v[78:79]
	v_pk_add_f32 v[120:121], v[120:121], v[80:81]
	v_pk_add_f32 v[122:123], v[122:123], v[82:83]
	v_pk_add_f32 v[124:125], v[124:125], v[84:85]
	v_pk_add_f32 v[126:127], v[126:127], v[86:87]
	v_pk_add_f32 v[128:129], v[128:129], v[88:89]
	v_pk_add_f32 v[130:131], v[130:131], v[90:91]
	v_cvt_pk_bf16_f32 v208, v100, v101
	v_cvt_pk_bf16_f32 v209, v102, v103
	v_cvt_pk_bf16_f32 v210, v104, v105
	v_cvt_pk_bf16_f32 v211, v106, v107
	v_cvt_pk_bf16_f32 v212, v108, v109
	v_cvt_pk_bf16_f32 v213, v110, v111
	v_cvt_pk_bf16_f32 v214, v112, v113
	v_cvt_pk_bf16_f32 v215, v114, v115
	v_cvt_pk_bf16_f32 v216, v116, v117
	v_cvt_pk_bf16_f32 v217, v118, v119
	v_cvt_pk_bf16_f32 v218, v120, v121
	v_cvt_pk_bf16_f32 v219, v122, v123
	v_cvt_pk_bf16_f32 v220, v124, v125
	v_cvt_pk_bf16_f32 v221, v126, v127
	v_cvt_pk_bf16_f32 v222, v128, v129
	v_cvt_pk_bf16_f32 v223, v130, v131
	global_store_dwordx4 v39, v[208:211], s[10:11]
	global_store_dwordx4 v39, v[212:215], s[10:11] offset:1024
	global_store_dwordx4 v39, v[216:219], s[10:11] offset:2048
	global_store_dwordx4 v39, v[220:223], s[10:11] offset:3072
	v_pk_mul_f32 v[42:43], v[100:101], v[100:101]
	v_pk_fma_f32 v[42:43], v[102:103], v[102:103], v[42:43]
	v_pk_fma_f32 v[42:43], v[104:105], v[104:105], v[42:43]
	v_pk_fma_f32 v[42:43], v[106:107], v[106:107], v[42:43]
	v_pk_fma_f32 v[42:43], v[108:109], v[108:109], v[42:43]
	v_pk_fma_f32 v[42:43], v[110:111], v[110:111], v[42:43]
	v_pk_fma_f32 v[42:43], v[112:113], v[112:113], v[42:43]
	v_pk_fma_f32 v[42:43], v[114:115], v[114:115], v[42:43]
	v_pk_fma_f32 v[42:43], v[116:117], v[116:117], v[42:43]
	v_pk_fma_f32 v[42:43], v[118:119], v[118:119], v[42:43]
	v_pk_fma_f32 v[42:43], v[120:121], v[120:121], v[42:43]
	v_pk_fma_f32 v[42:43], v[122:123], v[122:123], v[42:43]
	v_pk_fma_f32 v[42:43], v[124:125], v[124:125], v[42:43]
	v_pk_fma_f32 v[42:43], v[126:127], v[126:127], v[42:43]
	v_pk_fma_f32 v[42:43], v[128:129], v[128:129], v[42:43]
	v_pk_fma_f32 v[42:43], v[130:131], v[130:131], v[42:43]
	v_add_f32_e32 v42, v42, v43
	s_nop 1
	v_add_f32_dpp v42, v42, v42 quad_perm:[1,0,3,2] row_mask:0xf bank_mask:0xf
	s_nop 1
	v_add_f32_dpp v42, v42, v42 quad_perm:[2,3,0,1] row_mask:0xf bank_mask:0xf
	s_nop 1
	v_add_f32_dpp v42, v42, v42 row_half_mirror row_mask:0xf bank_mask:0xf
	s_nop 1
	v_add_f32_dpp v42, v42, v42 row_mirror row_mask:0xf bank_mask:0xf
	s_nop 1
	v_add_f32_dpp v42, v42, v42 row_bcast:15 row_mask:0xa bank_mask:0xf
	s_nop 1
	v_add_f32_dpp v42, v42, v42 row_bcast:31 row_mask:0xc bank_mask:0xf
	s_nop 1
	v_readlane_b32 s100, v42, 63
	s_nop 3
	v_mov_b32_e32 v44, s100
	v_fma_f32 v44, v44, v47, v224
	v_rsq_f32_e32 v45, v44
	s_nop 0
	v_mul_f32_e32 v46, v44, v45
	v_mul_f32_e32 v46, v46, v45
	v_fmaak_f32 v46, -0.5, v46, 0x3fc00000
	v_mul_f32_e32 v44, v45, v46
	v_mov_b32_e32 v45, v44
	v_pk_mul_f32 v[92:93], v[100:101], v[44:45]
	v_pk_fma_f32 v[92:93], v[92:93], v[2:3], v[164:165]
	v_cvt_pk_bf16_f32 v132, v92, v93
	v_pk_mul_f32 v[94:95], v[102:103], v[44:45]
	v_pk_fma_f32 v[94:95], v[94:95], v[4:5], v[166:167]
	v_cvt_pk_bf16_f32 v133, v94, v95
	v_pk_mul_f32 v[96:97], v[104:105], v[44:45]
	v_pk_fma_f32 v[96:97], v[96:97], v[6:7], v[168:169]
	v_cvt_pk_bf16_f32 v134, v96, v97
	v_pk_mul_f32 v[92:93], v[106:107], v[44:45]
	v_pk_fma_f32 v[92:93], v[92:93], v[8:9], v[170:171]
	v_cvt_pk_bf16_f32 v135, v92, v93
	v_pk_mul_f32 v[94:95], v[108:109], v[44:45]
	v_pk_fma_f32 v[94:95], v[94:95], v[10:11], v[172:173]
	v_cvt_pk_bf16_f32 v136, v94, v95
	v_pk_mul_f32 v[96:97], v[110:111], v[44:45]
	v_pk_fma_f32 v[96:97], v[96:97], v[12:13], v[174:175]
	v_cvt_pk_bf16_f32 v137, v96, v97
	v_pk_mul_f32 v[92:93], v[112:113], v[44:45]
	v_pk_fma_f32 v[92:93], v[92:93], v[14:15], v[176:177]
	v_cvt_pk_bf16_f32 v138, v92, v93
	v_pk_mul_f32 v[94:95], v[114:115], v[44:45]
	v_pk_fma_f32 v[94:95], v[94:95], v[16:17], v[178:179]
	v_cvt_pk_bf16_f32 v139, v94, v95
	v_pk_mul_f32 v[96:97], v[116:117], v[44:45]
	v_pk_fma_f32 v[96:97], v[96:97], v[18:19], v[180:181]
	v_cvt_pk_bf16_f32 v140, v96, v97
	v_pk_mul_f32 v[92:93], v[118:119], v[44:45]
	v_pk_fma_f32 v[92:93], v[92:93], v[20:21], v[182:183]
	v_cvt_pk_bf16_f32 v141, v92, v93
	v_pk_mul_f32 v[94:95], v[120:121], v[44:45]
	v_pk_fma_f32 v[94:95], v[94:95], v[22:23], v[184:185]
	v_cvt_pk_bf16_f32 v142, v94, v95
	v_pk_mul_f32 v[96:97], v[122:123], v[44:45]
	v_pk_fma_f32 v[96:97], v[96:97], v[24:25], v[186:187]
	v_cvt_pk_bf16_f32 v143, v96, v97
	v_pk_mul_f32 v[92:93], v[124:125], v[44:45]
	v_pk_fma_f32 v[92:93], v[92:93], v[26:27], v[188:189]
	v_cvt_pk_bf16_f32 v144, v92, v93
	v_pk_mul_f32 v[94:95], v[126:127], v[44:45]
	v_pk_fma_f32 v[94:95], v[94:95], v[28:29], v[190:191]
	v_cvt_pk_bf16_f32 v145, v94, v95
	v_pk_mul_f32 v[96:97], v[128:129], v[44:45]
	v_pk_fma_f32 v[96:97], v[96:97], v[30:31], v[192:193]
	v_cvt_pk_bf16_f32 v146, v96, v97
	v_pk_mul_f32 v[92:93], v[130:131], v[44:45]
	v_pk_fma_f32 v[92:93], v[92:93], v[32:33], v[194:195]
	v_cvt_pk_bf16_f32 v147, v92, v93
	global_store_dwordx4 v39, v[132:135], s[20:21]
	global_store_dwordx4 v39, v[136:139], s[20:21] offset:1024
	global_store_dwordx4 v39, v[140:143], s[20:21] offset:2048
	global_store_dwordx4 v39, v[144:147], s[20:21] offset:3072

.LBB0_902:
	s_cmp_eq_u32 s101, 0
	s_cbranch_scc1 .Lnf2_orig
	s_cmp_eq_u32 s101, 2
	s_cbranch_scc1 .LBB0_908
	s_cmpk_lt_i32 s7, 0x4000
	s_cbranch_scc0 .Lnf2_orig
	s_add_i32 s7, s7, s42
	v_lshl_add_u64 v[36:37], v[36:37], 0, s[44:45]
	s_cmp_lt_i32 s7, s81
	s_cbranch_scc1 .LBB0_902
	s_branch .LBB0_908
